# removed the per-segment s_setprio toggling from the four GEMM K-loops
# speedup vs baseline: 1.0055x; 1.0055x over previous
; #define PG8_STAGE(bufoff, gbase, voff) do { _Pragma("unroll") for (int _i = 0; _i < 2; ++_i) \
;         __builtin_amdgcn_global_load_lds((const unsigned*)((const char*)(gbase) + (voff)[_i]), (PG8_LAS unsigned*)(lds + (bufoff) + ldsw + _i * 8192), 16, 0, 0); } while (0)
; #define PG8_LDA(dst, b, h) do { _Pragma("unroll") for (int m = 0; m < 4; ++m) _Pragma("unroll") for (int k = 0; k < 2; ++k) dst[m][k] = *(const PG8_LAS bf16x8*)(lds + PG8_SA(b, h) + aoff + m * 2048 + k * 1024); } while (0)
; #define PG8_LDB(dst, b, h) do { _Pragma("unroll") for (int n = 0; n < 2; ++n) _Pragma("unroll") for (int k = 0; k < 2; ++k) dst[n][k] = *(const PG8_LAS bf16x8*)(lds + PG8_SB(b, h) + boff + n * 2048 + k * 1024); } while (0)
; template <class Epi, class Sched, bool ALIGN_EPI = false, bool SP2 = false>
; __device__ __forceinline__ void gemm_phase(PG8_LAS unsigned char* lds, const Gemm g, const Sched& S, const Epi& E) {
;     ...
;         for (int t = 0; t < nt; t += 2) {
;             const bool last = (t == nt - 2);
;             const char* a1 = cA + (size_t)(t + 1) * kstep;
;             const char* a2 = last ? nA : cA + (size_t)(t + 2) * kstep; const char* b2 = last ? nB : cB + (size_t)(t + 2) * kstep;
;             const char* a3 = a2 + kstep; const char* b3 = b2 + kstep;
;             if (last && has_next) S.a_ready(nxt);
;             if constexpr (SP2) {
;             PG8_LDB(B0, 0, 0); PG8_LDB(B1, 0, 1); PG8_SCHED; PG8_LDA(At, 0, 0); PG8_STAGE(PG8_SA(1, 1), a1 + hstep, voffA);
;             PG8_WAIT_V(8); PG8_WAIT_L(0); PG8_BAR; PG8_MMA(0, 0, At, B0); PG8_MMA(0, 1, At, B1); PG8_BAR; PG8_SCHED;
;             PG8_LDA(At, 0, 1); PG8_STAGE(PG8_SB(0, 0), b2, voffB); PG8_STAGE(PG8_SB(0, 1), b2 + hstep, voffB); PG8_STAGE(PG8_SA(0, 0), a2, voffA);
;             PG8_WAIT_V(8); PG8_WAIT_L(0); PG8_BAR; PG8_MMA(1, 0, At, B0); PG8_MMA(1, 1, At, B1); PG8_BAR; PG8_SCHED;
;             PG8_LDB(B0, 1, 0); PG8_LDB(B1, 1, 1); PG8_SCHED; PG8_LDA(At, 1, 0); PG8_STAGE(PG8_SA(0, 1), a2 + hstep, voffA);
;             PG8_WAIT_V(8); PG8_WAIT_L(0); PG8_BAR; PG8_MMA(0, 0, At, B0); PG8_MMA(0, 1, At, B1); PG8_BAR; PG8_SCHED;
;             PG8_LDA(At, 1, 1); PG8_STAGE(PG8_SB(1, 0), b3, voffB); PG8_STAGE(PG8_SB(1, 1), b3 + hstep, voffB); PG8_STAGE(PG8_SA(1, 0), a3, voffA);
;             PG8_WAIT_V(8); PG8_WAIT_L(0); PG8_BAR; PG8_MMA(1, 0, At, B0); PG8_MMA(1, 1, At, B1); PG8_BAR; PG8_SCHED;
.LBB0_766:
	s_ashr_i32 s17, s16, 31
	s_lshl_b64 s[20:21], s[16:17], 19
	s_add_u32 s20, s77, s20
	s_addc_u32 s21, s26, s21
	s_and_b64 s[30:31], s[6:7], exec
	s_cselect_b32 s17, s21, s39
	s_cselect_b32 s48, s20, s38
	s_ashr_i32 s15, s14, 31
	s_lshl_b64 s[30:31], s[14:15], 19
	v_readlane_b32 s42, v255, 18
	v_readlane_b32 s43, v255, 19
	s_add_u32 s30, s42, s30
	s_addc_u32 s31, s43, s31
	s_and_b64 s[42:43], s[6:7], exec
	s_cselect_b32 s15, s31, s41
	s_cselect_b32 s49, s30, s40
	s_add_u32 s38, s38, 0x40080
	s_addc_u32 s39, s39, 0
	s_add_u32 s50, s40, 0x100
	s_addc_u32 s51, s41, 0
	s_mov_b32 s54, -2
	s_add_u32 s40, s38, 0xfffc0080
	s_addc_u32 s41, s39, -1
	s_add_i32 s55, 0, 0x10000
	s_cmp_eq_u32 s54, 12
	s_cselect_b32 s43, s17, s41
	s_cselect_b32 s42, s48, s40
	v_add_u32_e32 v140, s55, v143
	s_cselect_b32 s41, s15, s51
	s_cselect_b32 s40, s49, s50
	s_add_i32 s63, 0, 0x14000
	ds_read_b128 v[146:149], v140
	ds_read_b128 v[150:153], v140 offset:1024
	ds_read_b128 v[154:157], v140 offset:2048
	ds_read_b128 v[158:161], v140 offset:3072
	v_add_u32_e32 v140, s63, v143
	ds_read_b128 v[162:165], v140
	ds_read_b128 v[166:169], v140 offset:1024
	ds_read_b128 v[170:173], v140 offset:2048
	ds_read_b128 v[174:177], v140 offset:3072
	v_lshl_add_u64 v[140:141], s[38:39], 0, v[136:137]
	s_add_i32 m0, s19, 0xc000
	ds_read_b128 v[178:181], v145
	ds_read_b128 v[182:185], v145 offset:1024
	ds_read_b128 v[186:189], v145 offset:2048
	ds_read_b128 v[190:193], v145 offset:3072
	ds_read_b128 v[198:201], v145 offset:4096
	ds_read_b128 v[202:205], v145 offset:5120
	ds_read_b128 v[206:209], v145 offset:6144
	ds_read_b128 v[210:213], v145 offset:7168
	global_load_lds_dwordx4 v[140:141], off
	v_lshl_add_u64 v[140:141], s[38:39], 0, v[138:139]
	s_add_i32 m0, s19, 0xe000
	s_nop 0
	global_load_lds_dwordx4 v[140:141], off
	s_waitcnt vmcnt(8)
	s_waitcnt lgkmcnt(0)
	s_barrier
	s_waitcnt lgkmcnt(0)
	v_mfma_f32_16x16x32_bf16 v[126:129], v[146:149], v[178:181], 0
	v_mfma_f32_16x16x32_bf16 v[122:125], v[154:157], v[178:181], 0
	v_mfma_f32_16x16x32_bf16 v[118:121], v[146:149], v[186:189], 0
	v_mfma_f32_16x16x32_bf16 v[110:113], v[154:157], v[186:189], 0
	v_mfma_f32_16x16x32_bf16 v[102:105], v[146:149], v[198:201], 0
	v_mfma_f32_16x16x32_bf16 v[94:97], v[154:157], v[198:201], 0
	v_mfma_f32_16x16x32_bf16 v[86:89], v[146:149], v[206:209], 0
	v_mfma_f32_16x16x32_bf16 v[78:81], v[154:157], v[206:209], 0
	v_mfma_f32_16x16x32_bf16 v[126:129], v[150:153], v[182:185], v[126:129]
	v_mfma_f32_16x16x32_bf16 v[122:125], v[158:161], v[182:185], v[122:125]
	v_mfma_f32_16x16x32_bf16 v[118:121], v[150:153], v[190:193], v[118:121]
	v_mfma_f32_16x16x32_bf16 v[110:113], v[158:161], v[190:193], v[110:113]
	v_mfma_f32_16x16x32_bf16 v[102:105], v[150:153], v[202:205], v[102:105]
	v_mfma_f32_16x16x32_bf16 v[94:97], v[158:161], v[202:205], v[94:97]
	v_mfma_f32_16x16x32_bf16 v[86:89], v[150:153], v[210:213], v[86:89]
	v_mfma_f32_16x16x32_bf16 v[78:81], v[158:161], v[210:213], v[78:81]
	v_mfma_f32_16x16x32_bf16 v[114:117], v[162:165], v[178:181], 0
	v_mfma_f32_16x16x32_bf16 v[106:109], v[170:173], v[178:181], 0
	v_mfma_f32_16x16x32_bf16 v[98:101], v[162:165], v[186:189], 0
	v_mfma_f32_16x16x32_bf16 v[90:93], v[170:173], v[186:189], 0
	v_mfma_f32_16x16x32_bf16 v[82:85], v[162:165], v[198:201], 0
	v_mfma_f32_16x16x32_bf16 v[74:77], v[170:173], v[198:201], 0
	v_mfma_f32_16x16x32_bf16 v[70:73], v[162:165], v[206:209], 0
	v_mfma_f32_16x16x32_bf16 v[66:69], v[170:173], v[206:209], 0
	v_mfma_f32_16x16x32_bf16 v[114:117], v[166:169], v[182:185], v[114:117]
	v_mfma_f32_16x16x32_bf16 v[106:109], v[174:177], v[182:185], v[106:109]
	v_mfma_f32_16x16x32_bf16 v[98:101], v[166:169], v[190:193], v[98:101]
	v_mfma_f32_16x16x32_bf16 v[90:93], v[174:177], v[190:193], v[90:93]
	v_mfma_f32_16x16x32_bf16 v[82:85], v[166:169], v[202:205], v[82:85]
	v_mfma_f32_16x16x32_bf16 v[74:77], v[174:177], v[202:205], v[74:77]
	v_mfma_f32_16x16x32_bf16 v[70:73], v[166:169], v[210:213], v[70:73]
	v_mfma_f32_16x16x32_bf16 v[66:69], v[174:177], v[210:213], v[66:69]
	s_barrier
	s_add_i32 s55, s55, s5
	v_lshl_add_u64 v[140:141], s[40:41], 0, v[0:1]
	s_mov_b32 m0, s55
	ds_read_b128 v[178:181], v145 offset:16384
	ds_read_b128 v[182:185], v145 offset:17408
	ds_read_b128 v[186:189], v145 offset:18432
	ds_read_b128 v[190:193], v145 offset:19456
	ds_read_b128 v[198:201], v145 offset:20480
	ds_read_b128 v[202:205], v145 offset:21504
	ds_read_b128 v[206:209], v145 offset:22528
	ds_read_b128 v[210:213], v145 offset:23552
	global_load_lds_dwordx4 v[140:141], off
	s_add_i32 m0, s55, 0x2000
	s_add_u32 s72, s40, 0x40000
	v_lshl_add_u64 v[214:215], s[40:41], 0, v[130:131]
	s_addc_u32 s73, s41, 0
	s_add_i32 s55, s63, s5
	global_load_lds_dwordx4 v[214:215], off
	v_lshl_add_u64 v[216:217], s[72:73], 0, v[0:1]
	s_mov_b32 m0, s55
	v_lshl_add_u64 v[218:219], s[42:43], 0, v[132:133]
	global_load_lds_dwordx4 v[216:217], off
	v_lshl_add_u64 v[216:217], s[72:73], 0, v[130:131]
	s_add_i32 m0, s55, 0x2000
	s_nop 0
	global_load_lds_dwordx4 v[216:217], off
	v_lshl_add_u64 v[216:217], s[42:43], 0, v[134:135]
	s_mov_b32 m0, s19
	s_nop 0
	global_load_lds_dwordx4 v[216:217], off
	s_mov_b32 m0, s27
	s_nop 0
	global_load_lds_dwordx4 v[218:219], off
	s_waitcnt vmcnt(8)
	s_waitcnt lgkmcnt(0)
	s_barrier
; #define PG8_STAGE(bufoff, gbase, voff) do { _Pragma("unroll") for (int _i = 0; _i < 2; ++_i) \
;         __builtin_amdgcn_global_load_lds((const unsigned*)((const char*)(gbase) + (voff)[_i]), (PG8_LAS unsigned*)(lds + (bufoff) + ldsw + _i * 8192), 16, 0, 0); } while (0)
; #define PG8_LDA(dst, b, h) do { _Pragma("unroll") for (int m = 0; m < 4; ++m) _Pragma("unroll") for (int k = 0; k < 2; ++k) dst[m][k] = *(const PG8_LAS bf16x8*)(lds + PG8_SA(b, h) + aoff + m * 2048 + k * 1024); } while (0)
; #define PG8_LDB(dst, b, h) do { _Pragma("unroll") for (int n = 0; n < 2; ++n) _Pragma("unroll") for (int k = 0; k < 2; ++k) dst[n][k] = *(const PG8_LAS bf16x8*)(lds + PG8_SB(b, h) + boff + n * 2048 + k * 1024); } while (0)
; #define PG8_MMA(ai, bj, At, Bt) do { __builtin_amdgcn_s_setprio(1); _Pragma("unroll") for (int m = 0; m < 4; ++m) _Pragma("unroll") for (int n = 0; n < 2; ++n) _Pragma("unroll") for (int k = 0; k < 2; ++k) \
;         acc[ai][bj][m][n] = __builtin_amdgcn_mfma_f32_16x16x32_bf16(Bt[n][k], At[m][k], acc[ai][bj][m][n], 0, 0, 0); __builtin_amdgcn_s_setprio(0); } while (0)
; #define PG8_WAIT_V(n) asm volatile("s_waitcnt vmcnt(" #n ")" ::: "memory")
; template <class Epi, class Sched, bool ALIGN_EPI = false, bool SP2 = false>
; __device__ __forceinline__ void gemm_phase(PG8_LAS unsigned char* lds, const Gemm g, const Sched& S, const Epi& E) {
;     ...
;             PG8_LDB(B0, 0, 0); PG8_LDB(B1, 0, 1); PG8_SCHED; PG8_LDA(At, 0, 0); PG8_STAGE(PG8_SA(1, 1), a1 + hstep, voffA);
;             PG8_WAIT_V(8); PG8_WAIT_L(0); PG8_BAR; PG8_MMA(0, 0, At, B0); PG8_MMA(0, 1, At, B1); PG8_BAR; PG8_SCHED;
;             PG8_LDA(At, 0, 1); PG8_STAGE(PG8_SB(0, 0), b2, voffB); PG8_STAGE(PG8_SB(0, 1), b2 + hstep, voffB); PG8_STAGE(PG8_SA(0, 0), a2, voffA);
;             PG8_WAIT_V(8); PG8_WAIT_L(0); PG8_BAR; PG8_MMA(1, 0, At, B0); PG8_MMA(1, 1, At, B1); PG8_BAR; PG8_SCHED;
;             PG8_LDB(B0, 1, 0); PG8_LDB(B1, 1, 1); PG8_SCHED; PG8_LDA(At, 1, 0); PG8_STAGE(PG8_SA(0, 1), a2 + hstep, voffA);
;             PG8_WAIT_V(8); PG8_WAIT_L(0); PG8_BAR; PG8_MMA(0, 0, At, B0); PG8_MMA(0, 1, At, B1); PG8_BAR; PG8_SCHED;
;             PG8_LDA(At, 1, 1); PG8_STAGE(PG8_SB(1, 0), b3, voffB); PG8_STAGE(PG8_SB(1, 1), b3 + hstep, voffB); PG8_STAGE(PG8_SA(1, 0), a3, voffA);
;             PG8_WAIT_V(8); PG8_WAIT_L(0); PG8_BAR; PG8_MMA(1, 0, At, B0); PG8_MMA(1, 1, At, B1); PG8_BAR; PG8_SCHED;
	s_waitcnt lgkmcnt(0)
	v_mfma_f32_16x16x32_bf16 v[62:65], v[146:149], v[178:181], 0
	v_mfma_f32_16x16x32_bf16 v[58:61], v[154:157], v[178:181], 0
	v_mfma_f32_16x16x32_bf16 v[54:57], v[146:149], v[186:189], 0
	v_mfma_f32_16x16x32_bf16 v[46:49], v[154:157], v[186:189], 0
	v_mfma_f32_16x16x32_bf16 v[38:41], v[146:149], v[198:201], 0
	v_mfma_f32_16x16x32_bf16 v[30:33], v[154:157], v[198:201], 0
	v_mfma_f32_16x16x32_bf16 v[22:25], v[146:149], v[206:209], 0
	v_mfma_f32_16x16x32_bf16 v[14:17], v[154:157], v[206:209], 0
	v_mfma_f32_16x16x32_bf16 v[62:65], v[150:153], v[182:185], v[62:65]
	v_mfma_f32_16x16x32_bf16 v[58:61], v[158:161], v[182:185], v[58:61]
	v_mfma_f32_16x16x32_bf16 v[54:57], v[150:153], v[190:193], v[54:57]
	v_mfma_f32_16x16x32_bf16 v[46:49], v[158:161], v[190:193], v[46:49]
	v_mfma_f32_16x16x32_bf16 v[38:41], v[150:153], v[202:205], v[38:41]
	v_mfma_f32_16x16x32_bf16 v[30:33], v[158:161], v[202:205], v[30:33]
	v_mfma_f32_16x16x32_bf16 v[22:25], v[150:153], v[210:213], v[22:25]
	v_mfma_f32_16x16x32_bf16 v[14:17], v[158:161], v[210:213], v[14:17]
	v_mfma_f32_16x16x32_bf16 v[50:53], v[162:165], v[178:181], 0
	v_mfma_f32_16x16x32_bf16 v[42:45], v[170:173], v[178:181], 0
	v_mfma_f32_16x16x32_bf16 v[34:37], v[162:165], v[186:189], 0
	v_mfma_f32_16x16x32_bf16 v[26:29], v[170:173], v[186:189], 0
	v_mfma_f32_16x16x32_bf16 v[18:21], v[162:165], v[198:201], 0
	v_mfma_f32_16x16x32_bf16 v[10:13], v[170:173], v[198:201], 0
	v_mfma_f32_16x16x32_bf16 v[6:9], v[162:165], v[206:209], 0
	v_mfma_f32_16x16x32_bf16 v[2:5], v[170:173], v[206:209], 0
	v_mfma_f32_16x16x32_bf16 v[50:53], v[166:169], v[182:185], v[50:53]
	v_mfma_f32_16x16x32_bf16 v[42:45], v[174:177], v[182:185], v[42:45]
	v_mfma_f32_16x16x32_bf16 v[34:37], v[166:169], v[190:193], v[34:37]
	v_mfma_f32_16x16x32_bf16 v[26:29], v[174:177], v[190:193], v[26:29]
	v_mfma_f32_16x16x32_bf16 v[18:21], v[166:169], v[202:205], v[18:21]
	v_mfma_f32_16x16x32_bf16 v[10:13], v[174:177], v[202:205], v[10:13]
	v_mfma_f32_16x16x32_bf16 v[6:9], v[166:169], v[210:213], v[6:9]
	v_mfma_f32_16x16x32_bf16 v[2:5], v[174:177], v[210:213], v[2:5]
	s_barrier
	s_add_i32 s55, 0, 0x18000
	s_add_i32 s63, 0, 0x1c000
	v_add_u32_e32 v158, s55, v143
	v_add_u32_e32 v174, s63, v143
	ds_read_b128 v[146:149], v158
	ds_read_b128 v[150:153], v158 offset:1024
	ds_read_b128 v[154:157], v158 offset:2048
	ds_read_b128 v[158:161], v158 offset:3072
	ds_read_b128 v[162:165], v174
	ds_read_b128 v[166:169], v174 offset:1024
	ds_read_b128 v[170:173], v174 offset:2048
	ds_read_b128 v[174:177], v174 offset:3072
	s_add_u32 s42, s42, 0x40000
	s_addc_u32 s43, s43, 0
	s_mov_b32 m0, s28
	v_lshl_add_u64 v[220:221], s[42:43], 0, v[134:135]
	ds_read_b128 v[178:181], v145 offset:32768
	ds_read_b128 v[182:185], v145 offset:33792
	ds_read_b128 v[186:189], v145 offset:34816
	ds_read_b128 v[190:193], v145 offset:35840
	ds_read_b128 v[198:201], v145 offset:36864
	ds_read_b128 v[202:205], v145 offset:37888
	ds_read_b128 v[206:209], v145 offset:38912
	ds_read_b128 v[210:213], v145 offset:39936
	global_load_lds_dwordx4 v[220:221], off
	v_lshl_add_u64 v[220:221], s[42:43], 0, v[132:133]
	s_mov_b32 m0, s29
	s_nop 0
	global_load_lds_dwordx4 v[220:221], off
	s_waitcnt vmcnt(8)
	s_waitcnt lgkmcnt(0)
	s_barrier
	s_waitcnt lgkmcnt(0)
	v_mfma_f32_16x16x32_bf16 v[126:129], v[146:149], v[178:181], v[126:129]
	v_mfma_f32_16x16x32_bf16 v[122:125], v[154:157], v[178:181], v[122:125]
	v_mfma_f32_16x16x32_bf16 v[118:121], v[146:149], v[186:189], v[118:121]
	v_mfma_f32_16x16x32_bf16 v[110:113], v[154:157], v[186:189], v[110:113]
	v_mfma_f32_16x16x32_bf16 v[102:105], v[146:149], v[198:201], v[102:105]
	v_mfma_f32_16x16x32_bf16 v[94:97], v[154:157], v[198:201], v[94:97]
	v_mfma_f32_16x16x32_bf16 v[86:89], v[146:149], v[206:209], v[86:89]
	v_mfma_f32_16x16x32_bf16 v[78:81], v[154:157], v[206:209], v[78:81]
	v_mfma_f32_16x16x32_bf16 v[126:129], v[150:153], v[182:185], v[126:129]
	v_mfma_f32_16x16x32_bf16 v[122:125], v[158:161], v[182:185], v[122:125]
	v_mfma_f32_16x16x32_bf16 v[118:121], v[150:153], v[190:193], v[118:121]
	v_mfma_f32_16x16x32_bf16 v[110:113], v[158:161], v[190:193], v[110:113]
	v_mfma_f32_16x16x32_bf16 v[102:105], v[150:153], v[202:205], v[102:105]
	v_mfma_f32_16x16x32_bf16 v[94:97], v[158:161], v[202:205], v[94:97]
	v_mfma_f32_16x16x32_bf16 v[86:89], v[150:153], v[210:213], v[86:89]
	v_mfma_f32_16x16x32_bf16 v[78:81], v[158:161], v[210:213], v[78:81]
	v_mfma_f32_16x16x32_bf16 v[114:117], v[162:165], v[178:181], v[114:117]
	v_mfma_f32_16x16x32_bf16 v[106:109], v[170:173], v[178:181], v[106:109]
	v_mfma_f32_16x16x32_bf16 v[98:101], v[162:165], v[186:189], v[98:101]
	v_mfma_f32_16x16x32_bf16 v[90:93], v[170:173], v[186:189], v[90:93]
	v_mfma_f32_16x16x32_bf16 v[82:85], v[162:165], v[198:201], v[82:85]
	v_mfma_f32_16x16x32_bf16 v[74:77], v[170:173], v[198:201], v[74:77]
	v_mfma_f32_16x16x32_bf16 v[70:73], v[162:165], v[206:209], v[70:73]
	v_mfma_f32_16x16x32_bf16 v[66:69], v[170:173], v[206:209], v[66:69]
	v_mfma_f32_16x16x32_bf16 v[114:117], v[166:169], v[182:185], v[114:117]
	v_mfma_f32_16x16x32_bf16 v[106:109], v[174:177], v[182:185], v[106:109]
	v_mfma_f32_16x16x32_bf16 v[98:101], v[166:169], v[190:193], v[98:101]
	v_mfma_f32_16x16x32_bf16 v[90:93], v[174:177], v[190:193], v[90:93]
	v_mfma_f32_16x16x32_bf16 v[82:85], v[166:169], v[202:205], v[82:85]
	v_mfma_f32_16x16x32_bf16 v[74:77], v[174:177], v[202:205], v[74:77]
	v_mfma_f32_16x16x32_bf16 v[70:73], v[166:169], v[210:213], v[70:73]
	v_mfma_f32_16x16x32_bf16 v[66:69], v[174:177], v[210:213], v[66:69]
	s_barrier
; #define PG8_STAGE(bufoff, gbase, voff) do { _Pragma("unroll") for (int _i = 0; _i < 2; ++_i) \
;         __builtin_amdgcn_global_load_lds((const unsigned*)((const char*)(gbase) + (voff)[_i]), (PG8_LAS unsigned*)(lds + (bufoff) + ldsw + _i * 8192), 16, 0, 0); } while (0)
; #define PG8_LDA(dst, b, h) do { _Pragma("unroll") for (int m = 0; m < 4; ++m) _Pragma("unroll") for (int k = 0; k < 2; ++k) dst[m][k] = *(const PG8_LAS bf16x8*)(lds + PG8_SA(b, h) + aoff + m * 2048 + k * 1024); } while (0)
; #define PG8_LDB(dst, b, h) do { _Pragma("unroll") for (int n = 0; n < 2; ++n) _Pragma("unroll") for (int k = 0; k < 2; ++k) dst[n][k] = *(const PG8_LAS bf16x8*)(lds + PG8_SB(b, h) + boff + n * 2048 + k * 1024); } while (0)
; #define PG8_MMA(ai, bj, At, Bt) do { __builtin_amdgcn_s_setprio(1); _Pragma("unroll") for (int m = 0; m < 4; ++m) _Pragma("unroll") for (int n = 0; n < 2; ++n) _Pragma("unroll") for (int k = 0; k < 2; ++k) \
;         acc[ai][bj][m][n] = __builtin_amdgcn_mfma_f32_16x16x32_bf16(Bt[n][k], At[m][k], acc[ai][bj][m][n], 0, 0, 0); __builtin_amdgcn_s_setprio(0); } while (0)
; #define PG8_WAIT_V(n) asm volatile("s_waitcnt vmcnt(" #n ")" ::: "memory")
; template <class Epi, class Sched, bool ALIGN_EPI = false, bool SP2 = false>
; __device__ __forceinline__ void gemm_phase(PG8_LAS unsigned char* lds, const Gemm g, const Sched& S, const Epi& E) {
;     ...
;             PG8_LDB(B0, 0, 0); PG8_LDB(B1, 0, 1); PG8_SCHED; PG8_LDA(At, 0, 0); PG8_STAGE(PG8_SA(1, 1), a1 + hstep, voffA);
;             PG8_WAIT_V(8); PG8_WAIT_L(0); PG8_BAR; PG8_MMA(0, 0, At, B0); PG8_MMA(0, 1, At, B1); PG8_BAR; PG8_SCHED;
;             PG8_LDA(At, 0, 1); PG8_STAGE(PG8_SB(0, 0), b2, voffB); PG8_STAGE(PG8_SB(0, 1), b2 + hstep, voffB); PG8_STAGE(PG8_SA(0, 0), a2, voffA);
;             PG8_WAIT_V(8); PG8_WAIT_L(0); PG8_BAR; PG8_MMA(1, 0, At, B0); PG8_MMA(1, 1, At, B1); PG8_BAR; PG8_SCHED;
;             PG8_LDB(B0, 1, 0); PG8_LDB(B1, 1, 1); PG8_SCHED; PG8_LDA(At, 1, 0); PG8_STAGE(PG8_SA(0, 1), a2 + hstep, voffA);
;             PG8_WAIT_V(8); PG8_WAIT_L(0); PG8_BAR; PG8_MMA(0, 0, At, B0); PG8_MMA(0, 1, At, B1); PG8_BAR; PG8_SCHED;
;             PG8_LDA(At, 1, 1); PG8_STAGE(PG8_SB(1, 0), b3, voffB); PG8_STAGE(PG8_SB(1, 1), b3 + hstep, voffB); PG8_STAGE(PG8_SA(1, 0), a3, voffA);
;             PG8_WAIT_V(8); PG8_WAIT_L(0); PG8_BAR; PG8_MMA(1, 0, At, B0); PG8_MMA(1, 1, At, B1); PG8_BAR; PG8_SCHED;
	s_add_i32 s42, s55, s5
	v_lshl_add_u64 v[140:141], v[140:141], 0, s[58:59]
	s_mov_b32 m0, s42
	ds_read_b128 v[178:181], v145 offset:49152
	ds_read_b128 v[182:185], v145 offset:50176
	ds_read_b128 v[186:189], v145 offset:51200
	ds_read_b128 v[190:193], v145 offset:52224
	ds_read_b128 v[198:201], v145 offset:53248
	ds_read_b128 v[202:205], v145 offset:54272
	ds_read_b128 v[206:209], v145 offset:55296
	ds_read_b128 v[210:213], v145 offset:56320
	global_load_lds_dwordx4 v[140:141], off
	s_add_i32 m0, s42, 0x2000
	s_add_u32 s40, s40, 0x40080
	v_lshl_add_u64 v[140:141], v[214:215], 0, s[58:59]
	s_addc_u32 s41, s41, 0
	s_add_i32 s42, s63, s5
	global_load_lds_dwordx4 v[140:141], off
	v_lshl_add_u64 v[140:141], s[40:41], 0, v[0:1]
	s_mov_b32 m0, s42
	s_nop 0
	global_load_lds_dwordx4 v[140:141], off
	v_lshl_add_u64 v[140:141], s[40:41], 0, v[130:131]
	s_add_i32 m0, s42, 0x2000
	s_nop 0
	global_load_lds_dwordx4 v[140:141], off
	v_lshl_add_u64 v[140:141], v[216:217], 0, s[58:59]
	s_mov_b32 m0, s37
	s_nop 0
	global_load_lds_dwordx4 v[140:141], off
	v_lshl_add_u64 v[140:141], v[218:219], 0, s[58:59]
	s_mov_b32 m0, s44
	s_nop 0
	global_load_lds_dwordx4 v[140:141], off
	s_waitcnt vmcnt(8)
	s_waitcnt lgkmcnt(0)
	s_barrier
	s_waitcnt lgkmcnt(0)
	v_mfma_f32_16x16x32_bf16 v[62:65], v[146:149], v[178:181], v[62:65]
	v_mfma_f32_16x16x32_bf16 v[58:61], v[154:157], v[178:181], v[58:61]
	v_mfma_f32_16x16x32_bf16 v[54:57], v[146:149], v[186:189], v[54:57]
	v_mfma_f32_16x16x32_bf16 v[46:49], v[154:157], v[186:189], v[46:49]
	v_mfma_f32_16x16x32_bf16 v[38:41], v[146:149], v[198:201], v[38:41]
	v_mfma_f32_16x16x32_bf16 v[30:33], v[154:157], v[198:201], v[30:33]
	v_mfma_f32_16x16x32_bf16 v[22:25], v[146:149], v[206:209], v[22:25]
	v_mfma_f32_16x16x32_bf16 v[14:17], v[154:157], v[206:209], v[14:17]
	v_mfma_f32_16x16x32_bf16 v[62:65], v[150:153], v[182:185], v[62:65]
	v_mfma_f32_16x16x32_bf16 v[58:61], v[158:161], v[182:185], v[58:61]
	v_mfma_f32_16x16x32_bf16 v[54:57], v[150:153], v[190:193], v[54:57]
	v_mfma_f32_16x16x32_bf16 v[46:49], v[158:161], v[190:193], v[46:49]
	v_mfma_f32_16x16x32_bf16 v[38:41], v[150:153], v[202:205], v[38:41]
	v_mfma_f32_16x16x32_bf16 v[30:33], v[158:161], v[202:205], v[30:33]
	v_mfma_f32_16x16x32_bf16 v[22:25], v[150:153], v[210:213], v[22:25]
	v_mfma_f32_16x16x32_bf16 v[14:17], v[158:161], v[210:213], v[14:17]
	v_mfma_f32_16x16x32_bf16 v[50:53], v[162:165], v[178:181], v[50:53]
	v_mfma_f32_16x16x32_bf16 v[42:45], v[170:173], v[178:181], v[42:45]
	v_mfma_f32_16x16x32_bf16 v[34:37], v[162:165], v[186:189], v[34:37]
	v_mfma_f32_16x16x32_bf16 v[26:29], v[170:173], v[186:189], v[26:29]
	v_mfma_f32_16x16x32_bf16 v[18:21], v[162:165], v[198:201], v[18:21]
	v_mfma_f32_16x16x32_bf16 v[10:13], v[170:173], v[198:201], v[10:13]
	v_mfma_f32_16x16x32_bf16 v[6:9], v[162:165], v[206:209], v[6:9]
	v_mfma_f32_16x16x32_bf16 v[2:5], v[170:173], v[206:209], v[2:5]
	v_mfma_f32_16x16x32_bf16 v[50:53], v[166:169], v[182:185], v[50:53]
	v_mfma_f32_16x16x32_bf16 v[42:45], v[174:177], v[182:185], v[42:45]
	v_mfma_f32_16x16x32_bf16 v[34:37], v[166:169], v[190:193], v[34:37]
	v_mfma_f32_16x16x32_bf16 v[26:29], v[174:177], v[190:193], v[26:29]
	v_mfma_f32_16x16x32_bf16 v[18:21], v[166:169], v[202:205], v[18:21]
	v_mfma_f32_16x16x32_bf16 v[10:13], v[174:177], v[202:205], v[10:13]
	v_mfma_f32_16x16x32_bf16 v[6:9], v[166:169], v[210:213], v[6:9]
	v_mfma_f32_16x16x32_bf16 v[2:5], v[174:177], v[210:213], v[2:5]
	s_barrier
	s_add_i32 s54, s54, 2
	s_add_u32 s38, s38, 0x100
	s_addc_u32 s39, s39, 0
	s_add_u32 s50, s50, 0x100
	s_addc_u32 s51, s51, 0
	s_cmp_gt_u32 s54, 13
	s_cbranch_scc1 .Lpeel_done_767
.LBB0_767:
	s_add_u32 s40, s38, 0xfffc0080
	s_addc_u32 s41, s39, -1
	s_add_i32 s55, 0, 0x10000
	s_cmp_eq_u32 s54, 12
	s_cselect_b32 s43, s17, s41
	s_cselect_b32 s42, s48, s40
	v_add_u32_e32 v140, s55, v143
	s_cselect_b32 s41, s15, s51
	s_cselect_b32 s40, s49, s50
	s_add_i32 s63, 0, 0x14000
	ds_read_b128 v[146:149], v140
	ds_read_b128 v[150:153], v140 offset:1024
	ds_read_b128 v[154:157], v140 offset:2048
	ds_read_b128 v[158:161], v140 offset:3072
	v_add_u32_e32 v140, s63, v143
	ds_read_b128 v[162:165], v140
	ds_read_b128 v[166:169], v140 offset:1024
	ds_read_b128 v[170:173], v140 offset:2048
	ds_read_b128 v[174:177], v140 offset:3072
	v_lshl_add_u64 v[140:141], s[38:39], 0, v[136:137]
	s_add_i32 m0, s19, 0xc000
	ds_read_b128 v[178:181], v145
	ds_read_b128 v[182:185], v145 offset:1024
	ds_read_b128 v[186:189], v145 offset:2048
	ds_read_b128 v[190:193], v145 offset:3072
	ds_read_b128 v[198:201], v145 offset:4096
	ds_read_b128 v[202:205], v145 offset:5120
	ds_read_b128 v[206:209], v145 offset:6144
	ds_read_b128 v[210:213], v145 offset:7168
	global_load_lds_dwordx4 v[140:141], off
	v_lshl_add_u64 v[140:141], s[38:39], 0, v[138:139]
	s_add_i32 m0, s19, 0xe000
	s_nop 0
	global_load_lds_dwordx4 v[140:141], off
	s_waitcnt vmcnt(8)
	s_waitcnt lgkmcnt(0)
	s_barrier
; #define PG8_STAGE(bufoff, gbase, voff) do { _Pragma("unroll") for (int _i = 0; _i < 2; ++_i) \
;         __builtin_amdgcn_global_load_lds((const unsigned*)((const char*)(gbase) + (voff)[_i]), (PG8_LAS unsigned*)(lds + (bufoff) + ldsw + _i * 8192), 16, 0, 0); } while (0)
; #define PG8_LDA(dst, b, h) do { _Pragma("unroll") for (int m = 0; m < 4; ++m) _Pragma("unroll") for (int k = 0; k < 2; ++k) dst[m][k] = *(const PG8_LAS bf16x8*)(lds + PG8_SA(b, h) + aoff + m * 2048 + k * 1024); } while (0)
; #define PG8_LDB(dst, b, h) do { _Pragma("unroll") for (int n = 0; n < 2; ++n) _Pragma("unroll") for (int k = 0; k < 2; ++k) dst[n][k] = *(const PG8_LAS bf16x8*)(lds + PG8_SB(b, h) + boff + n * 2048 + k * 1024); } while (0)
; #define PG8_MMA(ai, bj, At, Bt) do { __builtin_amdgcn_s_setprio(1); _Pragma("unroll") for (int m = 0; m < 4; ++m) _Pragma("unroll") for (int n = 0; n < 2; ++n) _Pragma("unroll") for (int k = 0; k < 2; ++k) \
;         acc[ai][bj][m][n] = __builtin_amdgcn_mfma_f32_16x16x32_bf16(Bt[n][k], At[m][k], acc[ai][bj][m][n], 0, 0, 0); __builtin_amdgcn_s_setprio(0); } while (0)
; #define PG8_WAIT_V(n) asm volatile("s_waitcnt vmcnt(" #n ")" ::: "memory")
; template <class Epi, class Sched, bool ALIGN_EPI = false, bool SP2 = false>
; __device__ __forceinline__ void gemm_phase(PG8_LAS unsigned char* lds, const Gemm g, const Sched& S, const Epi& E) {
;     ...
;             PG8_LDB(B0, 0, 0); PG8_LDB(B1, 0, 1); PG8_SCHED; PG8_LDA(At, 0, 0); PG8_STAGE(PG8_SA(1, 1), a1 + hstep, voffA);
;             PG8_WAIT_V(8); PG8_WAIT_L(0); PG8_BAR; PG8_MMA(0, 0, At, B0); PG8_MMA(0, 1, At, B1); PG8_BAR; PG8_SCHED;
;             PG8_LDA(At, 0, 1); PG8_STAGE(PG8_SB(0, 0), b2, voffB); PG8_STAGE(PG8_SB(0, 1), b2 + hstep, voffB); PG8_STAGE(PG8_SA(0, 0), a2, voffA);
;             PG8_WAIT_V(8); PG8_WAIT_L(0); PG8_BAR; PG8_MMA(1, 0, At, B0); PG8_MMA(1, 1, At, B1); PG8_BAR; PG8_SCHED;
;             PG8_LDB(B0, 1, 0); PG8_LDB(B1, 1, 1); PG8_SCHED; PG8_LDA(At, 1, 0); PG8_STAGE(PG8_SA(0, 1), a2 + hstep, voffA);
;             PG8_WAIT_V(8); PG8_WAIT_L(0); PG8_BAR; PG8_MMA(0, 0, At, B0); PG8_MMA(0, 1, At, B1); PG8_BAR; PG8_SCHED;
;             PG8_LDA(At, 1, 1); PG8_STAGE(PG8_SB(1, 0), b3, voffB); PG8_STAGE(PG8_SB(1, 1), b3 + hstep, voffB); PG8_STAGE(PG8_SA(1, 0), a3, voffA);
;             PG8_WAIT_V(8); PG8_WAIT_L(0); PG8_BAR; PG8_MMA(1, 0, At, B0); PG8_MMA(1, 1, At, B1); PG8_BAR; PG8_SCHED;
	s_waitcnt lgkmcnt(0)
	v_mfma_f32_16x16x32_bf16 v[126:129], v[146:149], v[178:181], v[126:129]
	v_mfma_f32_16x16x32_bf16 v[122:125], v[154:157], v[178:181], v[122:125]
	v_mfma_f32_16x16x32_bf16 v[118:121], v[146:149], v[186:189], v[118:121]
	v_mfma_f32_16x16x32_bf16 v[110:113], v[154:157], v[186:189], v[110:113]
	v_mfma_f32_16x16x32_bf16 v[102:105], v[146:149], v[198:201], v[102:105]
	v_mfma_f32_16x16x32_bf16 v[94:97], v[154:157], v[198:201], v[94:97]
	v_mfma_f32_16x16x32_bf16 v[86:89], v[146:149], v[206:209], v[86:89]
	v_mfma_f32_16x16x32_bf16 v[78:81], v[154:157], v[206:209], v[78:81]
	v_mfma_f32_16x16x32_bf16 v[126:129], v[150:153], v[182:185], v[126:129]
	v_mfma_f32_16x16x32_bf16 v[122:125], v[158:161], v[182:185], v[122:125]
	v_mfma_f32_16x16x32_bf16 v[118:121], v[150:153], v[190:193], v[118:121]
	v_mfma_f32_16x16x32_bf16 v[110:113], v[158:161], v[190:193], v[110:113]
	v_mfma_f32_16x16x32_bf16 v[102:105], v[150:153], v[202:205], v[102:105]
	v_mfma_f32_16x16x32_bf16 v[94:97], v[158:161], v[202:205], v[94:97]
	v_mfma_f32_16x16x32_bf16 v[86:89], v[150:153], v[210:213], v[86:89]
	v_mfma_f32_16x16x32_bf16 v[78:81], v[158:161], v[210:213], v[78:81]
	v_mfma_f32_16x16x32_bf16 v[114:117], v[162:165], v[178:181], v[114:117]
	v_mfma_f32_16x16x32_bf16 v[106:109], v[170:173], v[178:181], v[106:109]
	v_mfma_f32_16x16x32_bf16 v[98:101], v[162:165], v[186:189], v[98:101]
	v_mfma_f32_16x16x32_bf16 v[90:93], v[170:173], v[186:189], v[90:93]
	v_mfma_f32_16x16x32_bf16 v[82:85], v[162:165], v[198:201], v[82:85]
	v_mfma_f32_16x16x32_bf16 v[74:77], v[170:173], v[198:201], v[74:77]
	v_mfma_f32_16x16x32_bf16 v[70:73], v[162:165], v[206:209], v[70:73]
	v_mfma_f32_16x16x32_bf16 v[66:69], v[170:173], v[206:209], v[66:69]
	v_mfma_f32_16x16x32_bf16 v[114:117], v[166:169], v[182:185], v[114:117]
	v_mfma_f32_16x16x32_bf16 v[106:109], v[174:177], v[182:185], v[106:109]
	v_mfma_f32_16x16x32_bf16 v[98:101], v[166:169], v[190:193], v[98:101]
	v_mfma_f32_16x16x32_bf16 v[90:93], v[174:177], v[190:193], v[90:93]
	v_mfma_f32_16x16x32_bf16 v[82:85], v[166:169], v[202:205], v[82:85]
	v_mfma_f32_16x16x32_bf16 v[74:77], v[174:177], v[202:205], v[74:77]
	v_mfma_f32_16x16x32_bf16 v[70:73], v[166:169], v[210:213], v[70:73]
	v_mfma_f32_16x16x32_bf16 v[66:69], v[174:177], v[210:213], v[66:69]
	s_barrier
	s_add_i32 s55, s55, s5
	v_lshl_add_u64 v[140:141], s[40:41], 0, v[0:1]
	s_mov_b32 m0, s55
	ds_read_b128 v[178:181], v145 offset:16384
	ds_read_b128 v[182:185], v145 offset:17408
	ds_read_b128 v[186:189], v145 offset:18432
	ds_read_b128 v[190:193], v145 offset:19456
	ds_read_b128 v[198:201], v145 offset:20480
	ds_read_b128 v[202:205], v145 offset:21504
	ds_read_b128 v[206:209], v145 offset:22528
	ds_read_b128 v[210:213], v145 offset:23552
	global_load_lds_dwordx4 v[140:141], off
	s_add_i32 m0, s55, 0x2000
	s_add_u32 s72, s40, 0x40000
	v_lshl_add_u64 v[214:215], s[40:41], 0, v[130:131]
	s_addc_u32 s73, s41, 0
	s_add_i32 s55, s63, s5
	global_load_lds_dwordx4 v[214:215], off
	v_lshl_add_u64 v[216:217], s[72:73], 0, v[0:1]
	s_mov_b32 m0, s55
	v_lshl_add_u64 v[218:219], s[42:43], 0, v[132:133]
	global_load_lds_dwordx4 v[216:217], off
	v_lshl_add_u64 v[216:217], s[72:73], 0, v[130:131]
	s_add_i32 m0, s55, 0x2000
	s_nop 0
	global_load_lds_dwordx4 v[216:217], off
	v_lshl_add_u64 v[216:217], s[42:43], 0, v[134:135]
	s_mov_b32 m0, s19
	s_nop 0
	global_load_lds_dwordx4 v[216:217], off
	s_mov_b32 m0, s27
	s_nop 0
	global_load_lds_dwordx4 v[218:219], off
	s_waitcnt vmcnt(8)
	s_waitcnt lgkmcnt(0)
	s_barrier
	s_waitcnt lgkmcnt(0)
	v_mfma_f32_16x16x32_bf16 v[62:65], v[146:149], v[178:181], v[62:65]
	v_mfma_f32_16x16x32_bf16 v[58:61], v[154:157], v[178:181], v[58:61]
	v_mfma_f32_16x16x32_bf16 v[54:57], v[146:149], v[186:189], v[54:57]
	v_mfma_f32_16x16x32_bf16 v[46:49], v[154:157], v[186:189], v[46:49]
	v_mfma_f32_16x16x32_bf16 v[38:41], v[146:149], v[198:201], v[38:41]
	v_mfma_f32_16x16x32_bf16 v[30:33], v[154:157], v[198:201], v[30:33]
	v_mfma_f32_16x16x32_bf16 v[22:25], v[146:149], v[206:209], v[22:25]
	v_mfma_f32_16x16x32_bf16 v[14:17], v[154:157], v[206:209], v[14:17]
	v_mfma_f32_16x16x32_bf16 v[62:65], v[150:153], v[182:185], v[62:65]
	v_mfma_f32_16x16x32_bf16 v[58:61], v[158:161], v[182:185], v[58:61]
	v_mfma_f32_16x16x32_bf16 v[54:57], v[150:153], v[190:193], v[54:57]
	v_mfma_f32_16x16x32_bf16 v[46:49], v[158:161], v[190:193], v[46:49]
	v_mfma_f32_16x16x32_bf16 v[38:41], v[150:153], v[202:205], v[38:41]
	v_mfma_f32_16x16x32_bf16 v[30:33], v[158:161], v[202:205], v[30:33]
	v_mfma_f32_16x16x32_bf16 v[22:25], v[150:153], v[210:213], v[22:25]
	v_mfma_f32_16x16x32_bf16 v[14:17], v[158:161], v[210:213], v[14:17]
	v_mfma_f32_16x16x32_bf16 v[50:53], v[162:165], v[178:181], v[50:53]
	v_mfma_f32_16x16x32_bf16 v[42:45], v[170:173], v[178:181], v[42:45]
	v_mfma_f32_16x16x32_bf16 v[34:37], v[162:165], v[186:189], v[34:37]
	v_mfma_f32_16x16x32_bf16 v[26:29], v[170:173], v[186:189], v[26:29]
	v_mfma_f32_16x16x32_bf16 v[18:21], v[162:165], v[198:201], v[18:21]
	v_mfma_f32_16x16x32_bf16 v[10:13], v[170:173], v[198:201], v[10:13]
	v_mfma_f32_16x16x32_bf16 v[6:9], v[162:165], v[206:209], v[6:9]
	v_mfma_f32_16x16x32_bf16 v[2:5], v[170:173], v[206:209], v[2:5]
	v_mfma_f32_16x16x32_bf16 v[50:53], v[166:169], v[182:185], v[50:53]
	v_mfma_f32_16x16x32_bf16 v[42:45], v[174:177], v[182:185], v[42:45]
	v_mfma_f32_16x16x32_bf16 v[34:37], v[166:169], v[190:193], v[34:37]
	v_mfma_f32_16x16x32_bf16 v[26:29], v[174:177], v[190:193], v[26:29]
	v_mfma_f32_16x16x32_bf16 v[18:21], v[166:169], v[202:205], v[18:21]
	v_mfma_f32_16x16x32_bf16 v[10:13], v[174:177], v[202:205], v[10:13]
	v_mfma_f32_16x16x32_bf16 v[6:9], v[166:169], v[210:213], v[6:9]
	v_mfma_f32_16x16x32_bf16 v[2:5], v[174:177], v[210:213], v[2:5]
	s_barrier
; #define PG8_STAGE(bufoff, gbase, voff) do { _Pragma("unroll") for (int _i = 0; _i < 2; ++_i) \
;         __builtin_amdgcn_global_load_lds((const unsigned*)((const char*)(gbase) + (voff)[_i]), (PG8_LAS unsigned*)(lds + (bufoff) + ldsw + _i * 8192), 16, 0, 0); } while (0)
; #define PG8_LDA(dst, b, h) do { _Pragma("unroll") for (int m = 0; m < 4; ++m) _Pragma("unroll") for (int k = 0; k < 2; ++k) dst[m][k] = *(const PG8_LAS bf16x8*)(lds + PG8_SA(b, h) + aoff + m * 2048 + k * 1024); } while (0)
; #define PG8_LDB(dst, b, h) do { _Pragma("unroll") for (int n = 0; n < 2; ++n) _Pragma("unroll") for (int k = 0; k < 2; ++k) dst[n][k] = *(const PG8_LAS bf16x8*)(lds + PG8_SB(b, h) + boff + n * 2048 + k * 1024); } while (0)
; #define PG8_MMA(ai, bj, At, Bt) do { __builtin_amdgcn_s_setprio(1); _Pragma("unroll") for (int m = 0; m < 4; ++m) _Pragma("unroll") for (int n = 0; n < 2; ++n) _Pragma("unroll") for (int k = 0; k < 2; ++k) \
;         acc[ai][bj][m][n] = __builtin_amdgcn_mfma_f32_16x16x32_bf16(Bt[n][k], At[m][k], acc[ai][bj][m][n], 0, 0, 0); __builtin_amdgcn_s_setprio(0); } while (0)
; #define PG8_WAIT_V(n) asm volatile("s_waitcnt vmcnt(" #n ")" ::: "memory")
; #define PG8_WAIT_L(n) asm volatile("s_waitcnt lgkmcnt(" #n ")" ::: "memory")
; #define PG8_BAR __builtin_amdgcn_s_barrier()
; #define PG8_SCHED __builtin_amdgcn_sched_barrier(0)
; template <class Epi, class Sched, bool ALIGN_EPI = false, bool SP2 = false>
; __device__ __forceinline__ void gemm_phase(PG8_LAS unsigned char* lds, const Gemm g, const Sched& S, const Epi& E) {
;     ...
;             PG8_LDB(B0, 1, 0); PG8_LDB(B1, 1, 1); PG8_SCHED; PG8_LDA(At, 1, 0); PG8_STAGE(PG8_SA(0, 1), a2 + hstep, voffA);
;             PG8_WAIT_V(8); PG8_WAIT_L(0); PG8_BAR; PG8_MMA(0, 0, At, B0); PG8_MMA(0, 1, At, B1); PG8_BAR; PG8_SCHED;
;             PG8_LDA(At, 1, 1); PG8_STAGE(PG8_SB(1, 0), b3, voffB); PG8_STAGE(PG8_SB(1, 1), b3 + hstep, voffB); PG8_STAGE(PG8_SA(1, 0), a3, voffA);
;             PG8_WAIT_V(8); PG8_WAIT_L(0); PG8_BAR; PG8_MMA(1, 0, At, B0); PG8_MMA(1, 1, At, B1); PG8_BAR; PG8_SCHED;
	s_add_i32 s55, 0, 0x18000
	s_add_i32 s63, 0, 0x1c000
	v_add_u32_e32 v158, s55, v143
	v_add_u32_e32 v174, s63, v143
	ds_read_b128 v[146:149], v158
	ds_read_b128 v[150:153], v158 offset:1024
	ds_read_b128 v[154:157], v158 offset:2048
	ds_read_b128 v[158:161], v158 offset:3072
	ds_read_b128 v[162:165], v174
	ds_read_b128 v[166:169], v174 offset:1024
	ds_read_b128 v[170:173], v174 offset:2048
	ds_read_b128 v[174:177], v174 offset:3072
	s_add_u32 s42, s42, 0x40000
	s_addc_u32 s43, s43, 0
	s_mov_b32 m0, s28
	v_lshl_add_u64 v[220:221], s[42:43], 0, v[134:135]
	ds_read_b128 v[178:181], v145 offset:32768
	ds_read_b128 v[182:185], v145 offset:33792
	ds_read_b128 v[186:189], v145 offset:34816
	ds_read_b128 v[190:193], v145 offset:35840
	ds_read_b128 v[198:201], v145 offset:36864
	ds_read_b128 v[202:205], v145 offset:37888
	ds_read_b128 v[206:209], v145 offset:38912
	ds_read_b128 v[210:213], v145 offset:39936
	global_load_lds_dwordx4 v[220:221], off
	v_lshl_add_u64 v[220:221], s[42:43], 0, v[132:133]
	s_mov_b32 m0, s29
	s_nop 0
	global_load_lds_dwordx4 v[220:221], off
	s_waitcnt vmcnt(8)
	s_waitcnt lgkmcnt(0)
	s_barrier
	s_waitcnt lgkmcnt(0)
	v_mfma_f32_16x16x32_bf16 v[126:129], v[146:149], v[178:181], v[126:129]
	v_mfma_f32_16x16x32_bf16 v[122:125], v[154:157], v[178:181], v[122:125]
	v_mfma_f32_16x16x32_bf16 v[118:121], v[146:149], v[186:189], v[118:121]
	v_mfma_f32_16x16x32_bf16 v[110:113], v[154:157], v[186:189], v[110:113]
	v_mfma_f32_16x16x32_bf16 v[102:105], v[146:149], v[198:201], v[102:105]
	v_mfma_f32_16x16x32_bf16 v[94:97], v[154:157], v[198:201], v[94:97]
	v_mfma_f32_16x16x32_bf16 v[86:89], v[146:149], v[206:209], v[86:89]
	v_mfma_f32_16x16x32_bf16 v[78:81], v[154:157], v[206:209], v[78:81]
	v_mfma_f32_16x16x32_bf16 v[126:129], v[150:153], v[182:185], v[126:129]
	v_mfma_f32_16x16x32_bf16 v[122:125], v[158:161], v[182:185], v[122:125]
	v_mfma_f32_16x16x32_bf16 v[118:121], v[150:153], v[190:193], v[118:121]
	v_mfma_f32_16x16x32_bf16 v[110:113], v[158:161], v[190:193], v[110:113]
	v_mfma_f32_16x16x32_bf16 v[102:105], v[150:153], v[202:205], v[102:105]
	v_mfma_f32_16x16x32_bf16 v[94:97], v[158:161], v[202:205], v[94:97]
	v_mfma_f32_16x16x32_bf16 v[86:89], v[150:153], v[210:213], v[86:89]
	v_mfma_f32_16x16x32_bf16 v[78:81], v[158:161], v[210:213], v[78:81]
	v_mfma_f32_16x16x32_bf16 v[114:117], v[162:165], v[178:181], v[114:117]
	v_mfma_f32_16x16x32_bf16 v[106:109], v[170:173], v[178:181], v[106:109]
	v_mfma_f32_16x16x32_bf16 v[98:101], v[162:165], v[186:189], v[98:101]
	v_mfma_f32_16x16x32_bf16 v[90:93], v[170:173], v[186:189], v[90:93]
	v_mfma_f32_16x16x32_bf16 v[82:85], v[162:165], v[198:201], v[82:85]
	v_mfma_f32_16x16x32_bf16 v[74:77], v[170:173], v[198:201], v[74:77]
	v_mfma_f32_16x16x32_bf16 v[70:73], v[162:165], v[206:209], v[70:73]
	v_mfma_f32_16x16x32_bf16 v[66:69], v[170:173], v[206:209], v[66:69]
	v_mfma_f32_16x16x32_bf16 v[114:117], v[166:169], v[182:185], v[114:117]
	v_mfma_f32_16x16x32_bf16 v[106:109], v[174:177], v[182:185], v[106:109]
	v_mfma_f32_16x16x32_bf16 v[98:101], v[166:169], v[190:193], v[98:101]
	v_mfma_f32_16x16x32_bf16 v[90:93], v[174:177], v[190:193], v[90:93]
	v_mfma_f32_16x16x32_bf16 v[82:85], v[166:169], v[202:205], v[82:85]
	v_mfma_f32_16x16x32_bf16 v[74:77], v[174:177], v[202:205], v[74:77]
	v_mfma_f32_16x16x32_bf16 v[70:73], v[166:169], v[210:213], v[70:73]
	v_mfma_f32_16x16x32_bf16 v[66:69], v[174:177], v[210:213], v[66:69]
	s_barrier
; #define PG8_STAGE(bufoff, gbase, voff) do { _Pragma("unroll") for (int _i = 0; _i < 2; ++_i) \
;         __builtin_amdgcn_global_load_lds((const unsigned*)((const char*)(gbase) + (voff)[_i]), (PG8_LAS unsigned*)(lds + (bufoff) + ldsw + _i * 8192), 16, 0, 0); } while (0)
; #define PG8_LDA(dst, b, h) do { _Pragma("unroll") for (int m = 0; m < 4; ++m) _Pragma("unroll") for (int k = 0; k < 2; ++k) dst[m][k] = *(const PG8_LAS bf16x8*)(lds + PG8_SA(b, h) + aoff + m * 2048 + k * 1024); } while (0)
; #define PG8_MMA(ai, bj, At, Bt) do { __builtin_amdgcn_s_setprio(1); _Pragma("unroll") for (int m = 0; m < 4; ++m) _Pragma("unroll") for (int n = 0; n < 2; ++n) _Pragma("unroll") for (int k = 0; k < 2; ++k) \
;         acc[ai][bj][m][n] = __builtin_amdgcn_mfma_f32_16x16x32_bf16(Bt[n][k], At[m][k], acc[ai][bj][m][n], 0, 0, 0); __builtin_amdgcn_s_setprio(0); } while (0)
; #define PG8_WAIT_V(n) asm volatile("s_waitcnt vmcnt(" #n ")" ::: "memory")
; #define PG8_WAIT_L(n) asm volatile("s_waitcnt lgkmcnt(" #n ")" ::: "memory")
; #define PG8_BAR __builtin_amdgcn_s_barrier()
; #define PG8_SCHED __builtin_amdgcn_sched_barrier(0)
; template <class Epi, class Sched, bool ALIGN_EPI = false, bool SP2 = false>
; __device__ __forceinline__ void gemm_phase(PG8_LAS unsigned char* lds, const Gemm g, const Sched& S, const Epi& E) {
;     ...
;             PG8_LDA(At, 1, 1); PG8_STAGE(PG8_SB(1, 0), b3, voffB); PG8_STAGE(PG8_SB(1, 1), b3 + hstep, voffB); PG8_STAGE(PG8_SA(1, 0), a3, voffA);
;             PG8_WAIT_V(8); PG8_WAIT_L(0); PG8_BAR; PG8_MMA(1, 0, At, B0); PG8_MMA(1, 1, At, B1); PG8_BAR; PG8_SCHED;
	s_add_i32 s42, s55, s5
	v_lshl_add_u64 v[140:141], v[140:141], 0, s[58:59]
	s_mov_b32 m0, s42
	ds_read_b128 v[178:181], v145 offset:49152
	ds_read_b128 v[182:185], v145 offset:50176
	ds_read_b128 v[186:189], v145 offset:51200
	ds_read_b128 v[190:193], v145 offset:52224
	ds_read_b128 v[198:201], v145 offset:53248
	ds_read_b128 v[202:205], v145 offset:54272
	ds_read_b128 v[206:209], v145 offset:55296
	ds_read_b128 v[210:213], v145 offset:56320
	global_load_lds_dwordx4 v[140:141], off
	s_add_i32 m0, s42, 0x2000
	s_add_u32 s40, s40, 0x40080
	v_lshl_add_u64 v[140:141], v[214:215], 0, s[58:59]
	s_addc_u32 s41, s41, 0
	s_add_i32 s42, s63, s5
	global_load_lds_dwordx4 v[140:141], off
	v_lshl_add_u64 v[140:141], s[40:41], 0, v[0:1]
	s_mov_b32 m0, s42
	s_nop 0
	global_load_lds_dwordx4 v[140:141], off
	v_lshl_add_u64 v[140:141], s[40:41], 0, v[130:131]
	s_add_i32 m0, s42, 0x2000
	s_nop 0
	global_load_lds_dwordx4 v[140:141], off
	v_lshl_add_u64 v[140:141], v[216:217], 0, s[58:59]
	s_mov_b32 m0, s37
	s_nop 0
	global_load_lds_dwordx4 v[140:141], off
	v_lshl_add_u64 v[140:141], v[218:219], 0, s[58:59]
	s_mov_b32 m0, s44
	s_nop 0
	global_load_lds_dwordx4 v[140:141], off
	s_waitcnt vmcnt(8)
	s_waitcnt lgkmcnt(0)
	s_barrier
	s_waitcnt lgkmcnt(0)
	v_mfma_f32_16x16x32_bf16 v[62:65], v[146:149], v[178:181], v[62:65]
	v_mfma_f32_16x16x32_bf16 v[58:61], v[154:157], v[178:181], v[58:61]
	v_mfma_f32_16x16x32_bf16 v[54:57], v[146:149], v[186:189], v[54:57]
	v_mfma_f32_16x16x32_bf16 v[46:49], v[154:157], v[186:189], v[46:49]
	v_mfma_f32_16x16x32_bf16 v[38:41], v[146:149], v[198:201], v[38:41]
	v_mfma_f32_16x16x32_bf16 v[30:33], v[154:157], v[198:201], v[30:33]
	v_mfma_f32_16x16x32_bf16 v[22:25], v[146:149], v[206:209], v[22:25]
	v_mfma_f32_16x16x32_bf16 v[14:17], v[154:157], v[206:209], v[14:17]
	v_mfma_f32_16x16x32_bf16 v[62:65], v[150:153], v[182:185], v[62:65]
	v_mfma_f32_16x16x32_bf16 v[58:61], v[158:161], v[182:185], v[58:61]
	v_mfma_f32_16x16x32_bf16 v[54:57], v[150:153], v[190:193], v[54:57]
	v_mfma_f32_16x16x32_bf16 v[46:49], v[158:161], v[190:193], v[46:49]
	v_mfma_f32_16x16x32_bf16 v[38:41], v[150:153], v[202:205], v[38:41]
	v_mfma_f32_16x16x32_bf16 v[30:33], v[158:161], v[202:205], v[30:33]
	v_mfma_f32_16x16x32_bf16 v[22:25], v[150:153], v[210:213], v[22:25]
	v_mfma_f32_16x16x32_bf16 v[14:17], v[158:161], v[210:213], v[14:17]
	v_mfma_f32_16x16x32_bf16 v[50:53], v[162:165], v[178:181], v[50:53]
	v_mfma_f32_16x16x32_bf16 v[42:45], v[170:173], v[178:181], v[42:45]
	v_mfma_f32_16x16x32_bf16 v[34:37], v[162:165], v[186:189], v[34:37]
	v_mfma_f32_16x16x32_bf16 v[26:29], v[170:173], v[186:189], v[26:29]
	v_mfma_f32_16x16x32_bf16 v[18:21], v[162:165], v[198:201], v[18:21]
	v_mfma_f32_16x16x32_bf16 v[10:13], v[170:173], v[198:201], v[10:13]
	v_mfma_f32_16x16x32_bf16 v[6:9], v[162:165], v[206:209], v[6:9]
	v_mfma_f32_16x16x32_bf16 v[2:5], v[170:173], v[206:209], v[2:5]
	v_mfma_f32_16x16x32_bf16 v[50:53], v[166:169], v[182:185], v[50:53]
	v_mfma_f32_16x16x32_bf16 v[42:45], v[174:177], v[182:185], v[42:45]
	v_mfma_f32_16x16x32_bf16 v[34:37], v[166:169], v[190:193], v[34:37]
	v_mfma_f32_16x16x32_bf16 v[26:29], v[174:177], v[190:193], v[26:29]
	v_mfma_f32_16x16x32_bf16 v[18:21], v[166:169], v[202:205], v[18:21]
	v_mfma_f32_16x16x32_bf16 v[10:13], v[174:177], v[202:205], v[10:13]
	v_mfma_f32_16x16x32_bf16 v[6:9], v[166:169], v[210:213], v[6:9]
	v_mfma_f32_16x16x32_bf16 v[2:5], v[174:177], v[210:213], v[2:5]
	s_barrier
	s_add_i32 s54, s54, 2
	s_add_u32 s38, s38, 0x100
	s_addc_u32 s39, s39, 0
	s_add_u32 s50, s50, 0x100
	s_addc_u32 s51, s51, 0
	s_cmp_gt_u32 s54, 13
	s_cbranch_scc0 .LBB0_767

; #define PG8_STAGE(bufoff, gbase, voff) do { _Pragma("unroll") for (int _i = 0; _i < 2; ++_i) \
;         __builtin_amdgcn_global_load_lds((const unsigned*)((const char*)(gbase) + (voff)[_i]), (PG8_LAS unsigned*)(lds + (bufoff) + ldsw + _i * 8192), 16, 0, 0); } while (0)
; #define PG8_LDA(dst, b, h) do { _Pragma("unroll") for (int m = 0; m < 4; ++m) _Pragma("unroll") for (int k = 0; k < 2; ++k) dst[m][k] = *(const PG8_LAS bf16x8*)(lds + PG8_SA(b, h) + aoff + m * 2048 + k * 1024); } while (0)
; #define PG8_LDB(dst, b, h) do { _Pragma("unroll") for (int n = 0; n < 2; ++n) _Pragma("unroll") for (int k = 0; k < 2; ++k) dst[n][k] = *(const PG8_LAS bf16x8*)(lds + PG8_SB(b, h) + boff + n * 2048 + k * 1024); } while (0)
; #define PG8_MMA(ai, bj, At, Bt) do { __builtin_amdgcn_s_setprio(1); _Pragma("unroll") for (int m = 0; m < 4; ++m) _Pragma("unroll") for (int n = 0; n < 2; ++n) _Pragma("unroll") for (int k = 0; k < 2; ++k) \
;         acc[ai][bj][m][n] = __builtin_amdgcn_mfma_f32_16x16x32_bf16(Bt[n][k], At[m][k], acc[ai][bj][m][n], 0, 0, 0); __builtin_amdgcn_s_setprio(0); } while (0)
; #define PG8_WAIT_V(n) asm volatile("s_waitcnt vmcnt(" #n ")" ::: "memory")
; #define PG8_BAR __builtin_amdgcn_s_barrier()
; template <class Epi, class Sched, bool ALIGN_EPI = false, bool SP2 = false>
; __device__ __forceinline__ void gemm_phase(PG8_LAS unsigned char* lds, const Gemm g, const Sched& S, const Epi& E) {
;     ...
;         for (int t = 0; t < nt; t += 2) {
;             const bool last = (t == nt - 2);
;             const char* a1 = cA + (size_t)(t + 1) * kstep;
;             const char* a2 = last ? nA : cA + (size_t)(t + 2) * kstep; const char* b2 = last ? nB : cB + (size_t)(t + 2) * kstep;
;             const char* a3 = a2 + kstep; const char* b3 = b2 + kstep;
;             if (last && has_next) S.a_ready(nxt);
;             if constexpr (SP2) {
;             PG8_LDB(B0, 0, 0); PG8_LDB(B1, 0, 1); PG8_SCHED; PG8_LDA(At, 0, 0); PG8_STAGE(PG8_SA(1, 1), a1 + hstep, voffA);
;             PG8_WAIT_V(8); PG8_WAIT_L(0); PG8_BAR; PG8_MMA(0, 0, At, B0); PG8_MMA(0, 1, At, B1); PG8_BAR; PG8_SCHED;
;             PG8_LDA(At, 0, 1); PG8_STAGE(PG8_SB(0, 0), b2, voffB); PG8_STAGE(PG8_SB(0, 1), b2 + hstep, voffB); PG8_STAGE(PG8_SA(0, 0), a2, voffA);
;             PG8_WAIT_V(8); PG8_WAIT_L(0); PG8_BAR; PG8_MMA(1, 0, At, B0); PG8_MMA(1, 1, At, B1); PG8_BAR; PG8_SCHED;
.LBB0_806:
	s_add_u32 s38, s38, 0x80
	s_addc_u32 s39, s39, 0
	s_add_u32 s86, s40, 0x100
	s_addc_u32 s87, s41, 0
	s_mov_b32 s40, 0
	s_waitcnt vmcnt(0)
	s_add_i32 vcc_lo, s40, 2
	s_add_u32 s72, s38, 0x80
	s_addc_u32 s41, s39, 0
	s_add_i32 vcc_hi, 0, 0x10000
	s_cmp_eq_u32 s65, s40
	s_cselect_b32 s41, s9, s41
	s_cselect_b32 s40, s8, s72
	v_add_u32_e32 v0, vcc_hi, v250
	s_cselect_b32 s73, s11, s87
	s_cselect_b32 s72, s10, s86
	s_add_i32 s78, 0, 0x14000
	ds_read_b128 v[130:133], v0
	ds_read_b128 v[134:137], v0 offset:1024
	ds_read_b128 v[138:141], v0 offset:2048
	ds_read_b128 v[142:145], v0 offset:3072
	v_add_u32_e32 v0, s78, v250
	ds_read_b128 v[146:149], v0
	ds_read_b128 v[150:153], v0 offset:1024
	ds_read_b128 v[154:157], v0 offset:2048
	ds_read_b128 v[158:161], v0 offset:3072
	v_lshl_add_u64 v[210:211], s[38:39], 0, v[206:207]
	s_add_i32 m0, s47, 0xc000
	ds_read_b128 v[162:165], v252
	ds_read_b128 v[166:169], v252 offset:1024
	ds_read_b128 v[170:173], v252 offset:2048
	ds_read_b128 v[174:177], v252 offset:3072
	ds_read_b128 v[178:181], v252 offset:4096
	ds_read_b128 v[182:185], v252 offset:5120
	ds_read_b128 v[186:189], v252 offset:6144
	ds_read_b128 v[190:193], v252 offset:7168
	global_load_lds_dwordx4 v[210:211], off
	v_lshl_add_u64 v[210:211], s[38:39], 0, v[208:209]
	s_add_i32 m0, s47, 0xe000
	s_nop 0
	global_load_lds_dwordx4 v[210:211], off
	s_waitcnt vmcnt(8)
	s_waitcnt lgkmcnt(0)
	s_barrier
	s_waitcnt lgkmcnt(0)
	v_mfma_f32_16x16x32_bf16 v[126:129], v[130:133], v[162:165], 0
	v_mfma_f32_16x16x32_bf16 v[122:125], v[138:141], v[162:165], 0
	v_mfma_f32_16x16x32_bf16 v[110:113], v[130:133], v[170:173], 0
	v_mfma_f32_16x16x32_bf16 v[106:109], v[138:141], v[170:173], 0
	v_mfma_f32_16x16x32_bf16 v[94:97], v[130:133], v[178:181], 0
	v_mfma_f32_16x16x32_bf16 v[90:93], v[138:141], v[178:181], 0
	v_mfma_f32_16x16x32_bf16 v[78:81], v[130:133], v[186:189], 0
	v_mfma_f32_16x16x32_bf16 v[74:77], v[138:141], v[186:189], 0
	v_mfma_f32_16x16x32_bf16 v[126:129], v[134:137], v[166:169], v[126:129]
	v_mfma_f32_16x16x32_bf16 v[122:125], v[142:145], v[166:169], v[122:125]
	v_mfma_f32_16x16x32_bf16 v[110:113], v[134:137], v[174:177], v[110:113]
	v_mfma_f32_16x16x32_bf16 v[106:109], v[142:145], v[174:177], v[106:109]
	v_mfma_f32_16x16x32_bf16 v[94:97], v[134:137], v[182:185], v[94:97]
	v_mfma_f32_16x16x32_bf16 v[90:93], v[142:145], v[182:185], v[90:93]
	v_mfma_f32_16x16x32_bf16 v[78:81], v[134:137], v[190:193], v[78:81]
	v_mfma_f32_16x16x32_bf16 v[74:77], v[142:145], v[190:193], v[74:77]
	v_mfma_f32_16x16x32_bf16 v[118:121], v[146:149], v[162:165], 0
	v_mfma_f32_16x16x32_bf16 v[114:117], v[154:157], v[162:165], 0
	v_mfma_f32_16x16x32_bf16 v[102:105], v[146:149], v[170:173], 0
	v_mfma_f32_16x16x32_bf16 v[98:101], v[154:157], v[170:173], 0
	v_mfma_f32_16x16x32_bf16 v[86:89], v[146:149], v[178:181], 0
	v_mfma_f32_16x16x32_bf16 v[82:85], v[154:157], v[178:181], 0
	v_mfma_f32_16x16x32_bf16 v[70:73], v[146:149], v[186:189], 0
	v_mfma_f32_16x16x32_bf16 v[66:69], v[154:157], v[186:189], 0
	v_mfma_f32_16x16x32_bf16 v[118:121], v[150:153], v[166:169], v[118:121]
	v_mfma_f32_16x16x32_bf16 v[114:117], v[158:161], v[166:169], v[114:117]
	v_mfma_f32_16x16x32_bf16 v[102:105], v[150:153], v[174:177], v[102:105]
	v_mfma_f32_16x16x32_bf16 v[98:101], v[158:161], v[174:177], v[98:101]
	v_mfma_f32_16x16x32_bf16 v[86:89], v[150:153], v[182:185], v[86:89]
	v_mfma_f32_16x16x32_bf16 v[82:85], v[158:161], v[182:185], v[82:85]
	v_mfma_f32_16x16x32_bf16 v[70:73], v[150:153], v[190:193], v[70:73]
	v_mfma_f32_16x16x32_bf16 v[66:69], v[158:161], v[190:193], v[66:69]
	s_barrier
	s_add_i32 s79, vcc_hi, s44
	v_lshl_add_u64 v[210:211], s[72:73], 0, v[198:199]
	s_mov_b32 m0, s79
	ds_read_b128 v[162:165], v252 offset:16384
	ds_read_b128 v[166:169], v252 offset:17408
	ds_read_b128 v[170:173], v252 offset:18432
	ds_read_b128 v[174:177], v252 offset:19456
	ds_read_b128 v[178:181], v252 offset:20480
	ds_read_b128 v[182:185], v252 offset:21504
	ds_read_b128 v[186:189], v252 offset:22528
	ds_read_b128 v[190:193], v252 offset:23552
	global_load_lds_dwordx4 v[210:211], off
	s_add_i32 m0, s79, 0x2000
	v_lshl_add_u64 v[212:213], s[72:73], 0, v[200:201]
	s_add_u32 s72, s72, s30
	s_addc_u32 s73, s73, 0
	s_add_i32 s78, s78, s44
	global_load_lds_dwordx4 v[212:213], off
	v_lshl_add_u64 v[214:215], s[72:73], 0, v[198:199]
	s_mov_b32 m0, s78
	v_lshl_add_u64 v[216:217], s[72:73], 0, v[200:201]
	global_load_lds_dwordx4 v[214:215], off
	s_add_i32 m0, s78, 0x2000
	v_lshl_add_u64 v[218:219], s[40:41], 0, v[198:199]
	global_load_lds_dwordx4 v[216:217], off
	s_mov_b32 m0, s47
	v_lshl_add_u64 v[220:221], s[40:41], 0, v[200:201]
	global_load_lds_dwordx4 v[218:219], off
	s_mov_b32 m0, s48
	s_nop 0
	global_load_lds_dwordx4 v[220:221], off
	s_waitcnt vmcnt(8)
	s_waitcnt lgkmcnt(0)
	s_barrier
; #define PG8_STAGE(bufoff, gbase, voff) do { _Pragma("unroll") for (int _i = 0; _i < 2; ++_i) \
;         __builtin_amdgcn_global_load_lds((const unsigned*)((const char*)(gbase) + (voff)[_i]), (PG8_LAS unsigned*)(lds + (bufoff) + ldsw + _i * 8192), 16, 0, 0); } while (0)
; #define PG8_LDA(dst, b, h) do { _Pragma("unroll") for (int m = 0; m < 4; ++m) _Pragma("unroll") for (int k = 0; k < 2; ++k) dst[m][k] = *(const PG8_LAS bf16x8*)(lds + PG8_SA(b, h) + aoff + m * 2048 + k * 1024); } while (0)
; #define PG8_LDB(dst, b, h) do { _Pragma("unroll") for (int n = 0; n < 2; ++n) _Pragma("unroll") for (int k = 0; k < 2; ++k) dst[n][k] = *(const PG8_LAS bf16x8*)(lds + PG8_SB(b, h) + boff + n * 2048 + k * 1024); } while (0)
; #define PG8_MMA(ai, bj, At, Bt) do { __builtin_amdgcn_s_setprio(1); _Pragma("unroll") for (int m = 0; m < 4; ++m) _Pragma("unroll") for (int n = 0; n < 2; ++n) _Pragma("unroll") for (int k = 0; k < 2; ++k) \
;         acc[ai][bj][m][n] = __builtin_amdgcn_mfma_f32_16x16x32_bf16(Bt[n][k], At[m][k], acc[ai][bj][m][n], 0, 0, 0); __builtin_amdgcn_s_setprio(0); } while (0)
; #define PG8_WAIT_V(n) asm volatile("s_waitcnt vmcnt(" #n ")" ::: "memory")
; template <class Epi, class Sched, bool ALIGN_EPI = false, bool SP2 = false>
; __device__ __forceinline__ void gemm_phase(PG8_LAS unsigned char* lds, const Gemm g, const Sched& S, const Epi& E) {
;     ...
;             PG8_LDB(B0, 0, 0); PG8_LDB(B1, 0, 1); PG8_SCHED; PG8_LDA(At, 0, 0); PG8_STAGE(PG8_SA(1, 1), a1 + hstep, voffA);
;             PG8_WAIT_V(8); PG8_WAIT_L(0); PG8_BAR; PG8_MMA(0, 0, At, B0); PG8_MMA(0, 1, At, B1); PG8_BAR; PG8_SCHED;
;             PG8_LDA(At, 0, 1); PG8_STAGE(PG8_SB(0, 0), b2, voffB); PG8_STAGE(PG8_SB(0, 1), b2 + hstep, voffB); PG8_STAGE(PG8_SA(0, 0), a2, voffA);
;             PG8_WAIT_V(8); PG8_WAIT_L(0); PG8_BAR; PG8_MMA(1, 0, At, B0); PG8_MMA(1, 1, At, B1); PG8_BAR; PG8_SCHED;
;             PG8_LDB(B0, 1, 0); PG8_LDB(B1, 1, 1); PG8_SCHED; PG8_LDA(At, 1, 0); PG8_STAGE(PG8_SA(0, 1), a2 + hstep, voffA);
;             PG8_WAIT_V(8); PG8_WAIT_L(0); PG8_BAR; PG8_MMA(0, 0, At, B0); PG8_MMA(0, 1, At, B1); PG8_BAR; PG8_SCHED;
;             PG8_LDA(At, 1, 1); PG8_STAGE(PG8_SB(1, 0), b3, voffB); PG8_STAGE(PG8_SB(1, 1), b3 + hstep, voffB); PG8_STAGE(PG8_SA(1, 0), a3, voffA);
;             PG8_WAIT_V(8); PG8_WAIT_L(0); PG8_BAR; PG8_MMA(1, 0, At, B0); PG8_MMA(1, 1, At, B1); PG8_BAR; PG8_SCHED;
	s_waitcnt lgkmcnt(0)
	v_mfma_f32_16x16x32_bf16 v[62:65], v[130:133], v[162:165], 0
	v_mfma_f32_16x16x32_bf16 v[58:61], v[138:141], v[162:165], 0
	v_mfma_f32_16x16x32_bf16 v[50:53], v[130:133], v[170:173], 0
	v_mfma_f32_16x16x32_bf16 v[42:45], v[138:141], v[170:173], 0
	v_mfma_f32_16x16x32_bf16 v[34:37], v[130:133], v[178:181], 0
	v_mfma_f32_16x16x32_bf16 v[26:29], v[138:141], v[178:181], 0
	v_mfma_f32_16x16x32_bf16 v[18:21], v[130:133], v[186:189], 0
	v_mfma_f32_16x16x32_bf16 v[14:17], v[138:141], v[186:189], 0
	v_mfma_f32_16x16x32_bf16 v[62:65], v[134:137], v[166:169], v[62:65]
	v_mfma_f32_16x16x32_bf16 v[58:61], v[142:145], v[166:169], v[58:61]
	v_mfma_f32_16x16x32_bf16 v[50:53], v[134:137], v[174:177], v[50:53]
	v_mfma_f32_16x16x32_bf16 v[42:45], v[142:145], v[174:177], v[42:45]
	v_mfma_f32_16x16x32_bf16 v[34:37], v[134:137], v[182:185], v[34:37]
	v_mfma_f32_16x16x32_bf16 v[26:29], v[142:145], v[182:185], v[26:29]
	v_mfma_f32_16x16x32_bf16 v[18:21], v[134:137], v[190:193], v[18:21]
	v_mfma_f32_16x16x32_bf16 v[14:17], v[142:145], v[190:193], v[14:17]
	v_mfma_f32_16x16x32_bf16 v[54:57], v[146:149], v[162:165], 0
	v_mfma_f32_16x16x32_bf16 v[46:49], v[154:157], v[162:165], 0
	v_mfma_f32_16x16x32_bf16 v[38:41], v[146:149], v[170:173], 0
	v_mfma_f32_16x16x32_bf16 v[30:33], v[154:157], v[170:173], 0
	v_mfma_f32_16x16x32_bf16 v[22:25], v[146:149], v[178:181], 0
	v_mfma_f32_16x16x32_bf16 v[10:13], v[154:157], v[178:181], 0
	v_mfma_f32_16x16x32_bf16 v[6:9], v[146:149], v[186:189], 0
	v_mfma_f32_16x16x32_bf16 v[2:5], v[154:157], v[186:189], 0
	v_mfma_f32_16x16x32_bf16 v[54:57], v[150:153], v[166:169], v[54:57]
	v_mfma_f32_16x16x32_bf16 v[46:49], v[158:161], v[166:169], v[46:49]
	v_mfma_f32_16x16x32_bf16 v[38:41], v[150:153], v[174:177], v[38:41]
	v_mfma_f32_16x16x32_bf16 v[30:33], v[158:161], v[174:177], v[30:33]
	v_mfma_f32_16x16x32_bf16 v[22:25], v[150:153], v[182:185], v[22:25]
	v_mfma_f32_16x16x32_bf16 v[10:13], v[158:161], v[182:185], v[10:13]
	v_mfma_f32_16x16x32_bf16 v[6:9], v[150:153], v[190:193], v[6:9]
	v_mfma_f32_16x16x32_bf16 v[2:5], v[158:161], v[190:193], v[2:5]
	s_barrier
	s_add_i32 s72, 0, 0x18000
	v_add_u32_e32 v0, s72, v250
	s_add_i32 s73, 0, 0x1c000
	ds_read_b128 v[130:133], v0
	ds_read_b128 v[134:137], v0 offset:1024
	ds_read_b128 v[138:141], v0 offset:2048
	ds_read_b128 v[142:145], v0 offset:3072
	v_add_u32_e32 v0, s73, v250
	ds_read_b128 v[146:149], v0
	ds_read_b128 v[150:153], v0 offset:1024
	ds_read_b128 v[154:157], v0 offset:2048
	ds_read_b128 v[158:161], v0 offset:3072
	s_add_u32 s40, s40, s30
	s_addc_u32 s41, s41, 0
	s_mov_b32 m0, s49
	v_lshl_add_u64 v[222:223], s[40:41], 0, v[198:199]
	ds_read_b128 v[162:165], v252 offset:32768
	ds_read_b128 v[166:169], v252 offset:33792
	ds_read_b128 v[170:173], v252 offset:34816
	ds_read_b128 v[174:177], v252 offset:35840
	ds_read_b128 v[178:181], v252 offset:36864
	ds_read_b128 v[182:185], v252 offset:37888
	ds_read_b128 v[186:189], v252 offset:38912
	ds_read_b128 v[190:193], v252 offset:39936
	global_load_lds_dwordx4 v[222:223], off
	v_lshl_add_u64 v[222:223], s[40:41], 0, v[200:201]
	s_mov_b32 m0, s50
	s_nop 0
	global_load_lds_dwordx4 v[222:223], off
	s_waitcnt vmcnt(8)
	s_waitcnt lgkmcnt(0)
	s_barrier
	s_waitcnt lgkmcnt(0)
	v_mfma_f32_16x16x32_bf16 v[126:129], v[130:133], v[162:165], v[126:129]
	v_mfma_f32_16x16x32_bf16 v[122:125], v[138:141], v[162:165], v[122:125]
	v_mfma_f32_16x16x32_bf16 v[110:113], v[130:133], v[170:173], v[110:113]
	v_mfma_f32_16x16x32_bf16 v[106:109], v[138:141], v[170:173], v[106:109]
	v_mfma_f32_16x16x32_bf16 v[94:97], v[130:133], v[178:181], v[94:97]
	v_mfma_f32_16x16x32_bf16 v[90:93], v[138:141], v[178:181], v[90:93]
	v_mfma_f32_16x16x32_bf16 v[78:81], v[130:133], v[186:189], v[78:81]
	v_mfma_f32_16x16x32_bf16 v[74:77], v[138:141], v[186:189], v[74:77]
	v_mfma_f32_16x16x32_bf16 v[126:129], v[134:137], v[166:169], v[126:129]
	v_mfma_f32_16x16x32_bf16 v[122:125], v[142:145], v[166:169], v[122:125]
	v_mfma_f32_16x16x32_bf16 v[110:113], v[134:137], v[174:177], v[110:113]
	v_mfma_f32_16x16x32_bf16 v[106:109], v[142:145], v[174:177], v[106:109]
	v_mfma_f32_16x16x32_bf16 v[94:97], v[134:137], v[182:185], v[94:97]
	v_mfma_f32_16x16x32_bf16 v[90:93], v[142:145], v[182:185], v[90:93]
	v_mfma_f32_16x16x32_bf16 v[78:81], v[134:137], v[190:193], v[78:81]
	v_mfma_f32_16x16x32_bf16 v[74:77], v[142:145], v[190:193], v[74:77]
	v_mfma_f32_16x16x32_bf16 v[118:121], v[146:149], v[162:165], v[118:121]
	v_mfma_f32_16x16x32_bf16 v[114:117], v[154:157], v[162:165], v[114:117]
	v_mfma_f32_16x16x32_bf16 v[102:105], v[146:149], v[170:173], v[102:105]
	v_mfma_f32_16x16x32_bf16 v[98:101], v[154:157], v[170:173], v[98:101]
	v_mfma_f32_16x16x32_bf16 v[86:89], v[146:149], v[178:181], v[86:89]
	v_mfma_f32_16x16x32_bf16 v[82:85], v[154:157], v[178:181], v[82:85]
	v_mfma_f32_16x16x32_bf16 v[70:73], v[146:149], v[186:189], v[70:73]
	v_mfma_f32_16x16x32_bf16 v[66:69], v[154:157], v[186:189], v[66:69]
	v_mfma_f32_16x16x32_bf16 v[118:121], v[150:153], v[166:169], v[118:121]
	v_mfma_f32_16x16x32_bf16 v[114:117], v[158:161], v[166:169], v[114:117]
	v_mfma_f32_16x16x32_bf16 v[102:105], v[150:153], v[174:177], v[102:105]
	v_mfma_f32_16x16x32_bf16 v[98:101], v[158:161], v[174:177], v[98:101]
	v_mfma_f32_16x16x32_bf16 v[86:89], v[150:153], v[182:185], v[86:89]
	v_mfma_f32_16x16x32_bf16 v[82:85], v[158:161], v[182:185], v[82:85]
	v_mfma_f32_16x16x32_bf16 v[70:73], v[150:153], v[190:193], v[70:73]
	v_mfma_f32_16x16x32_bf16 v[66:69], v[158:161], v[190:193], v[66:69]
	s_barrier
; #define PG8_STAGE(bufoff, gbase, voff) do { _Pragma("unroll") for (int _i = 0; _i < 2; ++_i) \
;         __builtin_amdgcn_global_load_lds((const unsigned*)((const char*)(gbase) + (voff)[_i]), (PG8_LAS unsigned*)(lds + (bufoff) + ldsw + _i * 8192), 16, 0, 0); } while (0)
; #define PG8_LDA(dst, b, h) do { _Pragma("unroll") for (int m = 0; m < 4; ++m) _Pragma("unroll") for (int k = 0; k < 2; ++k) dst[m][k] = *(const PG8_LAS bf16x8*)(lds + PG8_SA(b, h) + aoff + m * 2048 + k * 1024); } while (0)
; #define PG8_LDB(dst, b, h) do { _Pragma("unroll") for (int n = 0; n < 2; ++n) _Pragma("unroll") for (int k = 0; k < 2; ++k) dst[n][k] = *(const PG8_LAS bf16x8*)(lds + PG8_SB(b, h) + boff + n * 2048 + k * 1024); } while (0)
; #define PG8_MMA(ai, bj, At, Bt) do { __builtin_amdgcn_s_setprio(1); _Pragma("unroll") for (int m = 0; m < 4; ++m) _Pragma("unroll") for (int n = 0; n < 2; ++n) _Pragma("unroll") for (int k = 0; k < 2; ++k) \
;         acc[ai][bj][m][n] = __builtin_amdgcn_mfma_f32_16x16x32_bf16(Bt[n][k], At[m][k], acc[ai][bj][m][n], 0, 0, 0); __builtin_amdgcn_s_setprio(0); } while (0)
; #define PG8_WAIT_V(n) asm volatile("s_waitcnt vmcnt(" #n ")" ::: "memory")
; template <class Epi, class Sched, bool ALIGN_EPI = false, bool SP2 = false>
; __device__ __forceinline__ void gemm_phase(PG8_LAS unsigned char* lds, const Gemm g, const Sched& S, const Epi& E) {
;     ...
;             PG8_LDB(B0, 0, 0); PG8_LDB(B1, 0, 1); PG8_SCHED; PG8_LDA(At, 0, 0); PG8_STAGE(PG8_SA(1, 1), a1 + hstep, voffA);
;             PG8_WAIT_V(8); PG8_WAIT_L(0); PG8_BAR; PG8_MMA(0, 0, At, B0); PG8_MMA(0, 1, At, B1); PG8_BAR; PG8_SCHED;
;             PG8_LDA(At, 0, 1); PG8_STAGE(PG8_SB(0, 0), b2, voffB); PG8_STAGE(PG8_SB(0, 1), b2 + hstep, voffB); PG8_STAGE(PG8_SA(0, 0), a2, voffA);
;             PG8_WAIT_V(8); PG8_WAIT_L(0); PG8_BAR; PG8_MMA(1, 0, At, B0); PG8_MMA(1, 1, At, B1); PG8_BAR; PG8_SCHED;
;             PG8_LDB(B0, 1, 0); PG8_LDB(B1, 1, 1); PG8_SCHED; PG8_LDA(At, 1, 0); PG8_STAGE(PG8_SA(0, 1), a2 + hstep, voffA);
;             PG8_WAIT_V(8); PG8_WAIT_L(0); PG8_BAR; PG8_MMA(0, 0, At, B0); PG8_MMA(0, 1, At, B1); PG8_BAR; PG8_SCHED;
;             PG8_LDA(At, 1, 1); PG8_STAGE(PG8_SB(1, 0), b3, voffB); PG8_STAGE(PG8_SB(1, 1), b3 + hstep, voffB); PG8_STAGE(PG8_SA(1, 0), a3, voffA);
;             PG8_WAIT_V(8); PG8_WAIT_L(0); PG8_BAR; PG8_MMA(1, 0, At, B0); PG8_MMA(1, 1, At, B1); PG8_BAR; PG8_SCHED;
	s_add_i32 s40, s72, s44
	v_lshl_add_u64 v[210:211], v[210:211], 0, s[58:59]
	s_mov_b32 m0, s40
	ds_read_b128 v[162:165], v252 offset:49152
	ds_read_b128 v[166:169], v252 offset:50176
	ds_read_b128 v[170:173], v252 offset:51200
	ds_read_b128 v[174:177], v252 offset:52224
	ds_read_b128 v[178:181], v252 offset:53248
	ds_read_b128 v[182:185], v252 offset:54272
	ds_read_b128 v[186:189], v252 offset:55296
	ds_read_b128 v[190:193], v252 offset:56320
	global_load_lds_dwordx4 v[210:211], off
	v_lshl_add_u64 v[210:211], v[212:213], 0, s[58:59]
	s_add_i32 m0, s40, 0x2000
	s_add_i32 s40, s73, s44
	global_load_lds_dwordx4 v[210:211], off
	v_lshl_add_u64 v[210:211], v[214:215], 0, s[58:59]
	s_mov_b32 m0, s40
	s_nop 0
	global_load_lds_dwordx4 v[210:211], off
	v_lshl_add_u64 v[210:211], v[216:217], 0, s[58:59]
	s_add_i32 m0, s40, 0x2000
	s_nop 0
	global_load_lds_dwordx4 v[210:211], off
	v_lshl_add_u64 v[210:211], v[218:219], 0, s[58:59]
	s_mov_b32 m0, s55
	s_nop 0
	global_load_lds_dwordx4 v[210:211], off
	v_lshl_add_u64 v[210:211], v[220:221], 0, s[58:59]
	s_mov_b32 m0, s63
	s_nop 0
	global_load_lds_dwordx4 v[210:211], off
	s_waitcnt vmcnt(8)
	s_waitcnt lgkmcnt(0)
	s_barrier
	s_waitcnt lgkmcnt(0)
	v_mfma_f32_16x16x32_bf16 v[62:65], v[130:133], v[162:165], v[62:65]
	v_mfma_f32_16x16x32_bf16 v[58:61], v[138:141], v[162:165], v[58:61]
	v_mfma_f32_16x16x32_bf16 v[50:53], v[130:133], v[170:173], v[50:53]
	v_mfma_f32_16x16x32_bf16 v[42:45], v[138:141], v[170:173], v[42:45]
	v_mfma_f32_16x16x32_bf16 v[34:37], v[130:133], v[178:181], v[34:37]
	v_mfma_f32_16x16x32_bf16 v[26:29], v[138:141], v[178:181], v[26:29]
	v_mfma_f32_16x16x32_bf16 v[18:21], v[130:133], v[186:189], v[18:21]
	v_mfma_f32_16x16x32_bf16 v[14:17], v[138:141], v[186:189], v[14:17]
	v_mfma_f32_16x16x32_bf16 v[62:65], v[134:137], v[166:169], v[62:65]
	v_mfma_f32_16x16x32_bf16 v[58:61], v[142:145], v[166:169], v[58:61]
	v_mfma_f32_16x16x32_bf16 v[50:53], v[134:137], v[174:177], v[50:53]
	v_mfma_f32_16x16x32_bf16 v[42:45], v[142:145], v[174:177], v[42:45]
	v_mfma_f32_16x16x32_bf16 v[34:37], v[134:137], v[182:185], v[34:37]
	v_mfma_f32_16x16x32_bf16 v[26:29], v[142:145], v[182:185], v[26:29]
	v_mfma_f32_16x16x32_bf16 v[18:21], v[134:137], v[190:193], v[18:21]
	v_mfma_f32_16x16x32_bf16 v[14:17], v[142:145], v[190:193], v[14:17]
	v_mfma_f32_16x16x32_bf16 v[54:57], v[146:149], v[162:165], v[54:57]
	v_mfma_f32_16x16x32_bf16 v[46:49], v[154:157], v[162:165], v[46:49]
	v_mfma_f32_16x16x32_bf16 v[38:41], v[146:149], v[170:173], v[38:41]
	v_mfma_f32_16x16x32_bf16 v[30:33], v[154:157], v[170:173], v[30:33]
	v_mfma_f32_16x16x32_bf16 v[22:25], v[146:149], v[178:181], v[22:25]
	v_mfma_f32_16x16x32_bf16 v[10:13], v[154:157], v[178:181], v[10:13]
	v_mfma_f32_16x16x32_bf16 v[6:9], v[146:149], v[186:189], v[6:9]
	v_mfma_f32_16x16x32_bf16 v[2:5], v[154:157], v[186:189], v[2:5]
	v_mfma_f32_16x16x32_bf16 v[54:57], v[150:153], v[166:169], v[54:57]
	v_mfma_f32_16x16x32_bf16 v[46:49], v[158:161], v[166:169], v[46:49]
	v_mfma_f32_16x16x32_bf16 v[38:41], v[150:153], v[174:177], v[38:41]
	v_mfma_f32_16x16x32_bf16 v[30:33], v[158:161], v[174:177], v[30:33]
	v_mfma_f32_16x16x32_bf16 v[22:25], v[150:153], v[182:185], v[22:25]
	v_mfma_f32_16x16x32_bf16 v[10:13], v[158:161], v[182:185], v[10:13]
	v_mfma_f32_16x16x32_bf16 v[6:9], v[150:153], v[190:193], v[6:9]
	v_mfma_f32_16x16x32_bf16 v[2:5], v[158:161], v[190:193], v[2:5]
	s_barrier
	s_add_u32 s38, s38, 0x100
	s_addc_u32 s39, s39, 0
	s_add_u32 s86, s86, 0x100
	s_addc_u32 s87, s87, 0
	s_cmp_ge_u32 vcc_lo, s93
	s_mov_b32 s40, vcc_lo
	s_cbranch_scc1 .Lpeel_done_807
.LBB0_807:
	s_add_i32 vcc_lo, s40, 2
	s_add_u32 s72, s38, 0x80
	s_addc_u32 s41, s39, 0
	s_add_i32 vcc_hi, 0, 0x10000
	s_cmp_eq_u32 s65, s40
	s_cselect_b32 s41, s9, s41
	s_cselect_b32 s40, s8, s72
	v_add_u32_e32 v0, vcc_hi, v250
	s_cselect_b32 s73, s11, s87
	s_cselect_b32 s72, s10, s86
	s_add_i32 s78, 0, 0x14000
	ds_read_b128 v[130:133], v0
	ds_read_b128 v[134:137], v0 offset:1024
	ds_read_b128 v[138:141], v0 offset:2048
	ds_read_b128 v[142:145], v0 offset:3072
	v_add_u32_e32 v0, s78, v250
	ds_read_b128 v[146:149], v0
	ds_read_b128 v[150:153], v0 offset:1024
	ds_read_b128 v[154:157], v0 offset:2048
	ds_read_b128 v[158:161], v0 offset:3072
	v_lshl_add_u64 v[210:211], s[38:39], 0, v[206:207]
	s_add_i32 m0, s47, 0xc000
	ds_read_b128 v[162:165], v252
	ds_read_b128 v[166:169], v252 offset:1024
	ds_read_b128 v[170:173], v252 offset:2048
	ds_read_b128 v[174:177], v252 offset:3072
	ds_read_b128 v[178:181], v252 offset:4096
	ds_read_b128 v[182:185], v252 offset:5120
	ds_read_b128 v[186:189], v252 offset:6144
	ds_read_b128 v[190:193], v252 offset:7168
	global_load_lds_dwordx4 v[210:211], off
	v_lshl_add_u64 v[210:211], s[38:39], 0, v[208:209]
	s_add_i32 m0, s47, 0xe000
	s_nop 0
	global_load_lds_dwordx4 v[210:211], off
	s_waitcnt vmcnt(8)
	s_waitcnt lgkmcnt(0)
	s_barrier
; #define PG8_STAGE(bufoff, gbase, voff) do { _Pragma("unroll") for (int _i = 0; _i < 2; ++_i) \
;         __builtin_amdgcn_global_load_lds((const unsigned*)((const char*)(gbase) + (voff)[_i]), (PG8_LAS unsigned*)(lds + (bufoff) + ldsw + _i * 8192), 16, 0, 0); } while (0)
; #define PG8_LDA(dst, b, h) do { _Pragma("unroll") for (int m = 0; m < 4; ++m) _Pragma("unroll") for (int k = 0; k < 2; ++k) dst[m][k] = *(const PG8_LAS bf16x8*)(lds + PG8_SA(b, h) + aoff + m * 2048 + k * 1024); } while (0)
; #define PG8_LDB(dst, b, h) do { _Pragma("unroll") for (int n = 0; n < 2; ++n) _Pragma("unroll") for (int k = 0; k < 2; ++k) dst[n][k] = *(const PG8_LAS bf16x8*)(lds + PG8_SB(b, h) + boff + n * 2048 + k * 1024); } while (0)
; #define PG8_MMA(ai, bj, At, Bt) do { __builtin_amdgcn_s_setprio(1); _Pragma("unroll") for (int m = 0; m < 4; ++m) _Pragma("unroll") for (int n = 0; n < 2; ++n) _Pragma("unroll") for (int k = 0; k < 2; ++k) \
;         acc[ai][bj][m][n] = __builtin_amdgcn_mfma_f32_16x16x32_bf16(Bt[n][k], At[m][k], acc[ai][bj][m][n], 0, 0, 0); __builtin_amdgcn_s_setprio(0); } while (0)
; #define PG8_WAIT_V(n) asm volatile("s_waitcnt vmcnt(" #n ")" ::: "memory")
; #define PG8_WAIT_L(n) asm volatile("s_waitcnt lgkmcnt(" #n ")" ::: "memory")
; #define PG8_BAR __builtin_amdgcn_s_barrier()
; #define PG8_SCHED __builtin_amdgcn_sched_barrier(0)
; template <class Epi, class Sched, bool ALIGN_EPI = false, bool SP2 = false>
; __device__ __forceinline__ void gemm_phase(PG8_LAS unsigned char* lds, const Gemm g, const Sched& S, const Epi& E) {
;     ...
;             PG8_LDB(B0, 0, 0); PG8_LDB(B1, 0, 1); PG8_SCHED; PG8_LDA(At, 0, 0); PG8_STAGE(PG8_SA(1, 1), a1 + hstep, voffA);
;             PG8_WAIT_V(8); PG8_WAIT_L(0); PG8_BAR; PG8_MMA(0, 0, At, B0); PG8_MMA(0, 1, At, B1); PG8_BAR; PG8_SCHED;
;             PG8_LDA(At, 0, 1); PG8_STAGE(PG8_SB(0, 0), b2, voffB); PG8_STAGE(PG8_SB(0, 1), b2 + hstep, voffB); PG8_STAGE(PG8_SA(0, 0), a2, voffA);
;             PG8_WAIT_V(8); PG8_WAIT_L(0); PG8_BAR; PG8_MMA(1, 0, At, B0); PG8_MMA(1, 1, At, B1); PG8_BAR; PG8_SCHED;
;             PG8_LDB(B0, 1, 0); PG8_LDB(B1, 1, 1); PG8_SCHED; PG8_LDA(At, 1, 0); PG8_STAGE(PG8_SA(0, 1), a2 + hstep, voffA);
;             PG8_WAIT_V(8); PG8_WAIT_L(0); PG8_BAR; PG8_MMA(0, 0, At, B0); PG8_MMA(0, 1, At, B1); PG8_BAR; PG8_SCHED;
	s_waitcnt lgkmcnt(0)
	v_mfma_f32_16x16x32_bf16 v[126:129], v[130:133], v[162:165], v[126:129]
	v_mfma_f32_16x16x32_bf16 v[122:125], v[138:141], v[162:165], v[122:125]
	v_mfma_f32_16x16x32_bf16 v[110:113], v[130:133], v[170:173], v[110:113]
	v_mfma_f32_16x16x32_bf16 v[106:109], v[138:141], v[170:173], v[106:109]
	v_mfma_f32_16x16x32_bf16 v[94:97], v[130:133], v[178:181], v[94:97]
	v_mfma_f32_16x16x32_bf16 v[90:93], v[138:141], v[178:181], v[90:93]
	v_mfma_f32_16x16x32_bf16 v[78:81], v[130:133], v[186:189], v[78:81]
	v_mfma_f32_16x16x32_bf16 v[74:77], v[138:141], v[186:189], v[74:77]
	v_mfma_f32_16x16x32_bf16 v[126:129], v[134:137], v[166:169], v[126:129]
	v_mfma_f32_16x16x32_bf16 v[122:125], v[142:145], v[166:169], v[122:125]
	v_mfma_f32_16x16x32_bf16 v[110:113], v[134:137], v[174:177], v[110:113]
	v_mfma_f32_16x16x32_bf16 v[106:109], v[142:145], v[174:177], v[106:109]
	v_mfma_f32_16x16x32_bf16 v[94:97], v[134:137], v[182:185], v[94:97]
	v_mfma_f32_16x16x32_bf16 v[90:93], v[142:145], v[182:185], v[90:93]
	v_mfma_f32_16x16x32_bf16 v[78:81], v[134:137], v[190:193], v[78:81]
	v_mfma_f32_16x16x32_bf16 v[74:77], v[142:145], v[190:193], v[74:77]
	v_mfma_f32_16x16x32_bf16 v[118:121], v[146:149], v[162:165], v[118:121]
	v_mfma_f32_16x16x32_bf16 v[114:117], v[154:157], v[162:165], v[114:117]
	v_mfma_f32_16x16x32_bf16 v[102:105], v[146:149], v[170:173], v[102:105]
	v_mfma_f32_16x16x32_bf16 v[98:101], v[154:157], v[170:173], v[98:101]
	v_mfma_f32_16x16x32_bf16 v[86:89], v[146:149], v[178:181], v[86:89]
	v_mfma_f32_16x16x32_bf16 v[82:85], v[154:157], v[178:181], v[82:85]
	v_mfma_f32_16x16x32_bf16 v[70:73], v[146:149], v[186:189], v[70:73]
	v_mfma_f32_16x16x32_bf16 v[66:69], v[154:157], v[186:189], v[66:69]
	v_mfma_f32_16x16x32_bf16 v[118:121], v[150:153], v[166:169], v[118:121]
	v_mfma_f32_16x16x32_bf16 v[114:117], v[158:161], v[166:169], v[114:117]
	v_mfma_f32_16x16x32_bf16 v[102:105], v[150:153], v[174:177], v[102:105]
	v_mfma_f32_16x16x32_bf16 v[98:101], v[158:161], v[174:177], v[98:101]
	v_mfma_f32_16x16x32_bf16 v[86:89], v[150:153], v[182:185], v[86:89]
	v_mfma_f32_16x16x32_bf16 v[82:85], v[158:161], v[182:185], v[82:85]
	v_mfma_f32_16x16x32_bf16 v[70:73], v[150:153], v[190:193], v[70:73]
	v_mfma_f32_16x16x32_bf16 v[66:69], v[158:161], v[190:193], v[66:69]
	s_barrier
	s_add_i32 s79, vcc_hi, s44
	v_lshl_add_u64 v[210:211], s[72:73], 0, v[198:199]
	s_mov_b32 m0, s79
	ds_read_b128 v[162:165], v252 offset:16384
	ds_read_b128 v[166:169], v252 offset:17408
	ds_read_b128 v[170:173], v252 offset:18432
	ds_read_b128 v[174:177], v252 offset:19456
	ds_read_b128 v[178:181], v252 offset:20480
	ds_read_b128 v[182:185], v252 offset:21504
	ds_read_b128 v[186:189], v252 offset:22528
	ds_read_b128 v[190:193], v252 offset:23552
	global_load_lds_dwordx4 v[210:211], off
	s_add_i32 m0, s79, 0x2000
	v_lshl_add_u64 v[212:213], s[72:73], 0, v[200:201]
	s_add_u32 s72, s72, s30
	s_addc_u32 s73, s73, 0
	s_add_i32 s78, s78, s44
	global_load_lds_dwordx4 v[212:213], off
	v_lshl_add_u64 v[214:215], s[72:73], 0, v[198:199]
	s_mov_b32 m0, s78
	v_lshl_add_u64 v[216:217], s[72:73], 0, v[200:201]
	global_load_lds_dwordx4 v[214:215], off
	s_add_i32 m0, s78, 0x2000
	v_lshl_add_u64 v[218:219], s[40:41], 0, v[198:199]
	global_load_lds_dwordx4 v[216:217], off
	s_mov_b32 m0, s47
	v_lshl_add_u64 v[220:221], s[40:41], 0, v[200:201]
	global_load_lds_dwordx4 v[218:219], off
	s_mov_b32 m0, s48
	s_nop 0
	global_load_lds_dwordx4 v[220:221], off
	s_waitcnt vmcnt(8)
	s_waitcnt lgkmcnt(0)
	s_barrier
	s_waitcnt lgkmcnt(0)
	v_mfma_f32_16x16x32_bf16 v[62:65], v[130:133], v[162:165], v[62:65]
	v_mfma_f32_16x16x32_bf16 v[58:61], v[138:141], v[162:165], v[58:61]
	v_mfma_f32_16x16x32_bf16 v[50:53], v[130:133], v[170:173], v[50:53]
	v_mfma_f32_16x16x32_bf16 v[42:45], v[138:141], v[170:173], v[42:45]
	v_mfma_f32_16x16x32_bf16 v[34:37], v[130:133], v[178:181], v[34:37]
	v_mfma_f32_16x16x32_bf16 v[26:29], v[138:141], v[178:181], v[26:29]
	v_mfma_f32_16x16x32_bf16 v[18:21], v[130:133], v[186:189], v[18:21]
	v_mfma_f32_16x16x32_bf16 v[14:17], v[138:141], v[186:189], v[14:17]
	v_mfma_f32_16x16x32_bf16 v[62:65], v[134:137], v[166:169], v[62:65]
	v_mfma_f32_16x16x32_bf16 v[58:61], v[142:145], v[166:169], v[58:61]
	v_mfma_f32_16x16x32_bf16 v[50:53], v[134:137], v[174:177], v[50:53]
	v_mfma_f32_16x16x32_bf16 v[42:45], v[142:145], v[174:177], v[42:45]
	v_mfma_f32_16x16x32_bf16 v[34:37], v[134:137], v[182:185], v[34:37]
	v_mfma_f32_16x16x32_bf16 v[26:29], v[142:145], v[182:185], v[26:29]
	v_mfma_f32_16x16x32_bf16 v[18:21], v[134:137], v[190:193], v[18:21]
	v_mfma_f32_16x16x32_bf16 v[14:17], v[142:145], v[190:193], v[14:17]
	v_mfma_f32_16x16x32_bf16 v[54:57], v[146:149], v[162:165], v[54:57]
	v_mfma_f32_16x16x32_bf16 v[46:49], v[154:157], v[162:165], v[46:49]
	v_mfma_f32_16x16x32_bf16 v[38:41], v[146:149], v[170:173], v[38:41]
	v_mfma_f32_16x16x32_bf16 v[30:33], v[154:157], v[170:173], v[30:33]
	v_mfma_f32_16x16x32_bf16 v[22:25], v[146:149], v[178:181], v[22:25]
	v_mfma_f32_16x16x32_bf16 v[10:13], v[154:157], v[178:181], v[10:13]
	v_mfma_f32_16x16x32_bf16 v[6:9], v[146:149], v[186:189], v[6:9]
	v_mfma_f32_16x16x32_bf16 v[2:5], v[154:157], v[186:189], v[2:5]
	v_mfma_f32_16x16x32_bf16 v[54:57], v[150:153], v[166:169], v[54:57]
	v_mfma_f32_16x16x32_bf16 v[46:49], v[158:161], v[166:169], v[46:49]
	v_mfma_f32_16x16x32_bf16 v[38:41], v[150:153], v[174:177], v[38:41]
	v_mfma_f32_16x16x32_bf16 v[30:33], v[158:161], v[174:177], v[30:33]
	v_mfma_f32_16x16x32_bf16 v[22:25], v[150:153], v[182:185], v[22:25]
	v_mfma_f32_16x16x32_bf16 v[10:13], v[158:161], v[182:185], v[10:13]
	v_mfma_f32_16x16x32_bf16 v[6:9], v[150:153], v[190:193], v[6:9]
	v_mfma_f32_16x16x32_bf16 v[2:5], v[158:161], v[190:193], v[2:5]
	s_barrier
; #define PG8_STAGE(bufoff, gbase, voff) do { _Pragma("unroll") for (int _i = 0; _i < 2; ++_i) \
;         __builtin_amdgcn_global_load_lds((const unsigned*)((const char*)(gbase) + (voff)[_i]), (PG8_LAS unsigned*)(lds + (bufoff) + ldsw + _i * 8192), 16, 0, 0); } while (0)
; #define PG8_LDA(dst, b, h) do { _Pragma("unroll") for (int m = 0; m < 4; ++m) _Pragma("unroll") for (int k = 0; k < 2; ++k) dst[m][k] = *(const PG8_LAS bf16x8*)(lds + PG8_SA(b, h) + aoff + m * 2048 + k * 1024); } while (0)
; #define PG8_LDB(dst, b, h) do { _Pragma("unroll") for (int n = 0; n < 2; ++n) _Pragma("unroll") for (int k = 0; k < 2; ++k) dst[n][k] = *(const PG8_LAS bf16x8*)(lds + PG8_SB(b, h) + boff + n * 2048 + k * 1024); } while (0)
; #define PG8_MMA(ai, bj, At, Bt) do { __builtin_amdgcn_s_setprio(1); _Pragma("unroll") for (int m = 0; m < 4; ++m) _Pragma("unroll") for (int n = 0; n < 2; ++n) _Pragma("unroll") for (int k = 0; k < 2; ++k) \
;         acc[ai][bj][m][n] = __builtin_amdgcn_mfma_f32_16x16x32_bf16(Bt[n][k], At[m][k], acc[ai][bj][m][n], 0, 0, 0); __builtin_amdgcn_s_setprio(0); } while (0)
; #define PG8_WAIT_V(n) asm volatile("s_waitcnt vmcnt(" #n ")" ::: "memory")
; #define PG8_WAIT_L(n) asm volatile("s_waitcnt lgkmcnt(" #n ")" ::: "memory")
; #define PG8_BAR __builtin_amdgcn_s_barrier()
; #define PG8_SCHED __builtin_amdgcn_sched_barrier(0)
; template <class Epi, class Sched, bool ALIGN_EPI = false, bool SP2 = false>
; __device__ __forceinline__ void gemm_phase(PG8_LAS unsigned char* lds, const Gemm g, const Sched& S, const Epi& E) {
;     ...
;             PG8_LDB(B0, 1, 0); PG8_LDB(B1, 1, 1); PG8_SCHED; PG8_LDA(At, 1, 0); PG8_STAGE(PG8_SA(0, 1), a2 + hstep, voffA);
;             PG8_WAIT_V(8); PG8_WAIT_L(0); PG8_BAR; PG8_MMA(0, 0, At, B0); PG8_MMA(0, 1, At, B1); PG8_BAR; PG8_SCHED;
;             PG8_LDA(At, 1, 1); PG8_STAGE(PG8_SB(1, 0), b3, voffB); PG8_STAGE(PG8_SB(1, 1), b3 + hstep, voffB); PG8_STAGE(PG8_SA(1, 0), a3, voffA);
;             PG8_WAIT_V(8); PG8_WAIT_L(0); PG8_BAR; PG8_MMA(1, 0, At, B0); PG8_MMA(1, 1, At, B1); PG8_BAR; PG8_SCHED;
	s_add_i32 s72, 0, 0x18000
	v_add_u32_e32 v0, s72, v250
	s_add_i32 s73, 0, 0x1c000
	ds_read_b128 v[130:133], v0
	ds_read_b128 v[134:137], v0 offset:1024
	ds_read_b128 v[138:141], v0 offset:2048
	ds_read_b128 v[142:145], v0 offset:3072
	v_add_u32_e32 v0, s73, v250
	ds_read_b128 v[146:149], v0
	ds_read_b128 v[150:153], v0 offset:1024
	ds_read_b128 v[154:157], v0 offset:2048
	ds_read_b128 v[158:161], v0 offset:3072
	s_add_u32 s40, s40, s30
	s_addc_u32 s41, s41, 0
	s_mov_b32 m0, s49
	v_lshl_add_u64 v[222:223], s[40:41], 0, v[198:199]
	ds_read_b128 v[162:165], v252 offset:32768
	ds_read_b128 v[166:169], v252 offset:33792
	ds_read_b128 v[170:173], v252 offset:34816
	ds_read_b128 v[174:177], v252 offset:35840
	ds_read_b128 v[178:181], v252 offset:36864
	ds_read_b128 v[182:185], v252 offset:37888
	ds_read_b128 v[186:189], v252 offset:38912
	ds_read_b128 v[190:193], v252 offset:39936
	global_load_lds_dwordx4 v[222:223], off
	v_lshl_add_u64 v[222:223], s[40:41], 0, v[200:201]
	s_mov_b32 m0, s50
	s_nop 0
	global_load_lds_dwordx4 v[222:223], off
	s_waitcnt vmcnt(8)
	s_waitcnt lgkmcnt(0)
	s_barrier
	s_waitcnt lgkmcnt(0)
	v_mfma_f32_16x16x32_bf16 v[126:129], v[130:133], v[162:165], v[126:129]
	v_mfma_f32_16x16x32_bf16 v[122:125], v[138:141], v[162:165], v[122:125]
	v_mfma_f32_16x16x32_bf16 v[110:113], v[130:133], v[170:173], v[110:113]
	v_mfma_f32_16x16x32_bf16 v[106:109], v[138:141], v[170:173], v[106:109]
	v_mfma_f32_16x16x32_bf16 v[94:97], v[130:133], v[178:181], v[94:97]
	v_mfma_f32_16x16x32_bf16 v[90:93], v[138:141], v[178:181], v[90:93]
	v_mfma_f32_16x16x32_bf16 v[78:81], v[130:133], v[186:189], v[78:81]
	v_mfma_f32_16x16x32_bf16 v[74:77], v[138:141], v[186:189], v[74:77]
	v_mfma_f32_16x16x32_bf16 v[126:129], v[134:137], v[166:169], v[126:129]
	v_mfma_f32_16x16x32_bf16 v[122:125], v[142:145], v[166:169], v[122:125]
	v_mfma_f32_16x16x32_bf16 v[110:113], v[134:137], v[174:177], v[110:113]
	v_mfma_f32_16x16x32_bf16 v[106:109], v[142:145], v[174:177], v[106:109]
	v_mfma_f32_16x16x32_bf16 v[94:97], v[134:137], v[182:185], v[94:97]
	v_mfma_f32_16x16x32_bf16 v[90:93], v[142:145], v[182:185], v[90:93]
	v_mfma_f32_16x16x32_bf16 v[78:81], v[134:137], v[190:193], v[78:81]
	v_mfma_f32_16x16x32_bf16 v[74:77], v[142:145], v[190:193], v[74:77]
	v_mfma_f32_16x16x32_bf16 v[118:121], v[146:149], v[162:165], v[118:121]
	v_mfma_f32_16x16x32_bf16 v[114:117], v[154:157], v[162:165], v[114:117]
	v_mfma_f32_16x16x32_bf16 v[102:105], v[146:149], v[170:173], v[102:105]
	v_mfma_f32_16x16x32_bf16 v[98:101], v[154:157], v[170:173], v[98:101]
	v_mfma_f32_16x16x32_bf16 v[86:89], v[146:149], v[178:181], v[86:89]
	v_mfma_f32_16x16x32_bf16 v[82:85], v[154:157], v[178:181], v[82:85]
	v_mfma_f32_16x16x32_bf16 v[70:73], v[146:149], v[186:189], v[70:73]
	v_mfma_f32_16x16x32_bf16 v[66:69], v[154:157], v[186:189], v[66:69]
	v_mfma_f32_16x16x32_bf16 v[118:121], v[150:153], v[166:169], v[118:121]
	v_mfma_f32_16x16x32_bf16 v[114:117], v[158:161], v[166:169], v[114:117]
	v_mfma_f32_16x16x32_bf16 v[102:105], v[150:153], v[174:177], v[102:105]
	v_mfma_f32_16x16x32_bf16 v[98:101], v[158:161], v[174:177], v[98:101]
	v_mfma_f32_16x16x32_bf16 v[86:89], v[150:153], v[182:185], v[86:89]
	v_mfma_f32_16x16x32_bf16 v[82:85], v[158:161], v[182:185], v[82:85]
	v_mfma_f32_16x16x32_bf16 v[70:73], v[150:153], v[190:193], v[70:73]
	v_mfma_f32_16x16x32_bf16 v[66:69], v[158:161], v[190:193], v[66:69]
	s_barrier
	s_add_i32 s40, s72, s44
	v_lshl_add_u64 v[210:211], v[210:211], 0, s[58:59]
	s_mov_b32 m0, s40
	ds_read_b128 v[162:165], v252 offset:49152
	ds_read_b128 v[166:169], v252 offset:50176
	ds_read_b128 v[170:173], v252 offset:51200
	ds_read_b128 v[174:177], v252 offset:52224
	ds_read_b128 v[178:181], v252 offset:53248
	ds_read_b128 v[182:185], v252 offset:54272
	ds_read_b128 v[186:189], v252 offset:55296
	ds_read_b128 v[190:193], v252 offset:56320
	global_load_lds_dwordx4 v[210:211], off
	v_lshl_add_u64 v[210:211], v[212:213], 0, s[58:59]
	s_add_i32 m0, s40, 0x2000
	s_add_i32 s40, s73, s44
	global_load_lds_dwordx4 v[210:211], off
	v_lshl_add_u64 v[210:211], v[214:215], 0, s[58:59]
	s_mov_b32 m0, s40
	s_nop 0
	global_load_lds_dwordx4 v[210:211], off
	v_lshl_add_u64 v[210:211], v[216:217], 0, s[58:59]
	s_add_i32 m0, s40, 0x2000
	s_nop 0
	global_load_lds_dwordx4 v[210:211], off
	v_lshl_add_u64 v[210:211], v[218:219], 0, s[58:59]
	s_mov_b32 m0, s55
	s_nop 0
	global_load_lds_dwordx4 v[210:211], off
	v_lshl_add_u64 v[210:211], v[220:221], 0, s[58:59]
	s_mov_b32 m0, s63
	s_nop 0
	global_load_lds_dwordx4 v[210:211], off
	s_waitcnt vmcnt(8)
	s_waitcnt lgkmcnt(0)
	s_barrier
	s_waitcnt lgkmcnt(0)
	v_mfma_f32_16x16x32_bf16 v[62:65], v[130:133], v[162:165], v[62:65]
	v_mfma_f32_16x16x32_bf16 v[58:61], v[138:141], v[162:165], v[58:61]
	v_mfma_f32_16x16x32_bf16 v[50:53], v[130:133], v[170:173], v[50:53]
	v_mfma_f32_16x16x32_bf16 v[42:45], v[138:141], v[170:173], v[42:45]
	v_mfma_f32_16x16x32_bf16 v[34:37], v[130:133], v[178:181], v[34:37]
	v_mfma_f32_16x16x32_bf16 v[26:29], v[138:141], v[178:181], v[26:29]
	v_mfma_f32_16x16x32_bf16 v[18:21], v[130:133], v[186:189], v[18:21]
	v_mfma_f32_16x16x32_bf16 v[14:17], v[138:141], v[186:189], v[14:17]
	v_mfma_f32_16x16x32_bf16 v[62:65], v[134:137], v[166:169], v[62:65]
	v_mfma_f32_16x16x32_bf16 v[58:61], v[142:145], v[166:169], v[58:61]
	v_mfma_f32_16x16x32_bf16 v[50:53], v[134:137], v[174:177], v[50:53]
	v_mfma_f32_16x16x32_bf16 v[42:45], v[142:145], v[174:177], v[42:45]
	v_mfma_f32_16x16x32_bf16 v[34:37], v[134:137], v[182:185], v[34:37]
	v_mfma_f32_16x16x32_bf16 v[26:29], v[142:145], v[182:185], v[26:29]
	v_mfma_f32_16x16x32_bf16 v[18:21], v[134:137], v[190:193], v[18:21]
	v_mfma_f32_16x16x32_bf16 v[14:17], v[142:145], v[190:193], v[14:17]
	v_mfma_f32_16x16x32_bf16 v[54:57], v[146:149], v[162:165], v[54:57]
	v_mfma_f32_16x16x32_bf16 v[46:49], v[154:157], v[162:165], v[46:49]
	v_mfma_f32_16x16x32_bf16 v[38:41], v[146:149], v[170:173], v[38:41]
	v_mfma_f32_16x16x32_bf16 v[30:33], v[154:157], v[170:173], v[30:33]
	v_mfma_f32_16x16x32_bf16 v[22:25], v[146:149], v[178:181], v[22:25]
	v_mfma_f32_16x16x32_bf16 v[10:13], v[154:157], v[178:181], v[10:13]
	v_mfma_f32_16x16x32_bf16 v[6:9], v[146:149], v[186:189], v[6:9]
	v_mfma_f32_16x16x32_bf16 v[2:5], v[154:157], v[186:189], v[2:5]
	v_mfma_f32_16x16x32_bf16 v[54:57], v[150:153], v[166:169], v[54:57]
	v_mfma_f32_16x16x32_bf16 v[46:49], v[158:161], v[166:169], v[46:49]
	v_mfma_f32_16x16x32_bf16 v[38:41], v[150:153], v[174:177], v[38:41]
	v_mfma_f32_16x16x32_bf16 v[30:33], v[158:161], v[174:177], v[30:33]
	v_mfma_f32_16x16x32_bf16 v[22:25], v[150:153], v[182:185], v[22:25]
	v_mfma_f32_16x16x32_bf16 v[10:13], v[158:161], v[182:185], v[10:13]
	v_mfma_f32_16x16x32_bf16 v[6:9], v[150:153], v[190:193], v[6:9]
	v_mfma_f32_16x16x32_bf16 v[2:5], v[158:161], v[190:193], v[2:5]
	s_barrier
	s_add_u32 s38, s38, 0x100
	s_addc_u32 s39, s39, 0
	s_add_u32 s86, s86, 0x100
	s_addc_u32 s87, s87, 0
	s_cmp_ge_u32 vcc_lo, s93
	s_mov_b32 s40, vcc_lo
	s_cbranch_scc0 .LBB0_807

; #define PG8_STAGE(bufoff, gbase, voff) do { _Pragma("unroll") for (int _i = 0; _i < 2; ++_i) \
;         __builtin_amdgcn_global_load_lds((const unsigned*)((const char*)(gbase) + (voff)[_i]), (PG8_LAS unsigned*)(lds + (bufoff) + ldsw + _i * 8192), 16, 0, 0); } while (0)
; #define PG8_LDA(dst, b, h) do { _Pragma("unroll") for (int m = 0; m < 4; ++m) _Pragma("unroll") for (int k = 0; k < 2; ++k) dst[m][k] = *(const PG8_LAS bf16x8*)(lds + PG8_SA(b, h) + aoff + m * 2048 + k * 1024); } while (0)
; #define PG8_LDB(dst, b, h) do { _Pragma("unroll") for (int n = 0; n < 2; ++n) _Pragma("unroll") for (int k = 0; k < 2; ++k) dst[n][k] = *(const PG8_LAS bf16x8*)(lds + PG8_SB(b, h) + boff + n * 2048 + k * 1024); } while (0)
; #define PG8_MMA(ai, bj, At, Bt) do { __builtin_amdgcn_s_setprio(1); _Pragma("unroll") for (int m = 0; m < 4; ++m) _Pragma("unroll") for (int n = 0; n < 2; ++n) _Pragma("unroll") for (int k = 0; k < 2; ++k) \
;         acc[ai][bj][m][n] = __builtin_amdgcn_mfma_f32_16x16x32_bf16(Bt[n][k], At[m][k], acc[ai][bj][m][n], 0, 0, 0); __builtin_amdgcn_s_setprio(0); } while (0)
; #define PG8_WAIT_V(n) asm volatile("s_waitcnt vmcnt(" #n ")" ::: "memory")
; #define PG8_BAR __builtin_amdgcn_s_barrier()
; template <class Epi, class Sched, bool ALIGN_EPI = false, bool SP2 = false>
; __device__ __forceinline__ void gemm_phase(PG8_LAS unsigned char* lds, const Gemm g, const Sched& S, const Epi& E) {
;     ...
;         for (int t = 0; t < nt; t += 2) {
;             const bool last = (t == nt - 2);
;             const char* a1 = cA + (size_t)(t + 1) * kstep;
;             const char* a2 = last ? nA : cA + (size_t)(t + 2) * kstep; const char* b2 = last ? nB : cB + (size_t)(t + 2) * kstep;
;             const char* a3 = a2 + kstep; const char* b3 = b2 + kstep;
;             if (last && has_next) S.a_ready(nxt);
;             if constexpr (SP2) {
;             PG8_LDB(B0, 0, 0); PG8_LDB(B1, 0, 1); PG8_SCHED; PG8_LDA(At, 0, 0); PG8_STAGE(PG8_SA(1, 1), a1 + hstep, voffA);
;             PG8_WAIT_V(8); PG8_WAIT_L(0); PG8_BAR; PG8_MMA(0, 0, At, B0); PG8_MMA(0, 1, At, B1); PG8_BAR; PG8_SCHED;
;             PG8_LDA(At, 0, 1); PG8_STAGE(PG8_SB(0, 0), b2, voffB); PG8_STAGE(PG8_SB(0, 1), b2 + hstep, voffB); PG8_STAGE(PG8_SA(0, 0), a2, voffA);
;             PG8_WAIT_V(8); PG8_WAIT_L(0); PG8_BAR; PG8_MMA(1, 0, At, B0); PG8_MMA(1, 1, At, B1); PG8_BAR; PG8_SCHED;
.LBB0_832:
	s_add_u32 s30, s30, 0x80
	s_addc_u32 s31, s31, 0
	s_add_u32 s65, s38, 0x100
	s_addc_u32 s86, s39, 0
	s_mov_b32 s38, 0
	s_add_i32 s87, s38, 2
	s_add_u32 s72, s30, 0x80
	s_addc_u32 s39, s31, 0
	s_add_i32 s78, 0, 0x10000
	s_cmp_eq_u32 s54, s38
	s_cselect_b32 s39, s21, s39
	s_cselect_b32 s38, s20, s72
	v_add_u32_e32 v0, s78, v139
	s_cselect_b32 s73, s7, s86
	s_cselect_b32 s72, s6, s65
	s_add_i32 s79, 0, 0x14000
	ds_read_b128 v[142:145], v0
	ds_read_b128 v[146:149], v0 offset:1024
	ds_read_b128 v[150:153], v0 offset:2048
	ds_read_b128 v[154:157], v0 offset:3072
	v_add_u32_e32 v0, s79, v139
	ds_read_b128 v[158:161], v0
	ds_read_b128 v[162:165], v0 offset:1024
	ds_read_b128 v[166:169], v0 offset:2048
	ds_read_b128 v[170:173], v0 offset:3072
	v_lshl_add_u64 v[210:211], s[30:31], 0, v[134:135]
	s_add_i32 m0, s42, 0xc000
	ds_read_b128 v[174:177], v141
	ds_read_b128 v[178:181], v141 offset:1024
	ds_read_b128 v[182:185], v141 offset:2048
	ds_read_b128 v[186:189], v141 offset:3072
	ds_read_b128 v[190:193], v141 offset:4096
	ds_read_b128 v[198:201], v141 offset:5120
	ds_read_b128 v[202:205], v141 offset:6144
	ds_read_b128 v[206:209], v141 offset:7168
	global_load_lds_dwordx4 v[210:211], off
	v_lshl_add_u64 v[210:211], s[30:31], 0, v[136:137]
	s_add_i32 m0, s42, 0xe000
	s_nop 0
	global_load_lds_dwordx4 v[210:211], off
	s_waitcnt vmcnt(8)
	s_waitcnt lgkmcnt(0)
	s_barrier
	s_waitcnt lgkmcnt(0)
	v_mfma_f32_16x16x32_bf16 v[126:129], v[142:145], v[174:177], 0
	v_mfma_f32_16x16x32_bf16 v[122:125], v[150:153], v[174:177], 0
	v_mfma_f32_16x16x32_bf16 v[118:121], v[142:145], v[182:185], 0
	v_mfma_f32_16x16x32_bf16 v[114:117], v[150:153], v[182:185], 0
	v_mfma_f32_16x16x32_bf16 v[110:113], v[142:145], v[190:193], 0
	v_mfma_f32_16x16x32_bf16 v[102:105], v[150:153], v[190:193], 0
	v_mfma_f32_16x16x32_bf16 v[90:93], v[142:145], v[202:205], 0
	v_mfma_f32_16x16x32_bf16 v[82:85], v[150:153], v[202:205], 0
	v_mfma_f32_16x16x32_bf16 v[126:129], v[146:149], v[178:181], v[126:129]
	v_mfma_f32_16x16x32_bf16 v[122:125], v[154:157], v[178:181], v[122:125]
	v_mfma_f32_16x16x32_bf16 v[118:121], v[146:149], v[186:189], v[118:121]
	v_mfma_f32_16x16x32_bf16 v[114:117], v[154:157], v[186:189], v[114:117]
	v_mfma_f32_16x16x32_bf16 v[110:113], v[146:149], v[198:201], v[110:113]
	v_mfma_f32_16x16x32_bf16 v[102:105], v[154:157], v[198:201], v[102:105]
	v_mfma_f32_16x16x32_bf16 v[90:93], v[146:149], v[206:209], v[90:93]
	v_mfma_f32_16x16x32_bf16 v[82:85], v[154:157], v[206:209], v[82:85]
	v_mfma_f32_16x16x32_bf16 v[106:109], v[158:161], v[174:177], 0
	v_mfma_f32_16x16x32_bf16 v[98:101], v[166:169], v[174:177], 0
	v_mfma_f32_16x16x32_bf16 v[94:97], v[158:161], v[182:185], 0
	v_mfma_f32_16x16x32_bf16 v[86:89], v[166:169], v[182:185], 0
	v_mfma_f32_16x16x32_bf16 v[78:81], v[158:161], v[190:193], 0
	v_mfma_f32_16x16x32_bf16 v[74:77], v[166:169], v[190:193], 0
	v_mfma_f32_16x16x32_bf16 v[70:73], v[158:161], v[202:205], 0
	v_mfma_f32_16x16x32_bf16 v[66:69], v[166:169], v[202:205], 0
	v_mfma_f32_16x16x32_bf16 v[106:109], v[162:165], v[178:181], v[106:109]
	v_mfma_f32_16x16x32_bf16 v[98:101], v[170:173], v[178:181], v[98:101]
	v_mfma_f32_16x16x32_bf16 v[94:97], v[162:165], v[186:189], v[94:97]
	v_mfma_f32_16x16x32_bf16 v[86:89], v[170:173], v[186:189], v[86:89]
	v_mfma_f32_16x16x32_bf16 v[78:81], v[162:165], v[198:201], v[78:81]
	v_mfma_f32_16x16x32_bf16 v[74:77], v[170:173], v[198:201], v[74:77]
	v_mfma_f32_16x16x32_bf16 v[70:73], v[162:165], v[206:209], v[70:73]
	v_mfma_f32_16x16x32_bf16 v[66:69], v[170:173], v[206:209], v[66:69]
	s_barrier
	s_add_i32 s78, s78, s41
	v_lshl_add_u64 v[210:211], s[72:73], 0, v[132:133]
	s_mov_b32 m0, s78
	ds_read_b128 v[174:177], v141 offset:16384
	ds_read_b128 v[178:181], v141 offset:17408
	ds_read_b128 v[182:185], v141 offset:18432
	ds_read_b128 v[186:189], v141 offset:19456
	ds_read_b128 v[190:193], v141 offset:20480
	ds_read_b128 v[198:201], v141 offset:21504
	ds_read_b128 v[202:205], v141 offset:22528
	ds_read_b128 v[206:209], v141 offset:23552
	global_load_lds_dwordx4 v[210:211], off
	s_add_i32 m0, s78, 0x2000
	v_lshl_add_u64 v[212:213], s[72:73], 0, v[130:131]
	s_add_u32 s72, s72, s8
	s_addc_u32 s73, s73, 0
	s_add_i32 s78, s79, s41
	global_load_lds_dwordx4 v[212:213], off
	v_lshl_add_u64 v[214:215], s[72:73], 0, v[132:133]
	s_mov_b32 m0, s78
	v_lshl_add_u64 v[216:217], s[72:73], 0, v[130:131]
	global_load_lds_dwordx4 v[214:215], off
	s_add_i32 m0, s78, 0x2000
	v_lshl_add_u64 v[218:219], s[38:39], 0, v[132:133]
	global_load_lds_dwordx4 v[216:217], off
	s_mov_b32 m0, s42
	v_lshl_add_u64 v[220:221], s[38:39], 0, v[130:131]
	global_load_lds_dwordx4 v[218:219], off
	s_mov_b32 m0, s43
	s_nop 0
	global_load_lds_dwordx4 v[220:221], off
	s_waitcnt vmcnt(8)
	s_waitcnt lgkmcnt(0)
	s_barrier
; #define PG8_STAGE(bufoff, gbase, voff) do { _Pragma("unroll") for (int _i = 0; _i < 2; ++_i) \
;         __builtin_amdgcn_global_load_lds((const unsigned*)((const char*)(gbase) + (voff)[_i]), (PG8_LAS unsigned*)(lds + (bufoff) + ldsw + _i * 8192), 16, 0, 0); } while (0)
; #define PG8_LDA(dst, b, h) do { _Pragma("unroll") for (int m = 0; m < 4; ++m) _Pragma("unroll") for (int k = 0; k < 2; ++k) dst[m][k] = *(const PG8_LAS bf16x8*)(lds + PG8_SA(b, h) + aoff + m * 2048 + k * 1024); } while (0)
; #define PG8_LDB(dst, b, h) do { _Pragma("unroll") for (int n = 0; n < 2; ++n) _Pragma("unroll") for (int k = 0; k < 2; ++k) dst[n][k] = *(const PG8_LAS bf16x8*)(lds + PG8_SB(b, h) + boff + n * 2048 + k * 1024); } while (0)
; #define PG8_MMA(ai, bj, At, Bt) do { __builtin_amdgcn_s_setprio(1); _Pragma("unroll") for (int m = 0; m < 4; ++m) _Pragma("unroll") for (int n = 0; n < 2; ++n) _Pragma("unroll") for (int k = 0; k < 2; ++k) \
;         acc[ai][bj][m][n] = __builtin_amdgcn_mfma_f32_16x16x32_bf16(Bt[n][k], At[m][k], acc[ai][bj][m][n], 0, 0, 0); __builtin_amdgcn_s_setprio(0); } while (0)
; #define PG8_WAIT_V(n) asm volatile("s_waitcnt vmcnt(" #n ")" ::: "memory")
; #define PG8_WAIT_L(n) asm volatile("s_waitcnt lgkmcnt(" #n ")" ::: "memory")
; #define PG8_BAR __builtin_amdgcn_s_barrier()
; template <class Epi, class Sched, bool ALIGN_EPI = false, bool SP2 = false>
; __device__ __forceinline__ void gemm_phase(PG8_LAS unsigned char* lds, const Gemm g, const Sched& S, const Epi& E) {
;     ...
;             PG8_WAIT_V(8); PG8_WAIT_L(0); PG8_BAR; PG8_MMA(0, 0, At, B0); PG8_MMA(0, 1, At, B1); PG8_BAR; PG8_SCHED;
;             PG8_LDA(At, 0, 1); PG8_STAGE(PG8_SB(0, 0), b2, voffB); PG8_STAGE(PG8_SB(0, 1), b2 + hstep, voffB); PG8_STAGE(PG8_SA(0, 0), a2, voffA);
;             PG8_WAIT_V(8); PG8_WAIT_L(0); PG8_BAR; PG8_MMA(1, 0, At, B0); PG8_MMA(1, 1, At, B1); PG8_BAR; PG8_SCHED;
;             PG8_LDB(B0, 1, 0); PG8_LDB(B1, 1, 1); PG8_SCHED; PG8_LDA(At, 1, 0); PG8_STAGE(PG8_SA(0, 1), a2 + hstep, voffA);
;             PG8_WAIT_V(8); PG8_WAIT_L(0); PG8_BAR; PG8_MMA(0, 0, At, B0); PG8_MMA(0, 1, At, B1); PG8_BAR; PG8_SCHED;
;             PG8_LDA(At, 1, 1); PG8_STAGE(PG8_SB(1, 0), b3, voffB); PG8_STAGE(PG8_SB(1, 1), b3 + hstep, voffB); PG8_STAGE(PG8_SA(1, 0), a3, voffA);
;             PG8_WAIT_V(8); PG8_WAIT_L(0); PG8_BAR; PG8_MMA(1, 0, At, B0); PG8_MMA(1, 1, At, B1); PG8_BAR; PG8_SCHED;
	s_waitcnt lgkmcnt(0)
	v_mfma_f32_16x16x32_bf16 v[62:65], v[142:145], v[174:177], 0
	v_mfma_f32_16x16x32_bf16 v[58:61], v[150:153], v[174:177], 0
	v_mfma_f32_16x16x32_bf16 v[54:57], v[142:145], v[182:185], 0
	v_mfma_f32_16x16x32_bf16 v[50:53], v[150:153], v[182:185], 0
	v_mfma_f32_16x16x32_bf16 v[42:45], v[142:145], v[190:193], 0
	v_mfma_f32_16x16x32_bf16 v[34:37], v[150:153], v[190:193], 0
	v_mfma_f32_16x16x32_bf16 v[26:29], v[142:145], v[202:205], 0
	v_mfma_f32_16x16x32_bf16 v[18:21], v[150:153], v[202:205], 0
	v_mfma_f32_16x16x32_bf16 v[62:65], v[146:149], v[178:181], v[62:65]
	v_mfma_f32_16x16x32_bf16 v[58:61], v[154:157], v[178:181], v[58:61]
	v_mfma_f32_16x16x32_bf16 v[54:57], v[146:149], v[186:189], v[54:57]
	v_mfma_f32_16x16x32_bf16 v[50:53], v[154:157], v[186:189], v[50:53]
	v_mfma_f32_16x16x32_bf16 v[42:45], v[146:149], v[198:201], v[42:45]
	v_mfma_f32_16x16x32_bf16 v[34:37], v[154:157], v[198:201], v[34:37]
	v_mfma_f32_16x16x32_bf16 v[26:29], v[146:149], v[206:209], v[26:29]
	v_mfma_f32_16x16x32_bf16 v[18:21], v[154:157], v[206:209], v[18:21]
	v_mfma_f32_16x16x32_bf16 v[46:49], v[158:161], v[174:177], 0
	v_mfma_f32_16x16x32_bf16 v[38:41], v[166:169], v[174:177], 0
	v_mfma_f32_16x16x32_bf16 v[30:33], v[158:161], v[182:185], 0
	v_mfma_f32_16x16x32_bf16 v[22:25], v[166:169], v[182:185], 0
	v_mfma_f32_16x16x32_bf16 v[14:17], v[158:161], v[190:193], 0
	v_mfma_f32_16x16x32_bf16 v[10:13], v[166:169], v[190:193], 0
	v_mfma_f32_16x16x32_bf16 v[6:9], v[158:161], v[202:205], 0
	v_mfma_f32_16x16x32_bf16 v[2:5], v[166:169], v[202:205], 0
	v_mfma_f32_16x16x32_bf16 v[46:49], v[162:165], v[178:181], v[46:49]
	v_mfma_f32_16x16x32_bf16 v[38:41], v[170:173], v[178:181], v[38:41]
	v_mfma_f32_16x16x32_bf16 v[30:33], v[162:165], v[186:189], v[30:33]
	v_mfma_f32_16x16x32_bf16 v[22:25], v[170:173], v[186:189], v[22:25]
	v_mfma_f32_16x16x32_bf16 v[14:17], v[162:165], v[198:201], v[14:17]
	v_mfma_f32_16x16x32_bf16 v[10:13], v[170:173], v[198:201], v[10:13]
	v_mfma_f32_16x16x32_bf16 v[6:9], v[162:165], v[206:209], v[6:9]
	v_mfma_f32_16x16x32_bf16 v[2:5], v[170:173], v[206:209], v[2:5]
	s_barrier
	s_add_i32 s72, 0, 0x18000
	v_add_u32_e32 v0, s72, v139
	s_add_i32 s73, 0, 0x1c000
	ds_read_b128 v[142:145], v0
	ds_read_b128 v[146:149], v0 offset:1024
	ds_read_b128 v[150:153], v0 offset:2048
	ds_read_b128 v[154:157], v0 offset:3072
	v_add_u32_e32 v0, s73, v139
	ds_read_b128 v[158:161], v0
	ds_read_b128 v[162:165], v0 offset:1024
	ds_read_b128 v[166:169], v0 offset:2048
	ds_read_b128 v[170:173], v0 offset:3072
	s_add_u32 s38, s38, s8
	s_addc_u32 s39, s39, 0
	s_mov_b32 m0, s44
	v_lshl_add_u64 v[222:223], s[38:39], 0, v[132:133]
	ds_read_b128 v[174:177], v141 offset:32768
	ds_read_b128 v[178:181], v141 offset:33792
	ds_read_b128 v[182:185], v141 offset:34816
	ds_read_b128 v[186:189], v141 offset:35840
	ds_read_b128 v[190:193], v141 offset:36864
	ds_read_b128 v[198:201], v141 offset:37888
	ds_read_b128 v[202:205], v141 offset:38912
	ds_read_b128 v[206:209], v141 offset:39936
	global_load_lds_dwordx4 v[222:223], off
	v_lshl_add_u64 v[222:223], s[38:39], 0, v[130:131]
	s_mov_b32 m0, s45
	s_nop 0
	global_load_lds_dwordx4 v[222:223], off
	s_waitcnt vmcnt(8)
	s_waitcnt lgkmcnt(0)
	s_barrier
	s_waitcnt lgkmcnt(0)
	v_mfma_f32_16x16x32_bf16 v[126:129], v[142:145], v[174:177], v[126:129]
	v_mfma_f32_16x16x32_bf16 v[122:125], v[150:153], v[174:177], v[122:125]
	v_mfma_f32_16x16x32_bf16 v[118:121], v[142:145], v[182:185], v[118:121]
	v_mfma_f32_16x16x32_bf16 v[114:117], v[150:153], v[182:185], v[114:117]
	v_mfma_f32_16x16x32_bf16 v[110:113], v[142:145], v[190:193], v[110:113]
	v_mfma_f32_16x16x32_bf16 v[102:105], v[150:153], v[190:193], v[102:105]
	v_mfma_f32_16x16x32_bf16 v[90:93], v[142:145], v[202:205], v[90:93]
	v_mfma_f32_16x16x32_bf16 v[82:85], v[150:153], v[202:205], v[82:85]
	v_mfma_f32_16x16x32_bf16 v[126:129], v[146:149], v[178:181], v[126:129]
	v_mfma_f32_16x16x32_bf16 v[122:125], v[154:157], v[178:181], v[122:125]
	v_mfma_f32_16x16x32_bf16 v[118:121], v[146:149], v[186:189], v[118:121]
	v_mfma_f32_16x16x32_bf16 v[114:117], v[154:157], v[186:189], v[114:117]
	v_mfma_f32_16x16x32_bf16 v[110:113], v[146:149], v[198:201], v[110:113]
	v_mfma_f32_16x16x32_bf16 v[102:105], v[154:157], v[198:201], v[102:105]
	v_mfma_f32_16x16x32_bf16 v[90:93], v[146:149], v[206:209], v[90:93]
	v_mfma_f32_16x16x32_bf16 v[82:85], v[154:157], v[206:209], v[82:85]
	v_mfma_f32_16x16x32_bf16 v[106:109], v[158:161], v[174:177], v[106:109]
	v_mfma_f32_16x16x32_bf16 v[98:101], v[166:169], v[174:177], v[98:101]
	v_mfma_f32_16x16x32_bf16 v[94:97], v[158:161], v[182:185], v[94:97]
	v_mfma_f32_16x16x32_bf16 v[86:89], v[166:169], v[182:185], v[86:89]
	v_mfma_f32_16x16x32_bf16 v[78:81], v[158:161], v[190:193], v[78:81]
	v_mfma_f32_16x16x32_bf16 v[74:77], v[166:169], v[190:193], v[74:77]
	v_mfma_f32_16x16x32_bf16 v[70:73], v[158:161], v[202:205], v[70:73]
	v_mfma_f32_16x16x32_bf16 v[66:69], v[166:169], v[202:205], v[66:69]
	v_mfma_f32_16x16x32_bf16 v[106:109], v[162:165], v[178:181], v[106:109]
	v_mfma_f32_16x16x32_bf16 v[98:101], v[170:173], v[178:181], v[98:101]
	v_mfma_f32_16x16x32_bf16 v[94:97], v[162:165], v[186:189], v[94:97]
	v_mfma_f32_16x16x32_bf16 v[86:89], v[170:173], v[186:189], v[86:89]
	v_mfma_f32_16x16x32_bf16 v[78:81], v[162:165], v[198:201], v[78:81]
	v_mfma_f32_16x16x32_bf16 v[74:77], v[170:173], v[198:201], v[74:77]
	v_mfma_f32_16x16x32_bf16 v[70:73], v[162:165], v[206:209], v[70:73]
	v_mfma_f32_16x16x32_bf16 v[66:69], v[170:173], v[206:209], v[66:69]
	s_barrier
; #define PG8_STAGE(bufoff, gbase, voff) do { _Pragma("unroll") for (int _i = 0; _i < 2; ++_i) \
;         __builtin_amdgcn_global_load_lds((const unsigned*)((const char*)(gbase) + (voff)[_i]), (PG8_LAS unsigned*)(lds + (bufoff) + ldsw + _i * 8192), 16, 0, 0); } while (0)
; #define PG8_LDA(dst, b, h) do { _Pragma("unroll") for (int m = 0; m < 4; ++m) _Pragma("unroll") for (int k = 0; k < 2; ++k) dst[m][k] = *(const PG8_LAS bf16x8*)(lds + PG8_SA(b, h) + aoff + m * 2048 + k * 1024); } while (0)
; #define PG8_LDB(dst, b, h) do { _Pragma("unroll") for (int n = 0; n < 2; ++n) _Pragma("unroll") for (int k = 0; k < 2; ++k) dst[n][k] = *(const PG8_LAS bf16x8*)(lds + PG8_SB(b, h) + boff + n * 2048 + k * 1024); } while (0)
; template <class Epi, class Sched, bool ALIGN_EPI = false, bool SP2 = false>
; __device__ __forceinline__ void gemm_phase(PG8_LAS unsigned char* lds, const Gemm g, const Sched& S, const Epi& E) {
;     ...
;         for (int t = 0; t < nt; t += 2) {
;             const bool last = (t == nt - 2);
;             const char* a1 = cA + (size_t)(t + 1) * kstep;
;             const char* a2 = last ? nA : cA + (size_t)(t + 2) * kstep; const char* b2 = last ? nB : cB + (size_t)(t + 2) * kstep;
;             const char* a3 = a2 + kstep; const char* b3 = b2 + kstep;
;             if (last && has_next) S.a_ready(nxt);
;             if constexpr (SP2) {
;             PG8_LDB(B0, 0, 0); PG8_LDB(B1, 0, 1); PG8_SCHED; PG8_LDA(At, 0, 0); PG8_STAGE(PG8_SA(1, 1), a1 + hstep, voffA);
;             PG8_WAIT_V(8); PG8_WAIT_L(0); PG8_BAR; PG8_MMA(0, 0, At, B0); PG8_MMA(0, 1, At, B1); PG8_BAR; PG8_SCHED;
;             PG8_LDA(At, 0, 1); PG8_STAGE(PG8_SB(0, 0), b2, voffB); PG8_STAGE(PG8_SB(0, 1), b2 + hstep, voffB); PG8_STAGE(PG8_SA(0, 0), a2, voffA);
;             PG8_WAIT_V(8); PG8_WAIT_L(0); PG8_BAR; PG8_MMA(1, 0, At, B0); PG8_MMA(1, 1, At, B1); PG8_BAR; PG8_SCHED;
;             PG8_LDB(B0, 1, 0); PG8_LDB(B1, 1, 1); PG8_SCHED; PG8_LDA(At, 1, 0); PG8_STAGE(PG8_SA(0, 1), a2 + hstep, voffA);
;             PG8_WAIT_V(8); PG8_WAIT_L(0); PG8_BAR; PG8_MMA(0, 0, At, B0); PG8_MMA(0, 1, At, B1); PG8_BAR; PG8_SCHED;
;             PG8_LDA(At, 1, 1); PG8_STAGE(PG8_SB(1, 0), b3, voffB); PG8_STAGE(PG8_SB(1, 1), b3 + hstep, voffB); PG8_STAGE(PG8_SA(1, 0), a3, voffA);
;             PG8_WAIT_V(8); PG8_WAIT_L(0); PG8_BAR; PG8_MMA(1, 0, At, B0); PG8_MMA(1, 1, At, B1); PG8_BAR; PG8_SCHED;
	s_add_i32 s38, s72, s41
	v_lshl_add_u64 v[210:211], v[210:211], 0, s[58:59]
	s_mov_b32 m0, s38
	ds_read_b128 v[174:177], v141 offset:49152
	ds_read_b128 v[178:181], v141 offset:50176
	ds_read_b128 v[182:185], v141 offset:51200
	ds_read_b128 v[186:189], v141 offset:52224
	ds_read_b128 v[190:193], v141 offset:53248
	ds_read_b128 v[198:201], v141 offset:54272
	ds_read_b128 v[202:205], v141 offset:55296
	ds_read_b128 v[206:209], v141 offset:56320
	global_load_lds_dwordx4 v[210:211], off
	v_lshl_add_u64 v[210:211], v[212:213], 0, s[58:59]
	s_add_i32 m0, s38, 0x2000
	s_add_i32 s38, s73, s41
	global_load_lds_dwordx4 v[210:211], off
	v_lshl_add_u64 v[210:211], v[214:215], 0, s[58:59]
	s_mov_b32 m0, s38
	s_nop 0
	global_load_lds_dwordx4 v[210:211], off
	v_lshl_add_u64 v[210:211], v[216:217], 0, s[58:59]
	s_add_i32 m0, s38, 0x2000
	s_nop 0
	global_load_lds_dwordx4 v[210:211], off
	v_lshl_add_u64 v[210:211], v[218:219], 0, s[58:59]
	s_mov_b32 m0, s50
	s_nop 0
	global_load_lds_dwordx4 v[210:211], off
	v_lshl_add_u64 v[210:211], v[220:221], 0, s[58:59]
	s_mov_b32 m0, s51
	s_nop 0
	global_load_lds_dwordx4 v[210:211], off
	s_waitcnt vmcnt(8)
	s_waitcnt lgkmcnt(0)
	s_barrier
	s_waitcnt lgkmcnt(0)
	v_mfma_f32_16x16x32_bf16 v[62:65], v[142:145], v[174:177], v[62:65]
	v_mfma_f32_16x16x32_bf16 v[58:61], v[150:153], v[174:177], v[58:61]
	v_mfma_f32_16x16x32_bf16 v[54:57], v[142:145], v[182:185], v[54:57]
	v_mfma_f32_16x16x32_bf16 v[50:53], v[150:153], v[182:185], v[50:53]
	v_mfma_f32_16x16x32_bf16 v[42:45], v[142:145], v[190:193], v[42:45]
	v_mfma_f32_16x16x32_bf16 v[34:37], v[150:153], v[190:193], v[34:37]
	v_mfma_f32_16x16x32_bf16 v[26:29], v[142:145], v[202:205], v[26:29]
	v_mfma_f32_16x16x32_bf16 v[18:21], v[150:153], v[202:205], v[18:21]
	v_mfma_f32_16x16x32_bf16 v[62:65], v[146:149], v[178:181], v[62:65]
	v_mfma_f32_16x16x32_bf16 v[58:61], v[154:157], v[178:181], v[58:61]
	v_mfma_f32_16x16x32_bf16 v[54:57], v[146:149], v[186:189], v[54:57]
	v_mfma_f32_16x16x32_bf16 v[50:53], v[154:157], v[186:189], v[50:53]
	v_mfma_f32_16x16x32_bf16 v[42:45], v[146:149], v[198:201], v[42:45]
	v_mfma_f32_16x16x32_bf16 v[34:37], v[154:157], v[198:201], v[34:37]
	v_mfma_f32_16x16x32_bf16 v[26:29], v[146:149], v[206:209], v[26:29]
	v_mfma_f32_16x16x32_bf16 v[18:21], v[154:157], v[206:209], v[18:21]
	v_mfma_f32_16x16x32_bf16 v[46:49], v[158:161], v[174:177], v[46:49]
	v_mfma_f32_16x16x32_bf16 v[38:41], v[166:169], v[174:177], v[38:41]
	v_mfma_f32_16x16x32_bf16 v[30:33], v[158:161], v[182:185], v[30:33]
	v_mfma_f32_16x16x32_bf16 v[22:25], v[166:169], v[182:185], v[22:25]
	v_mfma_f32_16x16x32_bf16 v[14:17], v[158:161], v[190:193], v[14:17]
	v_mfma_f32_16x16x32_bf16 v[10:13], v[166:169], v[190:193], v[10:13]
	v_mfma_f32_16x16x32_bf16 v[6:9], v[158:161], v[202:205], v[6:9]
	v_mfma_f32_16x16x32_bf16 v[2:5], v[166:169], v[202:205], v[2:5]
	v_mfma_f32_16x16x32_bf16 v[46:49], v[162:165], v[178:181], v[46:49]
	v_mfma_f32_16x16x32_bf16 v[38:41], v[170:173], v[178:181], v[38:41]
	v_mfma_f32_16x16x32_bf16 v[30:33], v[162:165], v[186:189], v[30:33]
	v_mfma_f32_16x16x32_bf16 v[22:25], v[170:173], v[186:189], v[22:25]
	v_mfma_f32_16x16x32_bf16 v[14:17], v[162:165], v[198:201], v[14:17]
	v_mfma_f32_16x16x32_bf16 v[10:13], v[170:173], v[198:201], v[10:13]
	v_mfma_f32_16x16x32_bf16 v[6:9], v[162:165], v[206:209], v[6:9]
	v_mfma_f32_16x16x32_bf16 v[2:5], v[170:173], v[206:209], v[2:5]
	s_barrier
	s_add_u32 s30, s30, 0x100
	s_addc_u32 s31, s31, 0
	s_add_u32 s65, s65, 0x100
	s_addc_u32 s86, s86, 0
	s_cmp_ge_u32 s87, s4
	s_mov_b32 s38, s87
	s_cbranch_scc1 .Lpeel_done_833
.LBB0_833:
	s_add_i32 s87, s38, 2
	s_add_u32 s72, s30, 0x80
	s_addc_u32 s39, s31, 0
	s_add_i32 s78, 0, 0x10000
	s_cmp_eq_u32 s54, s38
	s_cselect_b32 s39, s21, s39
	s_cselect_b32 s38, s20, s72
	v_add_u32_e32 v0, s78, v139
	s_cselect_b32 s73, s7, s86
	s_cselect_b32 s72, s6, s65
	s_add_i32 s79, 0, 0x14000
	ds_read_b128 v[142:145], v0
	ds_read_b128 v[146:149], v0 offset:1024
	ds_read_b128 v[150:153], v0 offset:2048
	ds_read_b128 v[154:157], v0 offset:3072
	v_add_u32_e32 v0, s79, v139
	ds_read_b128 v[158:161], v0
	ds_read_b128 v[162:165], v0 offset:1024
	ds_read_b128 v[166:169], v0 offset:2048
	ds_read_b128 v[170:173], v0 offset:3072
	v_lshl_add_u64 v[210:211], s[30:31], 0, v[134:135]
	s_add_i32 m0, s42, 0xc000
	ds_read_b128 v[174:177], v141
	ds_read_b128 v[178:181], v141 offset:1024
	ds_read_b128 v[182:185], v141 offset:2048
	ds_read_b128 v[186:189], v141 offset:3072
	ds_read_b128 v[190:193], v141 offset:4096
	ds_read_b128 v[198:201], v141 offset:5120
	ds_read_b128 v[202:205], v141 offset:6144
	ds_read_b128 v[206:209], v141 offset:7168
	global_load_lds_dwordx4 v[210:211], off
	v_lshl_add_u64 v[210:211], s[30:31], 0, v[136:137]
	s_add_i32 m0, s42, 0xe000
	s_nop 0
	global_load_lds_dwordx4 v[210:211], off
	s_waitcnt vmcnt(8)
	s_waitcnt lgkmcnt(0)
	s_barrier
; #define PG8_STAGE(bufoff, gbase, voff) do { _Pragma("unroll") for (int _i = 0; _i < 2; ++_i) \
;         __builtin_amdgcn_global_load_lds((const unsigned*)((const char*)(gbase) + (voff)[_i]), (PG8_LAS unsigned*)(lds + (bufoff) + ldsw + _i * 8192), 16, 0, 0); } while (0)
; #define PG8_LDA(dst, b, h) do { _Pragma("unroll") for (int m = 0; m < 4; ++m) _Pragma("unroll") for (int k = 0; k < 2; ++k) dst[m][k] = *(const PG8_LAS bf16x8*)(lds + PG8_SA(b, h) + aoff + m * 2048 + k * 1024); } while (0)
; #define PG8_LDB(dst, b, h) do { _Pragma("unroll") for (int n = 0; n < 2; ++n) _Pragma("unroll") for (int k = 0; k < 2; ++k) dst[n][k] = *(const PG8_LAS bf16x8*)(lds + PG8_SB(b, h) + boff + n * 2048 + k * 1024); } while (0)
; #define PG8_MMA(ai, bj, At, Bt) do { __builtin_amdgcn_s_setprio(1); _Pragma("unroll") for (int m = 0; m < 4; ++m) _Pragma("unroll") for (int n = 0; n < 2; ++n) _Pragma("unroll") for (int k = 0; k < 2; ++k) \
;         acc[ai][bj][m][n] = __builtin_amdgcn_mfma_f32_16x16x32_bf16(Bt[n][k], At[m][k], acc[ai][bj][m][n], 0, 0, 0); __builtin_amdgcn_s_setprio(0); } while (0)
; #define PG8_WAIT_V(n) asm volatile("s_waitcnt vmcnt(" #n ")" ::: "memory")
; #define PG8_WAIT_L(n) asm volatile("s_waitcnt lgkmcnt(" #n ")" ::: "memory")
; #define PG8_BAR __builtin_amdgcn_s_barrier()
; template <class Epi, class Sched, bool ALIGN_EPI = false, bool SP2 = false>
; __device__ __forceinline__ void gemm_phase(PG8_LAS unsigned char* lds, const Gemm g, const Sched& S, const Epi& E) {
;     ...
;             PG8_WAIT_V(8); PG8_WAIT_L(0); PG8_BAR; PG8_MMA(0, 0, At, B0); PG8_MMA(0, 1, At, B1); PG8_BAR; PG8_SCHED;
;             PG8_LDA(At, 0, 1); PG8_STAGE(PG8_SB(0, 0), b2, voffB); PG8_STAGE(PG8_SB(0, 1), b2 + hstep, voffB); PG8_STAGE(PG8_SA(0, 0), a2, voffA);
;             PG8_WAIT_V(8); PG8_WAIT_L(0); PG8_BAR; PG8_MMA(1, 0, At, B0); PG8_MMA(1, 1, At, B1); PG8_BAR; PG8_SCHED;
;             PG8_LDB(B0, 1, 0); PG8_LDB(B1, 1, 1); PG8_SCHED; PG8_LDA(At, 1, 0); PG8_STAGE(PG8_SA(0, 1), a2 + hstep, voffA);
;             PG8_WAIT_V(8); PG8_WAIT_L(0); PG8_BAR; PG8_MMA(0, 0, At, B0); PG8_MMA(0, 1, At, B1); PG8_BAR; PG8_SCHED;
;             PG8_LDA(At, 1, 1); PG8_STAGE(PG8_SB(1, 0), b3, voffB); PG8_STAGE(PG8_SB(1, 1), b3 + hstep, voffB); PG8_STAGE(PG8_SA(1, 0), a3, voffA);
;             PG8_WAIT_V(8); PG8_WAIT_L(0); PG8_BAR; PG8_MMA(1, 0, At, B0); PG8_MMA(1, 1, At, B1); PG8_BAR; PG8_SCHED;
	s_waitcnt lgkmcnt(0)
	v_mfma_f32_16x16x32_bf16 v[126:129], v[142:145], v[174:177], v[126:129]
	v_mfma_f32_16x16x32_bf16 v[122:125], v[150:153], v[174:177], v[122:125]
	v_mfma_f32_16x16x32_bf16 v[118:121], v[142:145], v[182:185], v[118:121]
	v_mfma_f32_16x16x32_bf16 v[114:117], v[150:153], v[182:185], v[114:117]
	v_mfma_f32_16x16x32_bf16 v[110:113], v[142:145], v[190:193], v[110:113]
	v_mfma_f32_16x16x32_bf16 v[102:105], v[150:153], v[190:193], v[102:105]
	v_mfma_f32_16x16x32_bf16 v[90:93], v[142:145], v[202:205], v[90:93]
	v_mfma_f32_16x16x32_bf16 v[82:85], v[150:153], v[202:205], v[82:85]
	v_mfma_f32_16x16x32_bf16 v[126:129], v[146:149], v[178:181], v[126:129]
	v_mfma_f32_16x16x32_bf16 v[122:125], v[154:157], v[178:181], v[122:125]
	v_mfma_f32_16x16x32_bf16 v[118:121], v[146:149], v[186:189], v[118:121]
	v_mfma_f32_16x16x32_bf16 v[114:117], v[154:157], v[186:189], v[114:117]
	v_mfma_f32_16x16x32_bf16 v[110:113], v[146:149], v[198:201], v[110:113]
	v_mfma_f32_16x16x32_bf16 v[102:105], v[154:157], v[198:201], v[102:105]
	v_mfma_f32_16x16x32_bf16 v[90:93], v[146:149], v[206:209], v[90:93]
	v_mfma_f32_16x16x32_bf16 v[82:85], v[154:157], v[206:209], v[82:85]
	v_mfma_f32_16x16x32_bf16 v[106:109], v[158:161], v[174:177], v[106:109]
	v_mfma_f32_16x16x32_bf16 v[98:101], v[166:169], v[174:177], v[98:101]
	v_mfma_f32_16x16x32_bf16 v[94:97], v[158:161], v[182:185], v[94:97]
	v_mfma_f32_16x16x32_bf16 v[86:89], v[166:169], v[182:185], v[86:89]
	v_mfma_f32_16x16x32_bf16 v[78:81], v[158:161], v[190:193], v[78:81]
	v_mfma_f32_16x16x32_bf16 v[74:77], v[166:169], v[190:193], v[74:77]
	v_mfma_f32_16x16x32_bf16 v[70:73], v[158:161], v[202:205], v[70:73]
	v_mfma_f32_16x16x32_bf16 v[66:69], v[166:169], v[202:205], v[66:69]
	v_mfma_f32_16x16x32_bf16 v[106:109], v[162:165], v[178:181], v[106:109]
	v_mfma_f32_16x16x32_bf16 v[98:101], v[170:173], v[178:181], v[98:101]
	v_mfma_f32_16x16x32_bf16 v[94:97], v[162:165], v[186:189], v[94:97]
	v_mfma_f32_16x16x32_bf16 v[86:89], v[170:173], v[186:189], v[86:89]
	v_mfma_f32_16x16x32_bf16 v[78:81], v[162:165], v[198:201], v[78:81]
	v_mfma_f32_16x16x32_bf16 v[74:77], v[170:173], v[198:201], v[74:77]
	v_mfma_f32_16x16x32_bf16 v[70:73], v[162:165], v[206:209], v[70:73]
	v_mfma_f32_16x16x32_bf16 v[66:69], v[170:173], v[206:209], v[66:69]
	s_barrier
	s_add_i32 s78, s78, s41
	v_lshl_add_u64 v[210:211], s[72:73], 0, v[132:133]
	s_mov_b32 m0, s78
	ds_read_b128 v[174:177], v141 offset:16384
	ds_read_b128 v[178:181], v141 offset:17408
	ds_read_b128 v[182:185], v141 offset:18432
	ds_read_b128 v[186:189], v141 offset:19456
	ds_read_b128 v[190:193], v141 offset:20480
	ds_read_b128 v[198:201], v141 offset:21504
	ds_read_b128 v[202:205], v141 offset:22528
	ds_read_b128 v[206:209], v141 offset:23552
	global_load_lds_dwordx4 v[210:211], off
	s_add_i32 m0, s78, 0x2000
	v_lshl_add_u64 v[212:213], s[72:73], 0, v[130:131]
	s_add_u32 s72, s72, s8
	s_addc_u32 s73, s73, 0
	s_add_i32 s78, s79, s41
	global_load_lds_dwordx4 v[212:213], off
	v_lshl_add_u64 v[214:215], s[72:73], 0, v[132:133]
	s_mov_b32 m0, s78
	v_lshl_add_u64 v[216:217], s[72:73], 0, v[130:131]
	global_load_lds_dwordx4 v[214:215], off
	s_add_i32 m0, s78, 0x2000
	v_lshl_add_u64 v[218:219], s[38:39], 0, v[132:133]
	global_load_lds_dwordx4 v[216:217], off
	s_mov_b32 m0, s42
	v_lshl_add_u64 v[220:221], s[38:39], 0, v[130:131]
	global_load_lds_dwordx4 v[218:219], off
	s_mov_b32 m0, s43
	s_nop 0
	global_load_lds_dwordx4 v[220:221], off
	s_waitcnt vmcnt(8)
	s_waitcnt lgkmcnt(0)
	s_barrier
	s_waitcnt lgkmcnt(0)
	v_mfma_f32_16x16x32_bf16 v[62:65], v[142:145], v[174:177], v[62:65]
	v_mfma_f32_16x16x32_bf16 v[58:61], v[150:153], v[174:177], v[58:61]
	v_mfma_f32_16x16x32_bf16 v[54:57], v[142:145], v[182:185], v[54:57]
	v_mfma_f32_16x16x32_bf16 v[50:53], v[150:153], v[182:185], v[50:53]
	v_mfma_f32_16x16x32_bf16 v[42:45], v[142:145], v[190:193], v[42:45]
	v_mfma_f32_16x16x32_bf16 v[34:37], v[150:153], v[190:193], v[34:37]
	v_mfma_f32_16x16x32_bf16 v[26:29], v[142:145], v[202:205], v[26:29]
	v_mfma_f32_16x16x32_bf16 v[18:21], v[150:153], v[202:205], v[18:21]
	v_mfma_f32_16x16x32_bf16 v[62:65], v[146:149], v[178:181], v[62:65]
	v_mfma_f32_16x16x32_bf16 v[58:61], v[154:157], v[178:181], v[58:61]
	v_mfma_f32_16x16x32_bf16 v[54:57], v[146:149], v[186:189], v[54:57]
	v_mfma_f32_16x16x32_bf16 v[50:53], v[154:157], v[186:189], v[50:53]
	v_mfma_f32_16x16x32_bf16 v[42:45], v[146:149], v[198:201], v[42:45]
	v_mfma_f32_16x16x32_bf16 v[34:37], v[154:157], v[198:201], v[34:37]
	v_mfma_f32_16x16x32_bf16 v[26:29], v[146:149], v[206:209], v[26:29]
	v_mfma_f32_16x16x32_bf16 v[18:21], v[154:157], v[206:209], v[18:21]
	v_mfma_f32_16x16x32_bf16 v[46:49], v[158:161], v[174:177], v[46:49]
	v_mfma_f32_16x16x32_bf16 v[38:41], v[166:169], v[174:177], v[38:41]
	v_mfma_f32_16x16x32_bf16 v[30:33], v[158:161], v[182:185], v[30:33]
	v_mfma_f32_16x16x32_bf16 v[22:25], v[166:169], v[182:185], v[22:25]
	v_mfma_f32_16x16x32_bf16 v[14:17], v[158:161], v[190:193], v[14:17]
	v_mfma_f32_16x16x32_bf16 v[10:13], v[166:169], v[190:193], v[10:13]
	v_mfma_f32_16x16x32_bf16 v[6:9], v[158:161], v[202:205], v[6:9]
	v_mfma_f32_16x16x32_bf16 v[2:5], v[166:169], v[202:205], v[2:5]
	v_mfma_f32_16x16x32_bf16 v[46:49], v[162:165], v[178:181], v[46:49]
	v_mfma_f32_16x16x32_bf16 v[38:41], v[170:173], v[178:181], v[38:41]
	v_mfma_f32_16x16x32_bf16 v[30:33], v[162:165], v[186:189], v[30:33]
	v_mfma_f32_16x16x32_bf16 v[22:25], v[170:173], v[186:189], v[22:25]
	v_mfma_f32_16x16x32_bf16 v[14:17], v[162:165], v[198:201], v[14:17]
	v_mfma_f32_16x16x32_bf16 v[10:13], v[170:173], v[198:201], v[10:13]
	v_mfma_f32_16x16x32_bf16 v[6:9], v[162:165], v[206:209], v[6:9]
	v_mfma_f32_16x16x32_bf16 v[2:5], v[170:173], v[206:209], v[2:5]
	s_barrier
; #define PG8_STAGE(bufoff, gbase, voff) do { _Pragma("unroll") for (int _i = 0; _i < 2; ++_i) \
;         __builtin_amdgcn_global_load_lds((const unsigned*)((const char*)(gbase) + (voff)[_i]), (PG8_LAS unsigned*)(lds + (bufoff) + ldsw + _i * 8192), 16, 0, 0); } while (0)
; #define PG8_LDA(dst, b, h) do { _Pragma("unroll") for (int m = 0; m < 4; ++m) _Pragma("unroll") for (int k = 0; k < 2; ++k) dst[m][k] = *(const PG8_LAS bf16x8*)(lds + PG8_SA(b, h) + aoff + m * 2048 + k * 1024); } while (0)
; #define PG8_LDB(dst, b, h) do { _Pragma("unroll") for (int n = 0; n < 2; ++n) _Pragma("unroll") for (int k = 0; k < 2; ++k) dst[n][k] = *(const PG8_LAS bf16x8*)(lds + PG8_SB(b, h) + boff + n * 2048 + k * 1024); } while (0)
; #define PG8_MMA(ai, bj, At, Bt) do { __builtin_amdgcn_s_setprio(1); _Pragma("unroll") for (int m = 0; m < 4; ++m) _Pragma("unroll") for (int n = 0; n < 2; ++n) _Pragma("unroll") for (int k = 0; k < 2; ++k) \
;         acc[ai][bj][m][n] = __builtin_amdgcn_mfma_f32_16x16x32_bf16(Bt[n][k], At[m][k], acc[ai][bj][m][n], 0, 0, 0); __builtin_amdgcn_s_setprio(0); } while (0)
; #define PG8_WAIT_V(n) asm volatile("s_waitcnt vmcnt(" #n ")" ::: "memory")
; #define PG8_WAIT_L(n) asm volatile("s_waitcnt lgkmcnt(" #n ")" ::: "memory")
; #define PG8_BAR __builtin_amdgcn_s_barrier()
; #define PG8_SCHED __builtin_amdgcn_sched_barrier(0)
; template <class Epi, class Sched, bool ALIGN_EPI = false, bool SP2 = false>
; __device__ __forceinline__ void gemm_phase(PG8_LAS unsigned char* lds, const Gemm g, const Sched& S, const Epi& E) {
;     ...
;             PG8_LDB(B0, 1, 0); PG8_LDB(B1, 1, 1); PG8_SCHED; PG8_LDA(At, 1, 0); PG8_STAGE(PG8_SA(0, 1), a2 + hstep, voffA);
;             PG8_WAIT_V(8); PG8_WAIT_L(0); PG8_BAR; PG8_MMA(0, 0, At, B0); PG8_MMA(0, 1, At, B1); PG8_BAR; PG8_SCHED;
;             PG8_LDA(At, 1, 1); PG8_STAGE(PG8_SB(1, 0), b3, voffB); PG8_STAGE(PG8_SB(1, 1), b3 + hstep, voffB); PG8_STAGE(PG8_SA(1, 0), a3, voffA);
;             PG8_WAIT_V(8); PG8_WAIT_L(0); PG8_BAR; PG8_MMA(1, 0, At, B0); PG8_MMA(1, 1, At, B1); PG8_BAR; PG8_SCHED;
	s_add_i32 s72, 0, 0x18000
	v_add_u32_e32 v0, s72, v139
	s_add_i32 s73, 0, 0x1c000
	ds_read_b128 v[142:145], v0
	ds_read_b128 v[146:149], v0 offset:1024
	ds_read_b128 v[150:153], v0 offset:2048
	ds_read_b128 v[154:157], v0 offset:3072
	v_add_u32_e32 v0, s73, v139
	ds_read_b128 v[158:161], v0
	ds_read_b128 v[162:165], v0 offset:1024
	ds_read_b128 v[166:169], v0 offset:2048
	ds_read_b128 v[170:173], v0 offset:3072
	s_add_u32 s38, s38, s8
	s_addc_u32 s39, s39, 0
	s_mov_b32 m0, s44
	v_lshl_add_u64 v[222:223], s[38:39], 0, v[132:133]
	ds_read_b128 v[174:177], v141 offset:32768
	ds_read_b128 v[178:181], v141 offset:33792
	ds_read_b128 v[182:185], v141 offset:34816
	ds_read_b128 v[186:189], v141 offset:35840
	ds_read_b128 v[190:193], v141 offset:36864
	ds_read_b128 v[198:201], v141 offset:37888
	ds_read_b128 v[202:205], v141 offset:38912
	ds_read_b128 v[206:209], v141 offset:39936
	global_load_lds_dwordx4 v[222:223], off
	v_lshl_add_u64 v[222:223], s[38:39], 0, v[130:131]
	s_mov_b32 m0, s45
	s_nop 0
	global_load_lds_dwordx4 v[222:223], off
	s_waitcnt vmcnt(8)
	s_waitcnt lgkmcnt(0)
	s_barrier
	s_waitcnt lgkmcnt(0)
	v_mfma_f32_16x16x32_bf16 v[126:129], v[142:145], v[174:177], v[126:129]
	v_mfma_f32_16x16x32_bf16 v[122:125], v[150:153], v[174:177], v[122:125]
	v_mfma_f32_16x16x32_bf16 v[118:121], v[142:145], v[182:185], v[118:121]
	v_mfma_f32_16x16x32_bf16 v[114:117], v[150:153], v[182:185], v[114:117]
	v_mfma_f32_16x16x32_bf16 v[110:113], v[142:145], v[190:193], v[110:113]
	v_mfma_f32_16x16x32_bf16 v[102:105], v[150:153], v[190:193], v[102:105]
	v_mfma_f32_16x16x32_bf16 v[90:93], v[142:145], v[202:205], v[90:93]
	v_mfma_f32_16x16x32_bf16 v[82:85], v[150:153], v[202:205], v[82:85]
	v_mfma_f32_16x16x32_bf16 v[126:129], v[146:149], v[178:181], v[126:129]
	v_mfma_f32_16x16x32_bf16 v[122:125], v[154:157], v[178:181], v[122:125]
	v_mfma_f32_16x16x32_bf16 v[118:121], v[146:149], v[186:189], v[118:121]
	v_mfma_f32_16x16x32_bf16 v[114:117], v[154:157], v[186:189], v[114:117]
	v_mfma_f32_16x16x32_bf16 v[110:113], v[146:149], v[198:201], v[110:113]
	v_mfma_f32_16x16x32_bf16 v[102:105], v[154:157], v[198:201], v[102:105]
	v_mfma_f32_16x16x32_bf16 v[90:93], v[146:149], v[206:209], v[90:93]
	v_mfma_f32_16x16x32_bf16 v[82:85], v[154:157], v[206:209], v[82:85]
	v_mfma_f32_16x16x32_bf16 v[106:109], v[158:161], v[174:177], v[106:109]
	v_mfma_f32_16x16x32_bf16 v[98:101], v[166:169], v[174:177], v[98:101]
	v_mfma_f32_16x16x32_bf16 v[94:97], v[158:161], v[182:185], v[94:97]
	v_mfma_f32_16x16x32_bf16 v[86:89], v[166:169], v[182:185], v[86:89]
	v_mfma_f32_16x16x32_bf16 v[78:81], v[158:161], v[190:193], v[78:81]
	v_mfma_f32_16x16x32_bf16 v[74:77], v[166:169], v[190:193], v[74:77]
	v_mfma_f32_16x16x32_bf16 v[70:73], v[158:161], v[202:205], v[70:73]
	v_mfma_f32_16x16x32_bf16 v[66:69], v[166:169], v[202:205], v[66:69]
	v_mfma_f32_16x16x32_bf16 v[106:109], v[162:165], v[178:181], v[106:109]
	v_mfma_f32_16x16x32_bf16 v[98:101], v[170:173], v[178:181], v[98:101]
	v_mfma_f32_16x16x32_bf16 v[94:97], v[162:165], v[186:189], v[94:97]
	v_mfma_f32_16x16x32_bf16 v[86:89], v[170:173], v[186:189], v[86:89]
	v_mfma_f32_16x16x32_bf16 v[78:81], v[162:165], v[198:201], v[78:81]
	v_mfma_f32_16x16x32_bf16 v[74:77], v[170:173], v[198:201], v[74:77]
	v_mfma_f32_16x16x32_bf16 v[70:73], v[162:165], v[206:209], v[70:73]
	v_mfma_f32_16x16x32_bf16 v[66:69], v[170:173], v[206:209], v[66:69]
	s_barrier
	s_add_i32 s38, s72, s41
	v_lshl_add_u64 v[210:211], v[210:211], 0, s[58:59]
	s_mov_b32 m0, s38
	ds_read_b128 v[174:177], v141 offset:49152
	ds_read_b128 v[178:181], v141 offset:50176
	ds_read_b128 v[182:185], v141 offset:51200
	ds_read_b128 v[186:189], v141 offset:52224
	ds_read_b128 v[190:193], v141 offset:53248
	ds_read_b128 v[198:201], v141 offset:54272
	ds_read_b128 v[202:205], v141 offset:55296
	ds_read_b128 v[206:209], v141 offset:56320
	global_load_lds_dwordx4 v[210:211], off
	v_lshl_add_u64 v[210:211], v[212:213], 0, s[58:59]
	s_add_i32 m0, s38, 0x2000
	s_add_i32 s38, s73, s41
	global_load_lds_dwordx4 v[210:211], off
	v_lshl_add_u64 v[210:211], v[214:215], 0, s[58:59]
	s_mov_b32 m0, s38
	s_nop 0
	global_load_lds_dwordx4 v[210:211], off
	v_lshl_add_u64 v[210:211], v[216:217], 0, s[58:59]
	s_add_i32 m0, s38, 0x2000
	s_nop 0
	global_load_lds_dwordx4 v[210:211], off
	v_lshl_add_u64 v[210:211], v[218:219], 0, s[58:59]
	s_mov_b32 m0, s50
	s_nop 0
	global_load_lds_dwordx4 v[210:211], off
	v_lshl_add_u64 v[210:211], v[220:221], 0, s[58:59]
	s_mov_b32 m0, s51
	s_nop 0
	global_load_lds_dwordx4 v[210:211], off
	s_waitcnt vmcnt(8)
	s_waitcnt lgkmcnt(0)
	s_barrier
	s_waitcnt lgkmcnt(0)
	v_mfma_f32_16x16x32_bf16 v[62:65], v[142:145], v[174:177], v[62:65]
	v_mfma_f32_16x16x32_bf16 v[58:61], v[150:153], v[174:177], v[58:61]
	v_mfma_f32_16x16x32_bf16 v[54:57], v[142:145], v[182:185], v[54:57]
	v_mfma_f32_16x16x32_bf16 v[50:53], v[150:153], v[182:185], v[50:53]
	v_mfma_f32_16x16x32_bf16 v[42:45], v[142:145], v[190:193], v[42:45]
	v_mfma_f32_16x16x32_bf16 v[34:37], v[150:153], v[190:193], v[34:37]
	v_mfma_f32_16x16x32_bf16 v[26:29], v[142:145], v[202:205], v[26:29]
	v_mfma_f32_16x16x32_bf16 v[18:21], v[150:153], v[202:205], v[18:21]
	v_mfma_f32_16x16x32_bf16 v[62:65], v[146:149], v[178:181], v[62:65]
	v_mfma_f32_16x16x32_bf16 v[58:61], v[154:157], v[178:181], v[58:61]
	v_mfma_f32_16x16x32_bf16 v[54:57], v[146:149], v[186:189], v[54:57]
	v_mfma_f32_16x16x32_bf16 v[50:53], v[154:157], v[186:189], v[50:53]
	v_mfma_f32_16x16x32_bf16 v[42:45], v[146:149], v[198:201], v[42:45]
	v_mfma_f32_16x16x32_bf16 v[34:37], v[154:157], v[198:201], v[34:37]
	v_mfma_f32_16x16x32_bf16 v[26:29], v[146:149], v[206:209], v[26:29]
	v_mfma_f32_16x16x32_bf16 v[18:21], v[154:157], v[206:209], v[18:21]
	v_mfma_f32_16x16x32_bf16 v[46:49], v[158:161], v[174:177], v[46:49]
	v_mfma_f32_16x16x32_bf16 v[38:41], v[166:169], v[174:177], v[38:41]
	v_mfma_f32_16x16x32_bf16 v[30:33], v[158:161], v[182:185], v[30:33]
	v_mfma_f32_16x16x32_bf16 v[22:25], v[166:169], v[182:185], v[22:25]
	v_mfma_f32_16x16x32_bf16 v[14:17], v[158:161], v[190:193], v[14:17]
	v_mfma_f32_16x16x32_bf16 v[10:13], v[166:169], v[190:193], v[10:13]
	v_mfma_f32_16x16x32_bf16 v[6:9], v[158:161], v[202:205], v[6:9]
	v_mfma_f32_16x16x32_bf16 v[2:5], v[166:169], v[202:205], v[2:5]
	v_mfma_f32_16x16x32_bf16 v[46:49], v[162:165], v[178:181], v[46:49]
	v_mfma_f32_16x16x32_bf16 v[38:41], v[170:173], v[178:181], v[38:41]
	v_mfma_f32_16x16x32_bf16 v[30:33], v[162:165], v[186:189], v[30:33]
	v_mfma_f32_16x16x32_bf16 v[22:25], v[170:173], v[186:189], v[22:25]
	v_mfma_f32_16x16x32_bf16 v[14:17], v[162:165], v[198:201], v[14:17]
	v_mfma_f32_16x16x32_bf16 v[10:13], v[170:173], v[198:201], v[10:13]
	v_mfma_f32_16x16x32_bf16 v[6:9], v[162:165], v[206:209], v[6:9]
	v_mfma_f32_16x16x32_bf16 v[2:5], v[170:173], v[206:209], v[2:5]
	s_barrier
	s_add_u32 s30, s30, 0x100
	s_addc_u32 s31, s31, 0
	s_add_u32 s65, s65, 0x100
	s_addc_u32 s86, s86, 0
	s_cmp_ge_u32 s87, s4
	s_mov_b32 s38, s87
	s_cbranch_scc0 .LBB0_833

; #define PG8_STAGE(bufoff, gbase, voff) do { _Pragma("unroll") for (int _i = 0; _i < 2; ++_i) \
;         __builtin_amdgcn_global_load_lds((const unsigned*)((const char*)(gbase) + (voff)[_i]), (PG8_LAS unsigned*)(lds + (bufoff) + ldsw + _i * 8192), 16, 0, 0); } while (0)
; #define PG8_LDA(dst, b, h) do { _Pragma("unroll") for (int m = 0; m < 4; ++m) _Pragma("unroll") for (int k = 0; k < 2; ++k) dst[m][k] = *(const PG8_LAS bf16x8*)(lds + PG8_SA(b, h) + aoff + m * 2048 + k * 1024); } while (0)
; #define PG8_LDB(dst, b, h) do { _Pragma("unroll") for (int n = 0; n < 2; ++n) _Pragma("unroll") for (int k = 0; k < 2; ++k) dst[n][k] = *(const PG8_LAS bf16x8*)(lds + PG8_SB(b, h) + boff + n * 2048 + k * 1024); } while (0)
; #define PG8_WAIT_V(n) asm volatile("s_waitcnt vmcnt(" #n ")" ::: "memory")
; #define PG8_WAIT_L(n) asm volatile("s_waitcnt lgkmcnt(" #n ")" ::: "memory")
; #define PG8_BAR __builtin_amdgcn_s_barrier()
; #define PG8_SCHED __builtin_amdgcn_sched_barrier(0)
; template <class Epi, class Sched, bool ALIGN_EPI = false, bool SP2 = false>
; __device__ __forceinline__ void gemm_phase(PG8_LAS unsigned char* lds, const Gemm g, const Sched& S, const Epi& E) {
;     ...
;         const char* nA = has_next ? (const char*)g.A + (size_t)nxt.pm * tstep : cA; const char* nB = has_next ? (const char*)g.Bt + (size_t)nxt.pn * tstep : cB;
;         for (int t = 0; t < nt; t += 2) {
;             const bool last = (t == nt - 2);
;             const char* a1 = cA + (size_t)(t + 1) * kstep;
;             const char* a2 = last ? nA : cA + (size_t)(t + 2) * kstep; const char* b2 = last ? nB : cB + (size_t)(t + 2) * kstep;
;             const char* a3 = a2 + kstep; const char* b3 = b2 + kstep;
;             if (last && has_next) S.a_ready(nxt);
;             if constexpr (SP2) {
;             PG8_LDB(B0, 0, 0); PG8_LDB(B1, 0, 1); PG8_SCHED; PG8_LDA(At, 0, 0); PG8_STAGE(PG8_SA(1, 1), a1 + hstep, voffA);
;             PG8_WAIT_V(8); PG8_WAIT_L(0); PG8_BAR; PG8_MMA(0, 0, At, B0); PG8_MMA(0, 1, At, B1); PG8_BAR; PG8_SCHED;
;             PG8_LDA(At, 0, 1); PG8_STAGE(PG8_SB(0, 0), b2, voffB); PG8_STAGE(PG8_SB(0, 1), b2 + hstep, voffB); PG8_STAGE(PG8_SA(0, 0), a2, voffA);
;             PG8_WAIT_V(8); PG8_WAIT_L(0); PG8_BAR; PG8_MMA(1, 0, At, B0); PG8_MMA(1, 1, At, B1); PG8_BAR; PG8_SCHED;
.LBB0_1179:
	s_ashr_i32 s21, s20, 31
	s_lshl_b64 s[30:31], s[20:21], 19
	s_add_u32 s30, s77, s30
	s_addc_u32 s31, s26, s31
	s_and_b64 s[38:39], s[6:7], exec
	s_cselect_b32 s21, s31, s43
	s_cselect_b32 s29, s30, s42
	s_ashr_i32 s19, s18, 31
	s_lshl_b64 s[38:39], s[18:19], 19
	s_add_u32 s38, s22, s38
	s_addc_u32 s39, s23, s39
	s_and_b64 s[46:47], s[6:7], exec
	s_cselect_b32 s19, s39, s45
	s_cselect_b32 s41, s38, s44
	s_add_u32 s42, s42, 0x40080
	s_addc_u32 s43, s43, 0
	s_add_u32 s73, s44, 0x100
	s_addc_u32 s78, s45, 0
	s_mov_b32 s79, -2
	s_add_u32 s44, s42, 0xfffc0080
	s_addc_u32 s45, s43, -1
	s_add_i32 s86, 0, 0x10000
	s_cmp_eq_u32 s79, 12
	s_cselect_b32 s47, s21, s45
	s_cselect_b32 s46, s29, s44
	v_add_u32_e32 v0, s86, v145
	s_cselect_b32 s45, s19, s78
	s_cselect_b32 s44, s41, s73
	s_add_i32 s93, 0, 0x14000
	ds_read_b128 v[148:151], v0
	ds_read_b128 v[152:155], v0 offset:1024
	ds_read_b128 v[156:159], v0 offset:2048
	ds_read_b128 v[160:163], v0 offset:3072
	v_add_u32_e32 v0, s93, v145
	ds_read_b128 v[164:167], v0
	ds_read_b128 v[168:171], v0 offset:1024
	ds_read_b128 v[172:175], v0 offset:2048
	ds_read_b128 v[176:179], v0 offset:3072
	v_lshl_add_u64 v[142:143], s[42:43], 0, v[138:139]
	s_add_i32 m0, s49, 0xc000
	ds_read_b128 v[180:183], v147
	ds_read_b128 v[184:187], v147 offset:1024
	ds_read_b128 v[188:191], v147 offset:2048
	ds_read_b128 v[198:201], v147 offset:3072
	ds_read_b128 v[202:205], v147 offset:4096
	ds_read_b128 v[206:209], v147 offset:5120
	ds_read_b128 v[210:213], v147 offset:6144
	ds_read_b128 v[214:217], v147 offset:7168
	global_load_lds_dwordx4 v[142:143], off
	v_lshl_add_u64 v[142:143], s[42:43], 0, v[140:141]
	s_add_i32 m0, s49, 0xe000
	s_nop 0
	global_load_lds_dwordx4 v[142:143], off
	s_waitcnt vmcnt(8)
	s_waitcnt lgkmcnt(0)
	s_barrier
	s_waitcnt lgkmcnt(0)
	v_mfma_f32_16x16x32_bf16 v[126:129], v[148:151], v[180:183], 0
	v_mfma_f32_16x16x32_bf16 v[118:121], v[156:159], v[180:183], 0
	v_mfma_f32_16x16x32_bf16 v[110:113], v[148:151], v[188:191], 0
	v_mfma_f32_16x16x32_bf16 v[102:105], v[156:159], v[188:191], 0
	v_mfma_f32_16x16x32_bf16 v[94:97], v[148:151], v[202:205], 0
	v_mfma_f32_16x16x32_bf16 v[86:89], v[156:159], v[202:205], 0
	v_mfma_f32_16x16x32_bf16 v[78:81], v[148:151], v[210:213], 0
	v_mfma_f32_16x16x32_bf16 v[70:73], v[156:159], v[210:213], 0
	v_mfma_f32_16x16x32_bf16 v[126:129], v[152:155], v[184:187], v[126:129]
	v_mfma_f32_16x16x32_bf16 v[118:121], v[160:163], v[184:187], v[118:121]
	v_mfma_f32_16x16x32_bf16 v[110:113], v[152:155], v[198:201], v[110:113]
	v_mfma_f32_16x16x32_bf16 v[102:105], v[160:163], v[198:201], v[102:105]
	v_mfma_f32_16x16x32_bf16 v[94:97], v[152:155], v[206:209], v[94:97]
	v_mfma_f32_16x16x32_bf16 v[86:89], v[160:163], v[206:209], v[86:89]
	v_mfma_f32_16x16x32_bf16 v[78:81], v[152:155], v[214:217], v[78:81]
	v_mfma_f32_16x16x32_bf16 v[70:73], v[160:163], v[214:217], v[70:73]
	v_mfma_f32_16x16x32_bf16 v[122:125], v[164:167], v[180:183], 0
	v_mfma_f32_16x16x32_bf16 v[114:117], v[172:175], v[180:183], 0
	v_mfma_f32_16x16x32_bf16 v[106:109], v[164:167], v[188:191], 0
	v_mfma_f32_16x16x32_bf16 v[98:101], v[172:175], v[188:191], 0
	v_mfma_f32_16x16x32_bf16 v[90:93], v[164:167], v[202:205], 0
	v_mfma_f32_16x16x32_bf16 v[82:85], v[172:175], v[202:205], 0
	v_mfma_f32_16x16x32_bf16 v[74:77], v[164:167], v[210:213], 0
	v_mfma_f32_16x16x32_bf16 v[66:69], v[172:175], v[210:213], 0
	v_mfma_f32_16x16x32_bf16 v[122:125], v[168:171], v[184:187], v[122:125]
	v_mfma_f32_16x16x32_bf16 v[114:117], v[176:179], v[184:187], v[114:117]
	v_mfma_f32_16x16x32_bf16 v[106:109], v[168:171], v[198:201], v[106:109]
	v_mfma_f32_16x16x32_bf16 v[98:101], v[176:179], v[198:201], v[98:101]
	v_mfma_f32_16x16x32_bf16 v[90:93], v[168:171], v[206:209], v[90:93]
	v_mfma_f32_16x16x32_bf16 v[82:85], v[176:179], v[206:209], v[82:85]
	v_mfma_f32_16x16x32_bf16 v[74:77], v[168:171], v[214:217], v[74:77]
	v_mfma_f32_16x16x32_bf16 v[66:69], v[176:179], v[214:217], v[66:69]
	s_barrier
	s_add_i32 s86, s86, s25
	v_lshl_add_u64 v[142:143], s[44:45], 0, v[134:135]
	s_mov_b32 m0, s86
	ds_read_b128 v[180:183], v147 offset:16384
	ds_read_b128 v[184:187], v147 offset:17408
	ds_read_b128 v[188:191], v147 offset:18432
	ds_read_b128 v[198:201], v147 offset:19456
	ds_read_b128 v[202:205], v147 offset:20480
	ds_read_b128 v[206:209], v147 offset:21504
	ds_read_b128 v[210:213], v147 offset:22528
	ds_read_b128 v[214:217], v147 offset:23552
	global_load_lds_dwordx4 v[142:143], off
	s_add_i32 m0, s86, 0x2000
	s_add_u32 s86, s44, 0x40000
	v_lshl_add_u64 v[192:193], s[44:45], 0, v[130:131]
	s_addc_u32 s87, s45, 0
	s_add_i32 s93, s93, s25
	global_load_lds_dwordx4 v[192:193], off
	v_lshl_add_u64 v[218:219], s[86:87], 0, v[134:135]
	s_mov_b32 m0, s93
	v_lshl_add_u64 v[220:221], s[46:47], 0, v[132:133]
	global_load_lds_dwordx4 v[218:219], off
	v_lshl_add_u64 v[218:219], s[86:87], 0, v[130:131]
	s_add_i32 m0, s93, 0x2000
	s_nop 0
	global_load_lds_dwordx4 v[218:219], off
	v_lshl_add_u64 v[218:219], s[46:47], 0, v[136:137]
	s_mov_b32 m0, s49
	s_nop 0
	global_load_lds_dwordx4 v[218:219], off
	s_mov_b32 m0, s50
	s_nop 0
	global_load_lds_dwordx4 v[220:221], off
	s_waitcnt vmcnt(8)
	s_waitcnt lgkmcnt(0)
	s_barrier
; #define PG8_STAGE(bufoff, gbase, voff) do { _Pragma("unroll") for (int _i = 0; _i < 2; ++_i) \
;         __builtin_amdgcn_global_load_lds((const unsigned*)((const char*)(gbase) + (voff)[_i]), (PG8_LAS unsigned*)(lds + (bufoff) + ldsw + _i * 8192), 16, 0, 0); } while (0)
; #define PG8_LDA(dst, b, h) do { _Pragma("unroll") for (int m = 0; m < 4; ++m) _Pragma("unroll") for (int k = 0; k < 2; ++k) dst[m][k] = *(const PG8_LAS bf16x8*)(lds + PG8_SA(b, h) + aoff + m * 2048 + k * 1024); } while (0)
; #define PG8_LDB(dst, b, h) do { _Pragma("unroll") for (int n = 0; n < 2; ++n) _Pragma("unroll") for (int k = 0; k < 2; ++k) dst[n][k] = *(const PG8_LAS bf16x8*)(lds + PG8_SB(b, h) + boff + n * 2048 + k * 1024); } while (0)
; #define PG8_MMA(ai, bj, At, Bt) do { __builtin_amdgcn_s_setprio(1); _Pragma("unroll") for (int m = 0; m < 4; ++m) _Pragma("unroll") for (int n = 0; n < 2; ++n) _Pragma("unroll") for (int k = 0; k < 2; ++k) \
;         acc[ai][bj][m][n] = __builtin_amdgcn_mfma_f32_16x16x32_bf16(Bt[n][k], At[m][k], acc[ai][bj][m][n], 0, 0, 0); __builtin_amdgcn_s_setprio(0); } while (0)
; #define PG8_WAIT_V(n) asm volatile("s_waitcnt vmcnt(" #n ")" ::: "memory")
; #define PG8_WAIT_L(n) asm volatile("s_waitcnt lgkmcnt(" #n ")" ::: "memory")
; #define PG8_BAR __builtin_amdgcn_s_barrier()
; template <class Epi, class Sched, bool ALIGN_EPI = false, bool SP2 = false>
; __device__ __forceinline__ void gemm_phase(PG8_LAS unsigned char* lds, const Gemm g, const Sched& S, const Epi& E) {
;     ...
;             PG8_WAIT_V(8); PG8_WAIT_L(0); PG8_BAR; PG8_MMA(0, 0, At, B0); PG8_MMA(0, 1, At, B1); PG8_BAR; PG8_SCHED;
;             PG8_LDA(At, 0, 1); PG8_STAGE(PG8_SB(0, 0), b2, voffB); PG8_STAGE(PG8_SB(0, 1), b2 + hstep, voffB); PG8_STAGE(PG8_SA(0, 0), a2, voffA);
;             PG8_WAIT_V(8); PG8_WAIT_L(0); PG8_BAR; PG8_MMA(1, 0, At, B0); PG8_MMA(1, 1, At, B1); PG8_BAR; PG8_SCHED;
;             PG8_LDB(B0, 1, 0); PG8_LDB(B1, 1, 1); PG8_SCHED; PG8_LDA(At, 1, 0); PG8_STAGE(PG8_SA(0, 1), a2 + hstep, voffA);
;             PG8_WAIT_V(8); PG8_WAIT_L(0); PG8_BAR; PG8_MMA(0, 0, At, B0); PG8_MMA(0, 1, At, B1); PG8_BAR; PG8_SCHED;
;             PG8_LDA(At, 1, 1); PG8_STAGE(PG8_SB(1, 0), b3, voffB); PG8_STAGE(PG8_SB(1, 1), b3 + hstep, voffB); PG8_STAGE(PG8_SA(1, 0), a3, voffA);
;             PG8_WAIT_V(8); PG8_WAIT_L(0); PG8_BAR; PG8_MMA(1, 0, At, B0); PG8_MMA(1, 1, At, B1); PG8_BAR; PG8_SCHED;
	s_waitcnt lgkmcnt(0)
	v_mfma_f32_16x16x32_bf16 v[62:65], v[148:151], v[180:183], 0
	v_mfma_f32_16x16x32_bf16 v[54:57], v[156:159], v[180:183], 0
	v_mfma_f32_16x16x32_bf16 v[46:49], v[148:151], v[188:191], 0
	v_mfma_f32_16x16x32_bf16 v[38:41], v[156:159], v[188:191], 0
	v_mfma_f32_16x16x32_bf16 v[30:33], v[148:151], v[202:205], 0
	v_mfma_f32_16x16x32_bf16 v[22:25], v[156:159], v[202:205], 0
	v_mfma_f32_16x16x32_bf16 v[14:17], v[148:151], v[210:213], 0
	v_mfma_f32_16x16x32_bf16 v[6:9], v[156:159], v[210:213], 0
	v_mfma_f32_16x16x32_bf16 v[62:65], v[152:155], v[184:187], v[62:65]
	v_mfma_f32_16x16x32_bf16 v[54:57], v[160:163], v[184:187], v[54:57]
	v_mfma_f32_16x16x32_bf16 v[46:49], v[152:155], v[198:201], v[46:49]
	v_mfma_f32_16x16x32_bf16 v[38:41], v[160:163], v[198:201], v[38:41]
	v_mfma_f32_16x16x32_bf16 v[30:33], v[152:155], v[206:209], v[30:33]
	v_mfma_f32_16x16x32_bf16 v[22:25], v[160:163], v[206:209], v[22:25]
	v_mfma_f32_16x16x32_bf16 v[14:17], v[152:155], v[214:217], v[14:17]
	v_mfma_f32_16x16x32_bf16 v[6:9], v[160:163], v[214:217], v[6:9]
	v_mfma_f32_16x16x32_bf16 v[58:61], v[164:167], v[180:183], 0
	v_mfma_f32_16x16x32_bf16 v[50:53], v[172:175], v[180:183], 0
	v_mfma_f32_16x16x32_bf16 v[42:45], v[164:167], v[188:191], 0
	v_mfma_f32_16x16x32_bf16 v[34:37], v[172:175], v[188:191], 0
	v_mfma_f32_16x16x32_bf16 v[26:29], v[164:167], v[202:205], 0
	v_mfma_f32_16x16x32_bf16 v[18:21], v[172:175], v[202:205], 0
	v_mfma_f32_16x16x32_bf16 v[10:13], v[164:167], v[210:213], 0
	v_mfma_f32_16x16x32_bf16 v[2:5], v[172:175], v[210:213], 0
	v_mfma_f32_16x16x32_bf16 v[58:61], v[168:171], v[184:187], v[58:61]
	v_mfma_f32_16x16x32_bf16 v[50:53], v[176:179], v[184:187], v[50:53]
	v_mfma_f32_16x16x32_bf16 v[42:45], v[168:171], v[198:201], v[42:45]
	v_mfma_f32_16x16x32_bf16 v[34:37], v[176:179], v[198:201], v[34:37]
	v_mfma_f32_16x16x32_bf16 v[26:29], v[168:171], v[206:209], v[26:29]
	v_mfma_f32_16x16x32_bf16 v[18:21], v[176:179], v[206:209], v[18:21]
	v_mfma_f32_16x16x32_bf16 v[10:13], v[168:171], v[214:217], v[10:13]
	v_mfma_f32_16x16x32_bf16 v[2:5], v[176:179], v[214:217], v[2:5]
	s_barrier
	s_add_i32 s86, 0, 0x18000
	v_add_u32_e32 v0, s86, v145
	s_add_i32 s87, 0, 0x1c000
	ds_read_b128 v[148:151], v0
	ds_read_b128 v[152:155], v0 offset:1024
	ds_read_b128 v[156:159], v0 offset:2048
	ds_read_b128 v[160:163], v0 offset:3072
	v_add_u32_e32 v0, s87, v145
	ds_read_b128 v[164:167], v0
	ds_read_b128 v[168:171], v0 offset:1024
	ds_read_b128 v[172:175], v0 offset:2048
	ds_read_b128 v[176:179], v0 offset:3072
	s_add_u32 s46, s46, 0x40000
	s_addc_u32 s47, s47, 0
	s_mov_b32 m0, s51
	v_lshl_add_u64 v[222:223], s[46:47], 0, v[136:137]
	ds_read_b128 v[180:183], v147 offset:32768
	ds_read_b128 v[184:187], v147 offset:33792
	ds_read_b128 v[188:191], v147 offset:34816
	ds_read_b128 v[198:201], v147 offset:35840
	ds_read_b128 v[202:205], v147 offset:36864
	ds_read_b128 v[206:209], v147 offset:37888
	ds_read_b128 v[210:213], v147 offset:38912
	ds_read_b128 v[214:217], v147 offset:39936
	global_load_lds_dwordx4 v[222:223], off
	v_lshl_add_u64 v[222:223], s[46:47], 0, v[132:133]
	s_mov_b32 m0, s54
	s_nop 0
	global_load_lds_dwordx4 v[222:223], off
	s_waitcnt vmcnt(8)
	s_waitcnt lgkmcnt(0)
	s_barrier
	s_waitcnt lgkmcnt(0)
	v_mfma_f32_16x16x32_bf16 v[126:129], v[148:151], v[180:183], v[126:129]
	v_mfma_f32_16x16x32_bf16 v[118:121], v[156:159], v[180:183], v[118:121]
	v_mfma_f32_16x16x32_bf16 v[110:113], v[148:151], v[188:191], v[110:113]
	v_mfma_f32_16x16x32_bf16 v[102:105], v[156:159], v[188:191], v[102:105]
	v_mfma_f32_16x16x32_bf16 v[94:97], v[148:151], v[202:205], v[94:97]
	v_mfma_f32_16x16x32_bf16 v[86:89], v[156:159], v[202:205], v[86:89]
	v_mfma_f32_16x16x32_bf16 v[78:81], v[148:151], v[210:213], v[78:81]
	v_mfma_f32_16x16x32_bf16 v[70:73], v[156:159], v[210:213], v[70:73]
	v_mfma_f32_16x16x32_bf16 v[126:129], v[152:155], v[184:187], v[126:129]
	v_mfma_f32_16x16x32_bf16 v[118:121], v[160:163], v[184:187], v[118:121]
	v_mfma_f32_16x16x32_bf16 v[110:113], v[152:155], v[198:201], v[110:113]
	v_mfma_f32_16x16x32_bf16 v[102:105], v[160:163], v[198:201], v[102:105]
	v_mfma_f32_16x16x32_bf16 v[94:97], v[152:155], v[206:209], v[94:97]
	v_mfma_f32_16x16x32_bf16 v[86:89], v[160:163], v[206:209], v[86:89]
	v_mfma_f32_16x16x32_bf16 v[78:81], v[152:155], v[214:217], v[78:81]
	v_mfma_f32_16x16x32_bf16 v[70:73], v[160:163], v[214:217], v[70:73]
	v_mfma_f32_16x16x32_bf16 v[122:125], v[164:167], v[180:183], v[122:125]
	v_mfma_f32_16x16x32_bf16 v[114:117], v[172:175], v[180:183], v[114:117]
	v_mfma_f32_16x16x32_bf16 v[106:109], v[164:167], v[188:191], v[106:109]
	v_mfma_f32_16x16x32_bf16 v[98:101], v[172:175], v[188:191], v[98:101]
	v_mfma_f32_16x16x32_bf16 v[90:93], v[164:167], v[202:205], v[90:93]
	v_mfma_f32_16x16x32_bf16 v[82:85], v[172:175], v[202:205], v[82:85]
	v_mfma_f32_16x16x32_bf16 v[74:77], v[164:167], v[210:213], v[74:77]
	v_mfma_f32_16x16x32_bf16 v[66:69], v[172:175], v[210:213], v[66:69]
	v_mfma_f32_16x16x32_bf16 v[122:125], v[168:171], v[184:187], v[122:125]
	v_mfma_f32_16x16x32_bf16 v[114:117], v[176:179], v[184:187], v[114:117]
	v_mfma_f32_16x16x32_bf16 v[106:109], v[168:171], v[198:201], v[106:109]
	v_mfma_f32_16x16x32_bf16 v[98:101], v[176:179], v[198:201], v[98:101]
	v_mfma_f32_16x16x32_bf16 v[90:93], v[168:171], v[206:209], v[90:93]
	v_mfma_f32_16x16x32_bf16 v[82:85], v[176:179], v[206:209], v[82:85]
	v_mfma_f32_16x16x32_bf16 v[74:77], v[168:171], v[214:217], v[74:77]
	v_mfma_f32_16x16x32_bf16 v[66:69], v[176:179], v[214:217], v[66:69]
	s_barrier
; #define PG8_STAGE(bufoff, gbase, voff) do { _Pragma("unroll") for (int _i = 0; _i < 2; ++_i) \
;         __builtin_amdgcn_global_load_lds((const unsigned*)((const char*)(gbase) + (voff)[_i]), (PG8_LAS unsigned*)(lds + (bufoff) + ldsw + _i * 8192), 16, 0, 0); } while (0)
; #define PG8_LDA(dst, b, h) do { _Pragma("unroll") for (int m = 0; m < 4; ++m) _Pragma("unroll") for (int k = 0; k < 2; ++k) dst[m][k] = *(const PG8_LAS bf16x8*)(lds + PG8_SA(b, h) + aoff + m * 2048 + k * 1024); } while (0)
; #define PG8_LDB(dst, b, h) do { _Pragma("unroll") for (int n = 0; n < 2; ++n) _Pragma("unroll") for (int k = 0; k < 2; ++k) dst[n][k] = *(const PG8_LAS bf16x8*)(lds + PG8_SB(b, h) + boff + n * 2048 + k * 1024); } while (0)
; template <class Epi, class Sched, bool ALIGN_EPI = false, bool SP2 = false>
; __device__ __forceinline__ void gemm_phase(PG8_LAS unsigned char* lds, const Gemm g, const Sched& S, const Epi& E) {
;     ...
;         for (int t = 0; t < nt; t += 2) {
;             const bool last = (t == nt - 2);
;             const char* a1 = cA + (size_t)(t + 1) * kstep;
;             const char* a2 = last ? nA : cA + (size_t)(t + 2) * kstep; const char* b2 = last ? nB : cB + (size_t)(t + 2) * kstep;
;             const char* a3 = a2 + kstep; const char* b3 = b2 + kstep;
;             if (last && has_next) S.a_ready(nxt);
;             if constexpr (SP2) {
;             PG8_LDB(B0, 0, 0); PG8_LDB(B1, 0, 1); PG8_SCHED; PG8_LDA(At, 0, 0); PG8_STAGE(PG8_SA(1, 1), a1 + hstep, voffA);
;             PG8_WAIT_V(8); PG8_WAIT_L(0); PG8_BAR; PG8_MMA(0, 0, At, B0); PG8_MMA(0, 1, At, B1); PG8_BAR; PG8_SCHED;
;             PG8_LDA(At, 0, 1); PG8_STAGE(PG8_SB(0, 0), b2, voffB); PG8_STAGE(PG8_SB(0, 1), b2 + hstep, voffB); PG8_STAGE(PG8_SA(0, 0), a2, voffA);
;             PG8_WAIT_V(8); PG8_WAIT_L(0); PG8_BAR; PG8_MMA(1, 0, At, B0); PG8_MMA(1, 1, At, B1); PG8_BAR; PG8_SCHED;
;             PG8_LDB(B0, 1, 0); PG8_LDB(B1, 1, 1); PG8_SCHED; PG8_LDA(At, 1, 0); PG8_STAGE(PG8_SA(0, 1), a2 + hstep, voffA);
;             PG8_WAIT_V(8); PG8_WAIT_L(0); PG8_BAR; PG8_MMA(0, 0, At, B0); PG8_MMA(0, 1, At, B1); PG8_BAR; PG8_SCHED;
;             PG8_LDA(At, 1, 1); PG8_STAGE(PG8_SB(1, 0), b3, voffB); PG8_STAGE(PG8_SB(1, 1), b3 + hstep, voffB); PG8_STAGE(PG8_SA(1, 0), a3, voffA);
;             PG8_WAIT_V(8); PG8_WAIT_L(0); PG8_BAR; PG8_MMA(1, 0, At, B0); PG8_MMA(1, 1, At, B1); PG8_BAR; PG8_SCHED;
	s_add_i32 s46, s86, s25
	v_lshl_add_u64 v[142:143], v[142:143], 0, s[58:59]
	s_mov_b32 m0, s46
	ds_read_b128 v[180:183], v147 offset:49152
	ds_read_b128 v[184:187], v147 offset:50176
	ds_read_b128 v[188:191], v147 offset:51200
	ds_read_b128 v[198:201], v147 offset:52224
	ds_read_b128 v[202:205], v147 offset:53248
	ds_read_b128 v[206:209], v147 offset:54272
	ds_read_b128 v[210:213], v147 offset:55296
	ds_read_b128 v[214:217], v147 offset:56320
	global_load_lds_dwordx4 v[142:143], off
	s_add_i32 m0, s46, 0x2000
	s_add_u32 s44, s44, 0x40080
	v_lshl_add_u64 v[142:143], v[192:193], 0, s[58:59]
	s_addc_u32 s45, s45, 0
	s_add_i32 s46, s87, s25
	global_load_lds_dwordx4 v[142:143], off
	v_lshl_add_u64 v[142:143], s[44:45], 0, v[134:135]
	s_mov_b32 m0, s46
	s_nop 0
	global_load_lds_dwordx4 v[142:143], off
	v_lshl_add_u64 v[142:143], s[44:45], 0, v[130:131]
	s_add_i32 m0, s46, 0x2000
	s_nop 0
	global_load_lds_dwordx4 v[142:143], off
	v_lshl_add_u64 v[142:143], v[218:219], 0, s[58:59]
	s_mov_b32 m0, s55
	s_nop 0
	global_load_lds_dwordx4 v[142:143], off
	v_lshl_add_u64 v[142:143], v[220:221], 0, s[58:59]
	s_mov_b32 m0, s63
	s_nop 0
	global_load_lds_dwordx4 v[142:143], off
	s_waitcnt vmcnt(8)
	s_waitcnt lgkmcnt(0)
	s_barrier
	s_waitcnt lgkmcnt(0)
	v_mfma_f32_16x16x32_bf16 v[62:65], v[148:151], v[180:183], v[62:65]
	v_mfma_f32_16x16x32_bf16 v[54:57], v[156:159], v[180:183], v[54:57]
	v_mfma_f32_16x16x32_bf16 v[46:49], v[148:151], v[188:191], v[46:49]
	v_mfma_f32_16x16x32_bf16 v[38:41], v[156:159], v[188:191], v[38:41]
	v_mfma_f32_16x16x32_bf16 v[30:33], v[148:151], v[202:205], v[30:33]
	v_mfma_f32_16x16x32_bf16 v[22:25], v[156:159], v[202:205], v[22:25]
	v_mfma_f32_16x16x32_bf16 v[14:17], v[148:151], v[210:213], v[14:17]
	v_mfma_f32_16x16x32_bf16 v[6:9], v[156:159], v[210:213], v[6:9]
	v_mfma_f32_16x16x32_bf16 v[62:65], v[152:155], v[184:187], v[62:65]
	v_mfma_f32_16x16x32_bf16 v[54:57], v[160:163], v[184:187], v[54:57]
	v_mfma_f32_16x16x32_bf16 v[46:49], v[152:155], v[198:201], v[46:49]
	v_mfma_f32_16x16x32_bf16 v[38:41], v[160:163], v[198:201], v[38:41]
	v_mfma_f32_16x16x32_bf16 v[30:33], v[152:155], v[206:209], v[30:33]
	v_mfma_f32_16x16x32_bf16 v[22:25], v[160:163], v[206:209], v[22:25]
	v_mfma_f32_16x16x32_bf16 v[14:17], v[152:155], v[214:217], v[14:17]
	v_mfma_f32_16x16x32_bf16 v[6:9], v[160:163], v[214:217], v[6:9]
	v_mfma_f32_16x16x32_bf16 v[58:61], v[164:167], v[180:183], v[58:61]
	v_mfma_f32_16x16x32_bf16 v[50:53], v[172:175], v[180:183], v[50:53]
	v_mfma_f32_16x16x32_bf16 v[42:45], v[164:167], v[188:191], v[42:45]
	v_mfma_f32_16x16x32_bf16 v[34:37], v[172:175], v[188:191], v[34:37]
	v_mfma_f32_16x16x32_bf16 v[26:29], v[164:167], v[202:205], v[26:29]
	v_mfma_f32_16x16x32_bf16 v[18:21], v[172:175], v[202:205], v[18:21]
	v_mfma_f32_16x16x32_bf16 v[10:13], v[164:167], v[210:213], v[10:13]
	v_mfma_f32_16x16x32_bf16 v[2:5], v[172:175], v[210:213], v[2:5]
	v_mfma_f32_16x16x32_bf16 v[58:61], v[168:171], v[184:187], v[58:61]
	v_mfma_f32_16x16x32_bf16 v[50:53], v[176:179], v[184:187], v[50:53]
	v_mfma_f32_16x16x32_bf16 v[42:45], v[168:171], v[198:201], v[42:45]
	v_mfma_f32_16x16x32_bf16 v[34:37], v[176:179], v[198:201], v[34:37]
	v_mfma_f32_16x16x32_bf16 v[26:29], v[168:171], v[206:209], v[26:29]
	v_mfma_f32_16x16x32_bf16 v[18:21], v[176:179], v[206:209], v[18:21]
	v_mfma_f32_16x16x32_bf16 v[10:13], v[168:171], v[214:217], v[10:13]
	v_mfma_f32_16x16x32_bf16 v[2:5], v[176:179], v[214:217], v[2:5]
	s_barrier
	s_add_i32 s79, s79, 2
	s_add_u32 s42, s42, 0x100
	s_addc_u32 s43, s43, 0
	s_add_u32 s73, s73, 0x100
	s_addc_u32 s78, s78, 0
	s_cmp_gt_u32 s79, 13
	s_cbranch_scc1 .Lpeel_done_1180
.LBB0_1180:
	s_add_u32 s44, s42, 0xfffc0080
	s_addc_u32 s45, s43, -1
	s_add_i32 s86, 0, 0x10000
	s_cmp_eq_u32 s79, 12
	s_cselect_b32 s47, s21, s45
	s_cselect_b32 s46, s29, s44
	v_add_u32_e32 v0, s86, v145
	s_cselect_b32 s45, s19, s78
	s_cselect_b32 s44, s41, s73
	s_add_i32 s93, 0, 0x14000
	ds_read_b128 v[148:151], v0
	ds_read_b128 v[152:155], v0 offset:1024
	ds_read_b128 v[156:159], v0 offset:2048
	ds_read_b128 v[160:163], v0 offset:3072
	v_add_u32_e32 v0, s93, v145
	ds_read_b128 v[164:167], v0
	ds_read_b128 v[168:171], v0 offset:1024
	ds_read_b128 v[172:175], v0 offset:2048
	ds_read_b128 v[176:179], v0 offset:3072
	v_lshl_add_u64 v[142:143], s[42:43], 0, v[138:139]
	s_add_i32 m0, s49, 0xc000
	ds_read_b128 v[180:183], v147
	ds_read_b128 v[184:187], v147 offset:1024
	ds_read_b128 v[188:191], v147 offset:2048
	ds_read_b128 v[198:201], v147 offset:3072
	ds_read_b128 v[202:205], v147 offset:4096
	ds_read_b128 v[206:209], v147 offset:5120
	ds_read_b128 v[210:213], v147 offset:6144
	ds_read_b128 v[214:217], v147 offset:7168
	global_load_lds_dwordx4 v[142:143], off
	v_lshl_add_u64 v[142:143], s[42:43], 0, v[140:141]
	s_add_i32 m0, s49, 0xe000
	s_nop 0
	global_load_lds_dwordx4 v[142:143], off
	s_waitcnt vmcnt(8)
	s_waitcnt lgkmcnt(0)
	s_barrier
; #define PG8_STAGE(bufoff, gbase, voff) do { _Pragma("unroll") for (int _i = 0; _i < 2; ++_i) \
;         __builtin_amdgcn_global_load_lds((const unsigned*)((const char*)(gbase) + (voff)[_i]), (PG8_LAS unsigned*)(lds + (bufoff) + ldsw + _i * 8192), 16, 0, 0); } while (0)
; #define PG8_LDA(dst, b, h) do { _Pragma("unroll") for (int m = 0; m < 4; ++m) _Pragma("unroll") for (int k = 0; k < 2; ++k) dst[m][k] = *(const PG8_LAS bf16x8*)(lds + PG8_SA(b, h) + aoff + m * 2048 + k * 1024); } while (0)
; #define PG8_LDB(dst, b, h) do { _Pragma("unroll") for (int n = 0; n < 2; ++n) _Pragma("unroll") for (int k = 0; k < 2; ++k) dst[n][k] = *(const PG8_LAS bf16x8*)(lds + PG8_SB(b, h) + boff + n * 2048 + k * 1024); } while (0)
; #define PG8_MMA(ai, bj, At, Bt) do { __builtin_amdgcn_s_setprio(1); _Pragma("unroll") for (int m = 0; m < 4; ++m) _Pragma("unroll") for (int n = 0; n < 2; ++n) _Pragma("unroll") for (int k = 0; k < 2; ++k) \
;         acc[ai][bj][m][n] = __builtin_amdgcn_mfma_f32_16x16x32_bf16(Bt[n][k], At[m][k], acc[ai][bj][m][n], 0, 0, 0); __builtin_amdgcn_s_setprio(0); } while (0)
; #define PG8_WAIT_V(n) asm volatile("s_waitcnt vmcnt(" #n ")" ::: "memory")
; #define PG8_WAIT_L(n) asm volatile("s_waitcnt lgkmcnt(" #n ")" ::: "memory")
; #define PG8_BAR __builtin_amdgcn_s_barrier()
; template <class Epi, class Sched, bool ALIGN_EPI = false, bool SP2 = false>
; __device__ __forceinline__ void gemm_phase(PG8_LAS unsigned char* lds, const Gemm g, const Sched& S, const Epi& E) {
;     ...
;             PG8_WAIT_V(8); PG8_WAIT_L(0); PG8_BAR; PG8_MMA(0, 0, At, B0); PG8_MMA(0, 1, At, B1); PG8_BAR; PG8_SCHED;
;             PG8_LDA(At, 0, 1); PG8_STAGE(PG8_SB(0, 0), b2, voffB); PG8_STAGE(PG8_SB(0, 1), b2 + hstep, voffB); PG8_STAGE(PG8_SA(0, 0), a2, voffA);
;             PG8_WAIT_V(8); PG8_WAIT_L(0); PG8_BAR; PG8_MMA(1, 0, At, B0); PG8_MMA(1, 1, At, B1); PG8_BAR; PG8_SCHED;
;             PG8_LDB(B0, 1, 0); PG8_LDB(B1, 1, 1); PG8_SCHED; PG8_LDA(At, 1, 0); PG8_STAGE(PG8_SA(0, 1), a2 + hstep, voffA);
;             PG8_WAIT_V(8); PG8_WAIT_L(0); PG8_BAR; PG8_MMA(0, 0, At, B0); PG8_MMA(0, 1, At, B1); PG8_BAR; PG8_SCHED;
;             PG8_LDA(At, 1, 1); PG8_STAGE(PG8_SB(1, 0), b3, voffB); PG8_STAGE(PG8_SB(1, 1), b3 + hstep, voffB); PG8_STAGE(PG8_SA(1, 0), a3, voffA);
;             PG8_WAIT_V(8); PG8_WAIT_L(0); PG8_BAR; PG8_MMA(1, 0, At, B0); PG8_MMA(1, 1, At, B1); PG8_BAR; PG8_SCHED;
	s_waitcnt lgkmcnt(0)
	v_mfma_f32_16x16x32_bf16 v[126:129], v[148:151], v[180:183], v[126:129]
	v_mfma_f32_16x16x32_bf16 v[118:121], v[156:159], v[180:183], v[118:121]
	v_mfma_f32_16x16x32_bf16 v[110:113], v[148:151], v[188:191], v[110:113]
	v_mfma_f32_16x16x32_bf16 v[102:105], v[156:159], v[188:191], v[102:105]
	v_mfma_f32_16x16x32_bf16 v[94:97], v[148:151], v[202:205], v[94:97]
	v_mfma_f32_16x16x32_bf16 v[86:89], v[156:159], v[202:205], v[86:89]
	v_mfma_f32_16x16x32_bf16 v[78:81], v[148:151], v[210:213], v[78:81]
	v_mfma_f32_16x16x32_bf16 v[70:73], v[156:159], v[210:213], v[70:73]
	v_mfma_f32_16x16x32_bf16 v[126:129], v[152:155], v[184:187], v[126:129]
	v_mfma_f32_16x16x32_bf16 v[118:121], v[160:163], v[184:187], v[118:121]
	v_mfma_f32_16x16x32_bf16 v[110:113], v[152:155], v[198:201], v[110:113]
	v_mfma_f32_16x16x32_bf16 v[102:105], v[160:163], v[198:201], v[102:105]
	v_mfma_f32_16x16x32_bf16 v[94:97], v[152:155], v[206:209], v[94:97]
	v_mfma_f32_16x16x32_bf16 v[86:89], v[160:163], v[206:209], v[86:89]
	v_mfma_f32_16x16x32_bf16 v[78:81], v[152:155], v[214:217], v[78:81]
	v_mfma_f32_16x16x32_bf16 v[70:73], v[160:163], v[214:217], v[70:73]
	v_mfma_f32_16x16x32_bf16 v[122:125], v[164:167], v[180:183], v[122:125]
	v_mfma_f32_16x16x32_bf16 v[114:117], v[172:175], v[180:183], v[114:117]
	v_mfma_f32_16x16x32_bf16 v[106:109], v[164:167], v[188:191], v[106:109]
	v_mfma_f32_16x16x32_bf16 v[98:101], v[172:175], v[188:191], v[98:101]
	v_mfma_f32_16x16x32_bf16 v[90:93], v[164:167], v[202:205], v[90:93]
	v_mfma_f32_16x16x32_bf16 v[82:85], v[172:175], v[202:205], v[82:85]
	v_mfma_f32_16x16x32_bf16 v[74:77], v[164:167], v[210:213], v[74:77]
	v_mfma_f32_16x16x32_bf16 v[66:69], v[172:175], v[210:213], v[66:69]
	v_mfma_f32_16x16x32_bf16 v[122:125], v[168:171], v[184:187], v[122:125]
	v_mfma_f32_16x16x32_bf16 v[114:117], v[176:179], v[184:187], v[114:117]
	v_mfma_f32_16x16x32_bf16 v[106:109], v[168:171], v[198:201], v[106:109]
	v_mfma_f32_16x16x32_bf16 v[98:101], v[176:179], v[198:201], v[98:101]
	v_mfma_f32_16x16x32_bf16 v[90:93], v[168:171], v[206:209], v[90:93]
	v_mfma_f32_16x16x32_bf16 v[82:85], v[176:179], v[206:209], v[82:85]
	v_mfma_f32_16x16x32_bf16 v[74:77], v[168:171], v[214:217], v[74:77]
	v_mfma_f32_16x16x32_bf16 v[66:69], v[176:179], v[214:217], v[66:69]
	s_barrier
	s_add_i32 s86, s86, s25
	v_lshl_add_u64 v[142:143], s[44:45], 0, v[134:135]
	s_mov_b32 m0, s86
	ds_read_b128 v[180:183], v147 offset:16384
	ds_read_b128 v[184:187], v147 offset:17408
	ds_read_b128 v[188:191], v147 offset:18432
	ds_read_b128 v[198:201], v147 offset:19456
	ds_read_b128 v[202:205], v147 offset:20480
	ds_read_b128 v[206:209], v147 offset:21504
	ds_read_b128 v[210:213], v147 offset:22528
	ds_read_b128 v[214:217], v147 offset:23552
	global_load_lds_dwordx4 v[142:143], off
	s_add_i32 m0, s86, 0x2000
	s_add_u32 s86, s44, 0x40000
	v_lshl_add_u64 v[192:193], s[44:45], 0, v[130:131]
	s_addc_u32 s87, s45, 0
	s_add_i32 s93, s93, s25
	global_load_lds_dwordx4 v[192:193], off
	v_lshl_add_u64 v[218:219], s[86:87], 0, v[134:135]
	s_mov_b32 m0, s93
	v_lshl_add_u64 v[220:221], s[46:47], 0, v[132:133]
	global_load_lds_dwordx4 v[218:219], off
	v_lshl_add_u64 v[218:219], s[86:87], 0, v[130:131]
	s_add_i32 m0, s93, 0x2000
	s_nop 0
	global_load_lds_dwordx4 v[218:219], off
	v_lshl_add_u64 v[218:219], s[46:47], 0, v[136:137]
	s_mov_b32 m0, s49
	s_nop 0
	global_load_lds_dwordx4 v[218:219], off
	s_mov_b32 m0, s50
	s_nop 0
	global_load_lds_dwordx4 v[220:221], off
	s_waitcnt vmcnt(8)
	s_waitcnt lgkmcnt(0)
	s_barrier
	s_waitcnt lgkmcnt(0)
	v_mfma_f32_16x16x32_bf16 v[62:65], v[148:151], v[180:183], v[62:65]
	v_mfma_f32_16x16x32_bf16 v[54:57], v[156:159], v[180:183], v[54:57]
	v_mfma_f32_16x16x32_bf16 v[46:49], v[148:151], v[188:191], v[46:49]
	v_mfma_f32_16x16x32_bf16 v[38:41], v[156:159], v[188:191], v[38:41]
	v_mfma_f32_16x16x32_bf16 v[30:33], v[148:151], v[202:205], v[30:33]
	v_mfma_f32_16x16x32_bf16 v[22:25], v[156:159], v[202:205], v[22:25]
	v_mfma_f32_16x16x32_bf16 v[14:17], v[148:151], v[210:213], v[14:17]
	v_mfma_f32_16x16x32_bf16 v[6:9], v[156:159], v[210:213], v[6:9]
	v_mfma_f32_16x16x32_bf16 v[62:65], v[152:155], v[184:187], v[62:65]
	v_mfma_f32_16x16x32_bf16 v[54:57], v[160:163], v[184:187], v[54:57]
	v_mfma_f32_16x16x32_bf16 v[46:49], v[152:155], v[198:201], v[46:49]
	v_mfma_f32_16x16x32_bf16 v[38:41], v[160:163], v[198:201], v[38:41]
	v_mfma_f32_16x16x32_bf16 v[30:33], v[152:155], v[206:209], v[30:33]
	v_mfma_f32_16x16x32_bf16 v[22:25], v[160:163], v[206:209], v[22:25]
	v_mfma_f32_16x16x32_bf16 v[14:17], v[152:155], v[214:217], v[14:17]
	v_mfma_f32_16x16x32_bf16 v[6:9], v[160:163], v[214:217], v[6:9]
	v_mfma_f32_16x16x32_bf16 v[58:61], v[164:167], v[180:183], v[58:61]
	v_mfma_f32_16x16x32_bf16 v[50:53], v[172:175], v[180:183], v[50:53]
	v_mfma_f32_16x16x32_bf16 v[42:45], v[164:167], v[188:191], v[42:45]
	v_mfma_f32_16x16x32_bf16 v[34:37], v[172:175], v[188:191], v[34:37]
	v_mfma_f32_16x16x32_bf16 v[26:29], v[164:167], v[202:205], v[26:29]
	v_mfma_f32_16x16x32_bf16 v[18:21], v[172:175], v[202:205], v[18:21]
	v_mfma_f32_16x16x32_bf16 v[10:13], v[164:167], v[210:213], v[10:13]
	v_mfma_f32_16x16x32_bf16 v[2:5], v[172:175], v[210:213], v[2:5]
	v_mfma_f32_16x16x32_bf16 v[58:61], v[168:171], v[184:187], v[58:61]
	v_mfma_f32_16x16x32_bf16 v[50:53], v[176:179], v[184:187], v[50:53]
	v_mfma_f32_16x16x32_bf16 v[42:45], v[168:171], v[198:201], v[42:45]
	v_mfma_f32_16x16x32_bf16 v[34:37], v[176:179], v[198:201], v[34:37]
	v_mfma_f32_16x16x32_bf16 v[26:29], v[168:171], v[206:209], v[26:29]
	v_mfma_f32_16x16x32_bf16 v[18:21], v[176:179], v[206:209], v[18:21]
	v_mfma_f32_16x16x32_bf16 v[10:13], v[168:171], v[214:217], v[10:13]
	v_mfma_f32_16x16x32_bf16 v[2:5], v[176:179], v[214:217], v[2:5]
	s_barrier
; #define PG8_STAGE(bufoff, gbase, voff) do { _Pragma("unroll") for (int _i = 0; _i < 2; ++_i) \
;         __builtin_amdgcn_global_load_lds((const unsigned*)((const char*)(gbase) + (voff)[_i]), (PG8_LAS unsigned*)(lds + (bufoff) + ldsw + _i * 8192), 16, 0, 0); } while (0)
; #define PG8_LDA(dst, b, h) do { _Pragma("unroll") for (int m = 0; m < 4; ++m) _Pragma("unroll") for (int k = 0; k < 2; ++k) dst[m][k] = *(const PG8_LAS bf16x8*)(lds + PG8_SA(b, h) + aoff + m * 2048 + k * 1024); } while (0)
; #define PG8_LDB(dst, b, h) do { _Pragma("unroll") for (int n = 0; n < 2; ++n) _Pragma("unroll") for (int k = 0; k < 2; ++k) dst[n][k] = *(const PG8_LAS bf16x8*)(lds + PG8_SB(b, h) + boff + n * 2048 + k * 1024); } while (0)
; #define PG8_MMA(ai, bj, At, Bt) do { __builtin_amdgcn_s_setprio(1); _Pragma("unroll") for (int m = 0; m < 4; ++m) _Pragma("unroll") for (int n = 0; n < 2; ++n) _Pragma("unroll") for (int k = 0; k < 2; ++k) \
;         acc[ai][bj][m][n] = __builtin_amdgcn_mfma_f32_16x16x32_bf16(Bt[n][k], At[m][k], acc[ai][bj][m][n], 0, 0, 0); __builtin_amdgcn_s_setprio(0); } while (0)
; #define PG8_WAIT_V(n) asm volatile("s_waitcnt vmcnt(" #n ")" ::: "memory")
; #define PG8_WAIT_L(n) asm volatile("s_waitcnt lgkmcnt(" #n ")" ::: "memory")
; #define PG8_BAR __builtin_amdgcn_s_barrier()
; #define PG8_SCHED __builtin_amdgcn_sched_barrier(0)
; template <class Epi, class Sched, bool ALIGN_EPI = false, bool SP2 = false>
; __device__ __forceinline__ void gemm_phase(PG8_LAS unsigned char* lds, const Gemm g, const Sched& S, const Epi& E) {
;     ...
;             PG8_LDB(B0, 1, 0); PG8_LDB(B1, 1, 1); PG8_SCHED; PG8_LDA(At, 1, 0); PG8_STAGE(PG8_SA(0, 1), a2 + hstep, voffA);
;             PG8_WAIT_V(8); PG8_WAIT_L(0); PG8_BAR; PG8_MMA(0, 0, At, B0); PG8_MMA(0, 1, At, B1); PG8_BAR; PG8_SCHED;
;             PG8_LDA(At, 1, 1); PG8_STAGE(PG8_SB(1, 0), b3, voffB); PG8_STAGE(PG8_SB(1, 1), b3 + hstep, voffB); PG8_STAGE(PG8_SA(1, 0), a3, voffA);
;             PG8_WAIT_V(8); PG8_WAIT_L(0); PG8_BAR; PG8_MMA(1, 0, At, B0); PG8_MMA(1, 1, At, B1); PG8_BAR; PG8_SCHED;
	s_add_i32 s86, 0, 0x18000
	v_add_u32_e32 v0, s86, v145
	s_add_i32 s87, 0, 0x1c000
	ds_read_b128 v[148:151], v0
	ds_read_b128 v[152:155], v0 offset:1024
	ds_read_b128 v[156:159], v0 offset:2048
	ds_read_b128 v[160:163], v0 offset:3072
	v_add_u32_e32 v0, s87, v145
	ds_read_b128 v[164:167], v0
	ds_read_b128 v[168:171], v0 offset:1024
	ds_read_b128 v[172:175], v0 offset:2048
	ds_read_b128 v[176:179], v0 offset:3072
	s_add_u32 s46, s46, 0x40000
	s_addc_u32 s47, s47, 0
	s_mov_b32 m0, s51
	v_lshl_add_u64 v[222:223], s[46:47], 0, v[136:137]
	ds_read_b128 v[180:183], v147 offset:32768
	ds_read_b128 v[184:187], v147 offset:33792
	ds_read_b128 v[188:191], v147 offset:34816
	ds_read_b128 v[198:201], v147 offset:35840
	ds_read_b128 v[202:205], v147 offset:36864
	ds_read_b128 v[206:209], v147 offset:37888
	ds_read_b128 v[210:213], v147 offset:38912
	ds_read_b128 v[214:217], v147 offset:39936
	global_load_lds_dwordx4 v[222:223], off
	v_lshl_add_u64 v[222:223], s[46:47], 0, v[132:133]
	s_mov_b32 m0, s54
	s_nop 0
	global_load_lds_dwordx4 v[222:223], off
	s_waitcnt vmcnt(8)
	s_waitcnt lgkmcnt(0)
	s_barrier
	s_waitcnt lgkmcnt(0)
	v_mfma_f32_16x16x32_bf16 v[126:129], v[148:151], v[180:183], v[126:129]
	v_mfma_f32_16x16x32_bf16 v[118:121], v[156:159], v[180:183], v[118:121]
	v_mfma_f32_16x16x32_bf16 v[110:113], v[148:151], v[188:191], v[110:113]
	v_mfma_f32_16x16x32_bf16 v[102:105], v[156:159], v[188:191], v[102:105]
	v_mfma_f32_16x16x32_bf16 v[94:97], v[148:151], v[202:205], v[94:97]
	v_mfma_f32_16x16x32_bf16 v[86:89], v[156:159], v[202:205], v[86:89]
	v_mfma_f32_16x16x32_bf16 v[78:81], v[148:151], v[210:213], v[78:81]
	v_mfma_f32_16x16x32_bf16 v[70:73], v[156:159], v[210:213], v[70:73]
	v_mfma_f32_16x16x32_bf16 v[126:129], v[152:155], v[184:187], v[126:129]
	v_mfma_f32_16x16x32_bf16 v[118:121], v[160:163], v[184:187], v[118:121]
	v_mfma_f32_16x16x32_bf16 v[110:113], v[152:155], v[198:201], v[110:113]
	v_mfma_f32_16x16x32_bf16 v[102:105], v[160:163], v[198:201], v[102:105]
	v_mfma_f32_16x16x32_bf16 v[94:97], v[152:155], v[206:209], v[94:97]
	v_mfma_f32_16x16x32_bf16 v[86:89], v[160:163], v[206:209], v[86:89]
	v_mfma_f32_16x16x32_bf16 v[78:81], v[152:155], v[214:217], v[78:81]
	v_mfma_f32_16x16x32_bf16 v[70:73], v[160:163], v[214:217], v[70:73]
	v_mfma_f32_16x16x32_bf16 v[122:125], v[164:167], v[180:183], v[122:125]
	v_mfma_f32_16x16x32_bf16 v[114:117], v[172:175], v[180:183], v[114:117]
	v_mfma_f32_16x16x32_bf16 v[106:109], v[164:167], v[188:191], v[106:109]
	v_mfma_f32_16x16x32_bf16 v[98:101], v[172:175], v[188:191], v[98:101]
	v_mfma_f32_16x16x32_bf16 v[90:93], v[164:167], v[202:205], v[90:93]
	v_mfma_f32_16x16x32_bf16 v[82:85], v[172:175], v[202:205], v[82:85]
	v_mfma_f32_16x16x32_bf16 v[74:77], v[164:167], v[210:213], v[74:77]
	v_mfma_f32_16x16x32_bf16 v[66:69], v[172:175], v[210:213], v[66:69]
	v_mfma_f32_16x16x32_bf16 v[122:125], v[168:171], v[184:187], v[122:125]
	v_mfma_f32_16x16x32_bf16 v[114:117], v[176:179], v[184:187], v[114:117]
	v_mfma_f32_16x16x32_bf16 v[106:109], v[168:171], v[198:201], v[106:109]
	v_mfma_f32_16x16x32_bf16 v[98:101], v[176:179], v[198:201], v[98:101]
	v_mfma_f32_16x16x32_bf16 v[90:93], v[168:171], v[206:209], v[90:93]
	v_mfma_f32_16x16x32_bf16 v[82:85], v[176:179], v[206:209], v[82:85]
	v_mfma_f32_16x16x32_bf16 v[74:77], v[168:171], v[214:217], v[74:77]
	v_mfma_f32_16x16x32_bf16 v[66:69], v[176:179], v[214:217], v[66:69]
	s_barrier
	s_add_i32 s46, s86, s25
	v_lshl_add_u64 v[142:143], v[142:143], 0, s[58:59]
	s_mov_b32 m0, s46
	ds_read_b128 v[180:183], v147 offset:49152
	ds_read_b128 v[184:187], v147 offset:50176
	ds_read_b128 v[188:191], v147 offset:51200
	ds_read_b128 v[198:201], v147 offset:52224
	ds_read_b128 v[202:205], v147 offset:53248
	ds_read_b128 v[206:209], v147 offset:54272
	ds_read_b128 v[210:213], v147 offset:55296
	ds_read_b128 v[214:217], v147 offset:56320
	global_load_lds_dwordx4 v[142:143], off
	s_add_i32 m0, s46, 0x2000
	s_add_u32 s44, s44, 0x40080
	v_lshl_add_u64 v[142:143], v[192:193], 0, s[58:59]
	s_addc_u32 s45, s45, 0
	s_add_i32 s46, s87, s25
	global_load_lds_dwordx4 v[142:143], off
	v_lshl_add_u64 v[142:143], s[44:45], 0, v[134:135]
	s_mov_b32 m0, s46
	s_nop 0
	global_load_lds_dwordx4 v[142:143], off
	v_lshl_add_u64 v[142:143], s[44:45], 0, v[130:131]
	s_add_i32 m0, s46, 0x2000
	s_nop 0
	global_load_lds_dwordx4 v[142:143], off
	v_lshl_add_u64 v[142:143], v[218:219], 0, s[58:59]
	s_mov_b32 m0, s55
	s_nop 0
	global_load_lds_dwordx4 v[142:143], off
	v_lshl_add_u64 v[142:143], v[220:221], 0, s[58:59]
	s_mov_b32 m0, s63
	s_nop 0
	global_load_lds_dwordx4 v[142:143], off
	s_waitcnt vmcnt(8)
	s_waitcnt lgkmcnt(0)
	s_barrier
	s_waitcnt lgkmcnt(0)
	v_mfma_f32_16x16x32_bf16 v[62:65], v[148:151], v[180:183], v[62:65]
	v_mfma_f32_16x16x32_bf16 v[54:57], v[156:159], v[180:183], v[54:57]
	v_mfma_f32_16x16x32_bf16 v[46:49], v[148:151], v[188:191], v[46:49]
	v_mfma_f32_16x16x32_bf16 v[38:41], v[156:159], v[188:191], v[38:41]
	v_mfma_f32_16x16x32_bf16 v[30:33], v[148:151], v[202:205], v[30:33]
	v_mfma_f32_16x16x32_bf16 v[22:25], v[156:159], v[202:205], v[22:25]
	v_mfma_f32_16x16x32_bf16 v[14:17], v[148:151], v[210:213], v[14:17]
	v_mfma_f32_16x16x32_bf16 v[6:9], v[156:159], v[210:213], v[6:9]
	v_mfma_f32_16x16x32_bf16 v[62:65], v[152:155], v[184:187], v[62:65]
	v_mfma_f32_16x16x32_bf16 v[54:57], v[160:163], v[184:187], v[54:57]
	v_mfma_f32_16x16x32_bf16 v[46:49], v[152:155], v[198:201], v[46:49]
	v_mfma_f32_16x16x32_bf16 v[38:41], v[160:163], v[198:201], v[38:41]
	v_mfma_f32_16x16x32_bf16 v[30:33], v[152:155], v[206:209], v[30:33]
	v_mfma_f32_16x16x32_bf16 v[22:25], v[160:163], v[206:209], v[22:25]
	v_mfma_f32_16x16x32_bf16 v[14:17], v[152:155], v[214:217], v[14:17]
	v_mfma_f32_16x16x32_bf16 v[6:9], v[160:163], v[214:217], v[6:9]
	v_mfma_f32_16x16x32_bf16 v[58:61], v[164:167], v[180:183], v[58:61]
	v_mfma_f32_16x16x32_bf16 v[50:53], v[172:175], v[180:183], v[50:53]
	v_mfma_f32_16x16x32_bf16 v[42:45], v[164:167], v[188:191], v[42:45]
	v_mfma_f32_16x16x32_bf16 v[34:37], v[172:175], v[188:191], v[34:37]
	v_mfma_f32_16x16x32_bf16 v[26:29], v[164:167], v[202:205], v[26:29]
	v_mfma_f32_16x16x32_bf16 v[18:21], v[172:175], v[202:205], v[18:21]
	v_mfma_f32_16x16x32_bf16 v[10:13], v[164:167], v[210:213], v[10:13]
	v_mfma_f32_16x16x32_bf16 v[2:5], v[172:175], v[210:213], v[2:5]
	v_mfma_f32_16x16x32_bf16 v[58:61], v[168:171], v[184:187], v[58:61]
	v_mfma_f32_16x16x32_bf16 v[50:53], v[176:179], v[184:187], v[50:53]
	v_mfma_f32_16x16x32_bf16 v[42:45], v[168:171], v[198:201], v[42:45]
	v_mfma_f32_16x16x32_bf16 v[34:37], v[176:179], v[198:201], v[34:37]
	v_mfma_f32_16x16x32_bf16 v[26:29], v[168:171], v[206:209], v[26:29]
	v_mfma_f32_16x16x32_bf16 v[18:21], v[176:179], v[206:209], v[18:21]
	v_mfma_f32_16x16x32_bf16 v[10:13], v[168:171], v[214:217], v[10:13]
	v_mfma_f32_16x16x32_bf16 v[2:5], v[176:179], v[214:217], v[2:5]
	s_barrier
	s_add_i32 s79, s79, 2
	s_add_u32 s42, s42, 0x100
	s_addc_u32 s43, s43, 0
	s_add_u32 s73, s73, 0x100
	s_addc_u32 s78, s78, 0
	s_cmp_gt_u32 s79, 13
	s_cbranch_scc0 .LBB0_1180
